# in-proj GEMMs: next tile's first K-tile prefetched into LDS during the last K-step of the current tile (non-V tiles)
# speedup vs baseline: 1.0430x; 1.0005x over previous
_Z11mega_kernel6Params:
	s_mov_b32 s98, 0
	s_add_u32 s6, s0, 0x168
	s_mov_b32 s69, s2
	v_writelane_b32 v253, s0, 0
	s_addc_u32 s7, s1, 0
	v_and_b32_e32 v146, 0x3ff, v0
	v_writelane_b32 v253, s1, 1
	v_cmp_eq_u32_e64 s[0:1], 0, v146
	s_mov_b64 s[4:5], exec
	s_nop 0
	v_writelane_b32 v253, s0, 2
	s_nop 1
	v_writelane_b32 v253, s1, 3
	s_and_b64 s[0:1], s[4:5], s[0:1]
	s_mov_b64 exec, s[0:1]
	s_cbranch_execz .LBB0_2
	v_mov_b32_e32 v2, 0
	v_mov_b32_e32 v3, v2
	v_mov_b32_e32 v4, v2
	v_mov_b32_e32 v5, v2
	v_mov_b32_e32 v1, 0x13000
	ds_write_b128 v1, v[2:5]

.LBB0_286:
	s_and_b32 s0, s33, 7
	s_or_b32 s0, s0, s3
	s_lshl_b32 s34, s0, 7
	v_or_b32_e32 v0, s34, v149
	v_lshl_or_b32 v128, v0, 11, v158
	v_lshl_add_u64 v[98:99], s[14:15], 0, v[128:129]
	v_add_co_u32_e32 v6, vcc, 0x10000, v98
	s_lshl_b32 s1, s33, 4
	s_nop 0
	v_addc_co_u32_e32 v7, vcc, 0, v99, vcc
	s_and_b32 s0, s1, 0x7fffff80
	v_add_co_u32_e32 v8, vcc, 0x20000, v98
	v_or_b32_e32 v0, s0, v149
	s_nop 0
	v_addc_co_u32_e32 v9, vcc, 0, v99, vcc
	v_lshl_or_b32 v96, v0, 11, v158
	v_add_co_u32_e32 v10, vcc, 0x30000, v98
	v_mov_b32_e32 v97, v129
	s_nop 0
	v_addc_co_u32_e32 v11, vcc, 0, v99, vcc
	v_lshl_add_u64 v[100:101], s[12:13], 0, v[96:97]
	v_add_co_u32_e32 v12, vcc, s4, v100
	v_addc_co_u32_e32 v13, vcc, 0, v101, vcc
	v_add_co_u32_e32 v46, vcc, s5, v100
	v_addc_co_u32_e32 v47, vcc, 0, v101, vcc
	v_add_co_u32_e32 v48, vcc, s26, v100
	v_addc_co_u32_e32 v49, vcc, 0, v101, vcc
	s_movk_i32 s1, 0x100
	s_mov_b32 s6, s23
	v_mov_b32_e32 v0, 0
	v_mov_b32_e32 v1, v129
	v_mov_b32_e32 v2, v129
	v_mov_b32_e32 v3, v129
	v_mov_b32_e32 v4, 0
	v_mov_b32_e32 v5, v129
	v_mov_b32_e32 v6, v129
	v_mov_b32_e32 v7, v129
	v_mov_b32_e32 v8, 0
	v_mov_b32_e32 v9, v129
	v_mov_b32_e32 v10, v129
	v_mov_b32_e32 v11, v129
	v_mov_b32_e32 v12, 0
	v_mov_b32_e32 v13, v129
	v_lshl_add_u64 v[102:103], v[100:101], 0, s[10:11]
	v_lshl_add_u64 v[104:105], v[100:101], 0, s[18:19]
	v_lshl_add_u64 v[106:107], v[100:101], 0, s[20:21]
	v_lshl_add_u64 v[108:109], v[98:99], 0, s[10:11]
	v_lshl_add_u64 v[110:111], v[98:99], 0, s[18:19]
	v_lshl_add_u64 v[112:113], v[98:99], 0, s[20:21]
	s_barrier
	v_mov_b32_e32 v46, v129
	v_mov_b32_e32 v47, v129
	v_mov_b32_e32 v48, 0
	v_mov_b32_e32 v49, v129
	v_mov_b32_e32 v50, v129
	v_mov_b32_e32 v51, v129
	v_mov_b32_e32 v52, 0
	v_mov_b32_e32 v53, v129
	v_mov_b32_e32 v54, v129
	v_mov_b32_e32 v55, v129
	v_mov_b32_e32 v56, 0
	v_mov_b32_e32 v57, v129
	v_mov_b32_e32 v58, v129
	v_mov_b32_e32 v59, v129
	v_mov_b32_e32 v60, 0
	v_mov_b32_e32 v61, v129
	v_mov_b32_e32 v62, v129
	v_mov_b32_e32 v63, v129
	v_mov_b32_e32 v14, v129
	v_mov_b32_e32 v15, v129
	v_mov_b32_e32 v16, 0
	v_mov_b32_e32 v17, v129
	v_mov_b32_e32 v18, v129
	v_mov_b32_e32 v19, v129
	v_mov_b32_e32 v20, 0
	v_mov_b32_e32 v21, v129
	v_mov_b32_e32 v22, v129
	v_mov_b32_e32 v23, v129
	v_mov_b32_e32 v24, 0
	v_mov_b32_e32 v25, v129
	v_mov_b32_e32 v26, v129
	v_mov_b32_e32 v27, v129
	v_mov_b32_e32 v28, 0
	v_mov_b32_e32 v29, v129
	v_mov_b32_e32 v30, v129
	v_mov_b32_e32 v31, v129
	v_mov_b32_e32 v32, 0
	v_mov_b32_e32 v33, v129
	v_mov_b32_e32 v34, v129
	v_mov_b32_e32 v35, v129
	v_mov_b32_e32 v36, 0
	v_mov_b32_e32 v37, v129
	v_mov_b32_e32 v38, v129
	v_mov_b32_e32 v39, v129
	v_mov_b32_e32 v40, 0
	v_mov_b32_e32 v41, v129
	v_mov_b32_e32 v42, v129
	v_mov_b32_e32 v43, v129
	v_mov_b32_e32 v44, 0
	v_mov_b32_e32 v45, v129
	v_readlane_b32 s24, v253, 0
	v_readlane_b32 s25, v253, 1
	s_load_dwordx2 s[24:25], s[24:25], 0x160
	v_lshrrev_b32_e32 v71, 6, v146
	s_nop 0
	v_readfirstlane_b32 s1, v71
	v_lshrrev_b32_e32 v69, 3, v146
	v_and_b32_e32 v70, 7, v146
	v_xor_b32_e32 v70, v69, v70
	v_and_b32_e32 v70, 7, v70
	v_lshlrev_b32_e32 v70, 4, v70
	v_lshl_or_b32 v68, v69, 11, v70
	v_add_u32_e32 v69, 0x10000, v68
	v_add_u32_e32 v70, 0x20000, v68
	v_add_u32_e32 v71, 0x30000, v68
	s_and_b32 s7, s33, 7
	s_and_b32 s22, s69, 7
	s_lshl_b32 s22, s22, 3
	s_or_b32 s7, s7, s22
	s_lshl_b32 s7, s7, 18
	s_add_u32 s7, s7, 0x2000000
	s_lshr_b32 s22, s33, 3
	s_lshl_b32 s22, s22, 18
	s_add_u32 s22, s22, 0x7200000
	s_lshl_b32 s1, s1, 10
	s_waitcnt lgkmcnt(0)
	s_add_u32 s7, s24, s7
	s_addc_u32 m0, s25, 0
	s_add_u32 s22, s24, s22
	s_addc_u32 s25, s25, 0
	s_add_u32 s24, s7, 0x80
	s_cmp_eq_u32 s24, s98
	s_cbranch_scc0 .Lnp287_load
	s_add_u32 s24, s22, 0x80
	s_cmp_eq_u32 s24, s100
	s_cbranch_scc1 .Lnp287_have
.Lnp287_load:
	s_mov_b32 s98, s7
	s_mov_b32 s99, m0
	s_mov_b32 s100, s22
	s_mov_b32 s101, s25
	s_add_u32 m0, s1, 0x0
	s_nop 0
	global_load_lds_dwordx4 v68, s[98:99]
	s_add_u32 m0, s1, 0x1000
	s_nop 0
	global_load_lds_dwordx4 v69, s[98:99]
	s_add_u32 m0, s1, 0x2000
	s_nop 0
	global_load_lds_dwordx4 v70, s[98:99]
	s_add_u32 m0, s1, 0x3000
	s_nop 0
	global_load_lds_dwordx4 v71, s[98:99]
	s_add_u32 m0, s1, 0x8000
	s_nop 0
	global_load_lds_dwordx4 v68, s[100:101]
	s_add_u32 m0, s1, 0x9000
	s_nop 0
	global_load_lds_dwordx4 v69, s[100:101]
	s_add_u32 m0, s1, 0xa000
	s_nop 0
	global_load_lds_dwordx4 v70, s[100:101]
	s_add_u32 m0, s1, 0xb000
	s_nop 0
	global_load_lds_dwordx4 v71, s[100:101]
	s_add_u32 s98, s98, 0x80
	s_addc_u32 s99, s99, 0
	s_add_u32 s100, s100, 0x80
	s_addc_u32 s101, s101, 0
	s_waitcnt vmcnt(0)

.LBB0_287:
	s_add_i32 s2, s6, 2
	s_setprio 1
	ds_read_b128 v[114:117], v165 offset:32768
	ds_read_b128 v[122:125], v165 offset:34816
	ds_read_b128 v[118:121], v161
	ds_read_b128 v[138:141], v161 offset:2048
	ds_read_b128 v[174:177], v161 offset:4096
	ds_read_b128 v[178:181], v161 offset:6144
	s_waitcnt lgkmcnt(3)
	v_mfma_f32_16x16x32_bf16 v[0:3], v[114:117], v[118:121], v[0:3]
	ds_read_b128 v[182:185], v165 offset:36864
	v_mfma_f32_16x16x32_bf16 v[4:7], v[122:125], v[118:121], v[4:7]
	ds_read_b128 v[186:189], v165 offset:38912
	s_waitcnt lgkmcnt(1)
	v_mfma_f32_16x16x32_bf16 v[8:11], v[182:185], v[118:121], v[8:11]
	s_waitcnt lgkmcnt(0)
	v_mfma_f32_16x16x32_bf16 v[12:15], v[186:189], v[118:121], v[12:15]
	s_add_u32 m0, s1, 0x4000
	s_nop 0
	global_load_lds_dwordx4 v68, s[98:99]
	ds_read_b128 v[190:193], v166
	v_mfma_f32_16x16x32_bf16 v[16:19], v[114:117], v[138:141], v[16:19]
	v_mfma_f32_16x16x32_bf16 v[20:23], v[122:125], v[138:141], v[20:23]
	s_add_u32 m0, s1, 0x5000
	s_nop 0
	global_load_lds_dwordx4 v69, s[98:99]
	ds_read_b128 v[198:201], v166 offset:2048
	v_mfma_f32_16x16x32_bf16 v[24:27], v[182:185], v[138:141], v[24:27]
	v_mfma_f32_16x16x32_bf16 v[28:31], v[186:189], v[138:141], v[28:31]
	s_add_u32 m0, s1, 0x6000
	s_nop 0
	global_load_lds_dwordx4 v70, s[98:99]
	ds_read_b128 v[202:205], v166 offset:4096
	v_mfma_f32_16x16x32_bf16 v[32:35], v[114:117], v[174:177], v[32:35]
	v_mfma_f32_16x16x32_bf16 v[36:39], v[122:125], v[174:177], v[36:39]
	s_add_u32 m0, s1, 0x7000
	s_nop 0
	global_load_lds_dwordx4 v71, s[98:99]
	ds_read_b128 v[210:213], v166 offset:6144
	v_mfma_f32_16x16x32_bf16 v[40:43], v[182:185], v[174:177], v[40:43]
	v_mfma_f32_16x16x32_bf16 v[44:47], v[186:189], v[174:177], v[44:47]
	s_add_u32 m0, s1, 0xc000
	s_nop 0
	global_load_lds_dwordx4 v68, s[100:101]
	ds_read_b128 v[214:217], v167 offset:32768
	v_mfma_f32_16x16x32_bf16 v[48:51], v[114:117], v[178:181], v[48:51]
	v_mfma_f32_16x16x32_bf16 v[52:55], v[122:125], v[178:181], v[52:55]
	s_add_u32 m0, s1, 0xd000
	s_nop 0
	global_load_lds_dwordx4 v69, s[100:101]
	ds_read_b128 v[122:125], v167 offset:34816
	v_mfma_f32_16x16x32_bf16 v[56:59], v[182:185], v[178:181], v[56:59]
	v_mfma_f32_16x16x32_bf16 v[60:63], v[186:189], v[178:181], v[60:63]
	s_add_u32 m0, s1, 0xe000
	s_nop 0
	global_load_lds_dwordx4 v70, s[100:101]
	ds_read_b128 v[182:185], v167 offset:36864
	s_waitcnt lgkmcnt(2)
	v_mfma_f32_16x16x32_bf16 v[0:3], v[214:217], v[190:193], v[0:3]
	s_waitcnt lgkmcnt(1)
	v_mfma_f32_16x16x32_bf16 v[4:7], v[122:125], v[190:193], v[4:7]
	s_add_u32 m0, s1, 0xf000
	s_nop 0
	global_load_lds_dwordx4 v71, s[100:101]
	s_add_u32 s98, s98, 0x80
	s_addc_u32 s99, s99, 0
	s_add_u32 s100, s100, 0x80
	s_addc_u32 s101, s101, 0
	ds_read_b128 v[218:221], v167 offset:38912
	s_waitcnt lgkmcnt(1)
	v_mfma_f32_16x16x32_bf16 v[8:11], v[182:185], v[190:193], v[8:11]
	s_waitcnt lgkmcnt(0)
	v_mfma_f32_16x16x32_bf16 v[12:15], v[218:221], v[190:193], v[12:15]
	v_mfma_f32_16x16x32_bf16 v[16:19], v[214:217], v[198:201], v[16:19]
	v_mfma_f32_16x16x32_bf16 v[20:23], v[122:125], v[198:201], v[20:23]
	v_mfma_f32_16x16x32_bf16 v[24:27], v[182:185], v[198:201], v[24:27]
	v_mfma_f32_16x16x32_bf16 v[28:31], v[218:221], v[198:201], v[28:31]
	v_mfma_f32_16x16x32_bf16 v[32:35], v[214:217], v[202:205], v[32:35]
	v_mfma_f32_16x16x32_bf16 v[36:39], v[122:125], v[202:205], v[36:39]
	v_mfma_f32_16x16x32_bf16 v[40:43], v[182:185], v[202:205], v[40:43]
	v_mfma_f32_16x16x32_bf16 v[44:47], v[218:221], v[202:205], v[44:47]
	v_mfma_f32_16x16x32_bf16 v[48:51], v[214:217], v[210:213], v[48:51]
	v_mfma_f32_16x16x32_bf16 v[52:55], v[122:125], v[210:213], v[52:55]
	v_mfma_f32_16x16x32_bf16 v[56:59], v[182:185], v[210:213], v[56:59]
	v_mfma_f32_16x16x32_bf16 v[60:63], v[218:221], v[210:213], v[60:63]
	s_setprio 0
	s_waitcnt vmcnt(0) lgkmcnt(0)
	s_barrier
	s_cmp_lg_u32 s6, 14
	s_cbranch_scc1 .Lnh287_skip
	s_mov_b32 s7, 0
	s_add_i32 s22, s33, s96
	s_cmp_lt_u32 s22, 0xa0
	s_cbranch_scc0 .Lnh287_skip
	s_lshr_b32 s24, s33, 3
	s_sub_u32 s24, s24, 10
	s_cmp_lt_u32 s24, 2
	s_cbranch_scc1 .Lnh287_skip
	s_and_b32 s25, s22, 7
	s_and_b32 m0, s33, 7
	s_sub_i32 s25, s25, m0
	s_lshl_b32 s25, s25, 18
	s_sub_i32 s25, s25, 0x800
	s_ashr_i32 m0, s25, 31
	s_add_u32 s98, s98, s25
	s_addc_u32 s99, s99, m0
	s_lshr_b32 s24, s22, 3
	s_lshr_b32 m0, s33, 3
	s_sub_i32 s24, s24, m0
	s_lshl_b32 s24, s24, 18
	s_sub_i32 s24, s24, 0x800
	s_ashr_i32 m0, s24, 31
	s_add_u32 s100, s100, s24
	s_addc_u32 s101, s101, m0
	s_mov_b32 s7, 1
.Lnh287_skip:
	s_setprio 1
	ds_read_b128 v[84:87], v165 offset:49152
	ds_read_b128 v[88:91], v165 offset:51200
	ds_read_b128 v[64:67], v161 offset:16384
	ds_read_b128 v[72:75], v161 offset:18432
	ds_read_b128 v[76:79], v161 offset:20480
	ds_read_b128 v[92:95], v161 offset:22528
	s_waitcnt lgkmcnt(3)
	v_mfma_f32_16x16x32_bf16 v[0:3], v[84:87], v[64:67], v[0:3]
	ds_read_b128 v[122:125], v165 offset:53248
	v_mfma_f32_16x16x32_bf16 v[4:7], v[88:91], v[64:67], v[4:7]
	ds_read_b128 v[182:185], v165 offset:55296
	s_waitcnt lgkmcnt(1)
	v_mfma_f32_16x16x32_bf16 v[8:11], v[122:125], v[64:67], v[8:11]
	s_waitcnt lgkmcnt(0)
	v_mfma_f32_16x16x32_bf16 v[12:15], v[182:185], v[64:67], v[12:15]
	s_add_u32 m0, s1, 0x0
	s_nop 0
	global_load_lds_dwordx4 v68, s[98:99]
	ds_read_b128 v[190:193], v166 offset:16384
	v_mfma_f32_16x16x32_bf16 v[16:19], v[84:87], v[72:75], v[16:19]
	v_mfma_f32_16x16x32_bf16 v[20:23], v[88:91], v[72:75], v[20:23]
	s_add_u32 m0, s1, 0x1000
	s_nop 0
	global_load_lds_dwordx4 v69, s[98:99]
	ds_read_b128 v[198:201], v166 offset:18432
	v_mfma_f32_16x16x32_bf16 v[24:27], v[122:125], v[72:75], v[24:27]
	v_mfma_f32_16x16x32_bf16 v[28:31], v[182:185], v[72:75], v[28:31]
	s_add_u32 m0, s1, 0x2000
	s_nop 0
	global_load_lds_dwordx4 v70, s[98:99]
	ds_read_b128 v[202:205], v166 offset:20480
	v_mfma_f32_16x16x32_bf16 v[32:35], v[84:87], v[76:79], v[32:35]
	v_mfma_f32_16x16x32_bf16 v[36:39], v[88:91], v[76:79], v[36:39]
	s_add_u32 m0, s1, 0x3000
	s_nop 0
	global_load_lds_dwordx4 v71, s[98:99]
	ds_read_b128 v[210:213], v166 offset:22528
	v_mfma_f32_16x16x32_bf16 v[40:43], v[122:125], v[76:79], v[40:43]
	v_mfma_f32_16x16x32_bf16 v[44:47], v[182:185], v[76:79], v[44:47]
	s_add_u32 m0, s1, 0x8000
	s_nop 0
	global_load_lds_dwordx4 v68, s[100:101]
	ds_read_b128 v[214:217], v167 offset:49152
	v_mfma_f32_16x16x32_bf16 v[48:51], v[84:87], v[92:95], v[48:51]
	v_mfma_f32_16x16x32_bf16 v[52:55], v[88:91], v[92:95], v[52:55]
	s_add_u32 m0, s1, 0x9000
	s_nop 0
	global_load_lds_dwordx4 v69, s[100:101]
	ds_read_b128 v[218:221], v167 offset:51200
	v_mfma_f32_16x16x32_bf16 v[56:59], v[122:125], v[92:95], v[56:59]
	v_mfma_f32_16x16x32_bf16 v[60:63], v[182:185], v[92:95], v[60:63]
	s_add_u32 m0, s1, 0xa000
	s_nop 0
	global_load_lds_dwordx4 v70, s[100:101]
	ds_read_b128 v[122:125], v167 offset:53248
	s_waitcnt lgkmcnt(2)
	v_mfma_f32_16x16x32_bf16 v[0:3], v[214:217], v[190:193], v[0:3]
	s_waitcnt lgkmcnt(1)
	v_mfma_f32_16x16x32_bf16 v[4:7], v[218:221], v[190:193], v[4:7]
	s_add_u32 m0, s1, 0xb000
	s_nop 0
	global_load_lds_dwordx4 v71, s[100:101]
	s_add_u32 s98, s98, 0x80
	s_addc_u32 s99, s99, 0
	s_add_u32 s100, s100, 0x80
	s_addc_u32 s101, s101, 0
	ds_read_b128 v[182:185], v167 offset:55296
	s_waitcnt lgkmcnt(1)
	v_mfma_f32_16x16x32_bf16 v[8:11], v[122:125], v[190:193], v[8:11]
	s_waitcnt lgkmcnt(0)
	v_mfma_f32_16x16x32_bf16 v[12:15], v[182:185], v[190:193], v[12:15]
	v_mfma_f32_16x16x32_bf16 v[16:19], v[214:217], v[198:201], v[16:19]
	v_mfma_f32_16x16x32_bf16 v[20:23], v[218:221], v[198:201], v[20:23]
	v_mfma_f32_16x16x32_bf16 v[24:27], v[122:125], v[198:201], v[24:27]
	v_mfma_f32_16x16x32_bf16 v[28:31], v[182:185], v[198:201], v[28:31]
	v_mfma_f32_16x16x32_bf16 v[32:35], v[214:217], v[202:205], v[32:35]
	v_mfma_f32_16x16x32_bf16 v[36:39], v[218:221], v[202:205], v[36:39]
	v_mfma_f32_16x16x32_bf16 v[40:43], v[122:125], v[202:205], v[40:43]
	v_mfma_f32_16x16x32_bf16 v[44:47], v[182:185], v[202:205], v[44:47]
	v_mfma_f32_16x16x32_bf16 v[48:51], v[214:217], v[210:213], v[48:51]
	v_mfma_f32_16x16x32_bf16 v[52:55], v[218:221], v[210:213], v[52:55]
	v_mfma_f32_16x16x32_bf16 v[56:59], v[122:125], v[210:213], v[56:59]
	v_mfma_f32_16x16x32_bf16 v[60:63], v[182:185], v[210:213], v[60:63]
	s_setprio 0
	s_mov_b32 s6, s2
	s_waitcnt vmcnt(0) lgkmcnt(0)
	s_barrier
	s_cmp_lt_u32 s6, 16
	s_cbranch_scc1 .LBB0_287
	s_cmp_eq_u32 s7, 1
	s_cbranch_scc1 .Lnx287_keep
	s_mov_b32 s98, 0
.Lnx287_keep:
	s_cmpk_lt_u32 s33, 0x50
	v_or_b32_e32 v138, s0, v234
	v_add_u32_e32 v128, s34, v164
	s_cselect_b64 s[24:25], -1, 0
	s_and_b32 s0, s33, 0x7ffffff0
	v_or_b32_e32 v173, v128, v148
	s_cmpk_lg_i32 s0, 0x50
	s_mov_b64 s[6:7], -1
	s_cbranch_scc0 .LBB0_298
	s_waitcnt vmcnt(7)
	v_lshlrev_b32_e32 v64, 1, v128
	s_and_b64 s[0:1], s[16:17], s[24:25]
	v_and_b32_e32 v128, 0x780, v64
	v_cndmask_b32_e64 v64, 0, 1, s[0:1]
	v_cmp_ne_u32_e64 s[6:7], 1, v64
	v_mov_b64_e32 v[66:67], v[2:3]
	s_waitcnt vmcnt(6)
	v_mov_b64_e32 v[70:71], v[6:7]
	s_waitcnt vmcnt(5)
	v_mov_b64_e32 v[74:75], v[10:11]
	s_waitcnt vmcnt(3)
	v_mov_b64_e32 v[78:79], v[14:15]
	v_lshl_add_u64 v[140:141], v[132:133], 0, v[128:129]
	s_andn2_b64 vcc, exec, s[0:1]
	v_lshlrev_b32_e32 v137, 7, v173
	v_mov_b64_e32 v[64:65], v[0:1]
	v_mov_b64_e32 v[68:69], v[4:5]
	v_mov_b64_e32 v[72:73], v[8:9]
	v_mov_b64_e32 v[76:77], v[12:13]
	s_cbranch_vccnz .LBB0_291
	v_and_b32_e32 v128, 0x780, v137
	v_lshl_add_u64 v[76:77], v[132:133], 0, v[128:129]
	global_load_dwordx4 v[64:67], v[140:141], off
	global_load_dwordx4 v[68:71], v[140:141], off offset:16
	global_load_dwordx4 v[72:75], v[76:77], off
	s_nop 0
	global_load_dwordx4 v[76:79], v[76:77], off offset:16
	v_mov_b32_e32 v80, v3
	v_mov_b32_e32 v81, v7
	v_mov_b32_e32 v82, v7
	v_mov_b32_e32 v83, v3
	s_waitcnt vmcnt(6)
	v_mov_b32_e32 v84, v11
	v_mov_b32_e32 v85, v15
	v_mov_b32_e32 v86, v15
	v_mov_b32_e32 v87, v11
	s_waitcnt vmcnt(3)
	v_mov_b32_e32 v88, v64
	v_mov_b32_e32 v89, v66
	v_mov_b32_e32 v66, v65
	s_waitcnt vmcnt(2)
	v_mul_f32_e32 v90, v2, v68
	v_mul_f32_e32 v92, v6, v69
	v_mul_f32_e32 v94, v6, v68
	v_mul_f32_e32 v96, v2, v69
	v_pk_mul_f32 v[64:65], v[80:81], v[70:71]
	v_pk_mul_f32 v[68:69], v[82:83], v[70:71]
	s_waitcnt vmcnt(1)
	v_mov_b32_e32 v80, v72
	v_mov_b32_e32 v81, v74
	v_mov_b32_e32 v74, v73
	s_waitcnt vmcnt(0)
	v_mul_f32_e32 v82, v10, v76
	v_mul_f32_e32 v98, v14, v77
	v_mul_f32_e32 v100, v14, v76
	v_mul_f32_e32 v102, v10, v77
	v_pk_mul_f32 v[72:73], v[84:85], v[78:79]
	v_pk_mul_f32 v[76:77], v[86:87], v[78:79]
	v_pk_mul_f32 v[70:71], v[0:1], v[66:67]
	v_pk_mul_f32 v[66:67], v[4:5], v[66:67]
	v_mov_b32_e32 v91, v64
	v_mov_b32_e32 v93, v65
	v_mov_b32_e32 v95, v68
	v_mov_b32_e32 v97, v69
	v_pk_mul_f32 v[78:79], v[8:9], v[74:75]
	v_pk_mul_f32 v[74:75], v[12:13], v[74:75]
	v_mov_b32_e32 v83, v72
	v_mov_b32_e32 v99, v73
	v_mov_b32_e32 v101, v76
	v_mov_b32_e32 v103, v77
	v_pk_fma_f32 v[64:65], v[0:1], v[88:89], v[66:67] neg_lo:[0,0,1] neg_hi:[0,0,1]
	v_pk_add_f32 v[66:67], v[90:91], v[92:93] neg_lo:[0,1] neg_hi:[0,1]
	v_pk_fma_f32 v[68:69], v[4:5], v[88:89], v[70:71]
	v_pk_add_f32 v[70:71], v[94:95], v[96:97]
	v_pk_fma_f32 v[72:73], v[8:9], v[80:81], v[74:75] neg_lo:[0,0,1] neg_hi:[0,0,1]
	v_pk_add_f32 v[74:75], v[82:83], v[98:99] neg_lo:[0,1] neg_hi:[0,1]
	v_pk_fma_f32 v[76:77], v[12:13], v[80:81], v[78:79]
	v_pk_add_f32 v[78:79], v[100:101], v[102:103]

.LBB0_463:
	s_add_i32 s42, s43, 2
	s_setprio 1
	ds_read_b128 v[126:129], v120 offset:32768
	ds_read_b128 v[134:137], v120 offset:34816
	ds_read_b128 v[130:133], v119
	ds_read_b128 v[138:141], v119 offset:2048
	ds_read_b128 v[164:167], v119 offset:4096
	ds_read_b128 v[168:171], v119 offset:6144
	s_waitcnt lgkmcnt(3)
	v_mfma_f32_16x16x32_bf16 v[60:63], v[126:129], v[130:133], v[60:63]
	ds_read_b128 v[172:175], v120 offset:36864
	v_mfma_f32_16x16x32_bf16 v[40:43], v[134:137], v[130:133], v[40:43]
	ds_read_b128 v[176:179], v120 offset:38912
	s_waitcnt lgkmcnt(1)
	v_mfma_f32_16x16x32_bf16 v[28:31], v[172:175], v[130:133], v[28:31]
	s_waitcnt lgkmcnt(0)
	v_mfma_f32_16x16x32_bf16 v[12:15], v[176:179], v[130:133], v[12:15]
	s_add_u32 m0, s44, 0x4000
	s_nop 0
	global_load_lds_dwordx4 v68, s[98:99]
	ds_read_b128 v[180:183], v121
	v_mfma_f32_16x16x32_bf16 v[56:59], v[126:129], v[138:141], v[56:59]
	v_mfma_f32_16x16x32_bf16 v[44:47], v[134:137], v[138:141], v[44:47]
	s_add_u32 m0, s44, 0x5000
	s_nop 0
	global_load_lds_dwordx4 v69, s[98:99]
	ds_read_b128 v[188:191], v121 offset:2048
	v_mfma_f32_16x16x32_bf16 v[24:27], v[172:175], v[138:141], v[24:27]
	v_mfma_f32_16x16x32_bf16 v[8:11], v[176:179], v[138:141], v[8:11]
	s_add_u32 m0, s44, 0x6000
	s_nop 0
	global_load_lds_dwordx4 v70, s[98:99]
	ds_read_b128 v[192:195], v121 offset:4096
	v_mfma_f32_16x16x32_bf16 v[52:55], v[126:129], v[164:167], v[52:55]
	v_mfma_f32_16x16x32_bf16 v[36:39], v[134:137], v[164:167], v[36:39]
	s_add_u32 m0, s44, 0x7000
	s_nop 0
	global_load_lds_dwordx4 v71, s[98:99]
	ds_read_b128 v[200:203], v121 offset:6144
	v_mfma_f32_16x16x32_bf16 v[20:23], v[172:175], v[164:167], v[20:23]
	v_mfma_f32_16x16x32_bf16 v[4:7], v[176:179], v[164:167], v[4:7]
	s_add_u32 m0, s44, 0xc000
	s_nop 0
	global_load_lds_dwordx4 v68, s[100:101]
	ds_read_b128 v[204:207], v122 offset:32768
	v_mfma_f32_16x16x32_bf16 v[48:51], v[126:129], v[168:171], v[48:51]
	v_mfma_f32_16x16x32_bf16 v[32:35], v[134:137], v[168:171], v[32:35]
	s_add_u32 m0, s44, 0xd000
	s_nop 0
	global_load_lds_dwordx4 v69, s[100:101]
	ds_read_b128 v[134:137], v122 offset:34816
	v_mfma_f32_16x16x32_bf16 v[16:19], v[172:175], v[168:171], v[16:19]
	v_mfma_f32_16x16x32_bf16 v[0:3], v[176:179], v[168:171], v[0:3]
	s_add_u32 m0, s44, 0xe000
	s_nop 0
	global_load_lds_dwordx4 v70, s[100:101]
	ds_read_b128 v[172:175], v122 offset:36864
	s_waitcnt lgkmcnt(2)
	v_mfma_f32_16x16x32_bf16 v[60:63], v[204:207], v[180:183], v[60:63]
	s_waitcnt lgkmcnt(1)
	v_mfma_f32_16x16x32_bf16 v[40:43], v[134:137], v[180:183], v[40:43]
	s_add_u32 m0, s44, 0xf000
	s_nop 0
	global_load_lds_dwordx4 v71, s[100:101]
	s_add_u32 s98, s98, 0x80
	s_addc_u32 s99, s99, 0
	s_add_u32 s100, s100, 0x80
	s_addc_u32 s101, s101, 0
	ds_read_b128 v[208:211], v122 offset:38912
	s_waitcnt lgkmcnt(1)
	v_mfma_f32_16x16x32_bf16 v[28:31], v[172:175], v[180:183], v[28:31]
	s_waitcnt lgkmcnt(0)
	v_mfma_f32_16x16x32_bf16 v[12:15], v[208:211], v[180:183], v[12:15]
	v_mfma_f32_16x16x32_bf16 v[56:59], v[204:207], v[188:191], v[56:59]
	v_mfma_f32_16x16x32_bf16 v[44:47], v[134:137], v[188:191], v[44:47]
	v_mfma_f32_16x16x32_bf16 v[24:27], v[172:175], v[188:191], v[24:27]
	v_mfma_f32_16x16x32_bf16 v[8:11], v[208:211], v[188:191], v[8:11]
	v_mfma_f32_16x16x32_bf16 v[52:55], v[204:207], v[192:195], v[52:55]
	v_mfma_f32_16x16x32_bf16 v[36:39], v[134:137], v[192:195], v[36:39]
	v_mfma_f32_16x16x32_bf16 v[20:23], v[172:175], v[192:195], v[20:23]
	v_mfma_f32_16x16x32_bf16 v[4:7], v[208:211], v[192:195], v[4:7]
	v_mfma_f32_16x16x32_bf16 v[48:51], v[204:207], v[200:203], v[48:51]
	v_mfma_f32_16x16x32_bf16 v[32:35], v[134:137], v[200:203], v[32:35]
	v_mfma_f32_16x16x32_bf16 v[16:19], v[172:175], v[200:203], v[16:19]
	v_mfma_f32_16x16x32_bf16 v[0:3], v[208:211], v[200:203], v[0:3]
	s_setprio 0
	s_waitcnt vmcnt(0) lgkmcnt(0)
	s_barrier
	s_setprio 1
	ds_read_b128 v[84:87], v120 offset:49152
	ds_read_b128 v[88:91], v120 offset:51200
	ds_read_b128 v[64:67], v119 offset:16384
	ds_read_b128 v[72:75], v119 offset:18432
	ds_read_b128 v[76:79], v119 offset:20480
	ds_read_b128 v[92:95], v119 offset:22528
	s_waitcnt lgkmcnt(3)
	v_mfma_f32_16x16x32_bf16 v[60:63], v[84:87], v[64:67], v[60:63]
	ds_read_b128 v[134:137], v120 offset:53248
	v_mfma_f32_16x16x32_bf16 v[40:43], v[88:91], v[64:67], v[40:43]
	ds_read_b128 v[172:175], v120 offset:55296
	s_waitcnt lgkmcnt(1)
	v_mfma_f32_16x16x32_bf16 v[28:31], v[134:137], v[64:67], v[28:31]
	s_waitcnt lgkmcnt(0)
	v_mfma_f32_16x16x32_bf16 v[12:15], v[172:175], v[64:67], v[12:15]
	s_add_u32 m0, s44, 0x0
	s_nop 0
	global_load_lds_dwordx4 v68, s[98:99]
	ds_read_b128 v[180:183], v121 offset:16384
	v_mfma_f32_16x16x32_bf16 v[56:59], v[84:87], v[72:75], v[56:59]
	v_mfma_f32_16x16x32_bf16 v[44:47], v[88:91], v[72:75], v[44:47]
	s_add_u32 m0, s44, 0x1000
	s_nop 0
	global_load_lds_dwordx4 v69, s[98:99]
	ds_read_b128 v[188:191], v121 offset:18432
	v_mfma_f32_16x16x32_bf16 v[24:27], v[134:137], v[72:75], v[24:27]
	v_mfma_f32_16x16x32_bf16 v[8:11], v[172:175], v[72:75], v[8:11]
	s_add_u32 m0, s44, 0x2000
	s_nop 0
	global_load_lds_dwordx4 v70, s[98:99]
	ds_read_b128 v[192:195], v121 offset:20480
	v_mfma_f32_16x16x32_bf16 v[52:55], v[84:87], v[76:79], v[52:55]
	v_mfma_f32_16x16x32_bf16 v[36:39], v[88:91], v[76:79], v[36:39]
	s_add_u32 m0, s44, 0x3000
	s_nop 0
	global_load_lds_dwordx4 v71, s[98:99]
	ds_read_b128 v[200:203], v121 offset:22528
	v_mfma_f32_16x16x32_bf16 v[20:23], v[134:137], v[76:79], v[20:23]
	v_mfma_f32_16x16x32_bf16 v[4:7], v[172:175], v[76:79], v[4:7]
	s_add_u32 m0, s44, 0x8000
	s_nop 0
	global_load_lds_dwordx4 v68, s[100:101]
	ds_read_b128 v[204:207], v122 offset:49152
	v_mfma_f32_16x16x32_bf16 v[48:51], v[84:87], v[92:95], v[48:51]
	v_mfma_f32_16x16x32_bf16 v[32:35], v[88:91], v[92:95], v[32:35]
	s_add_u32 m0, s44, 0x9000
	s_nop 0
	global_load_lds_dwordx4 v69, s[100:101]
	ds_read_b128 v[208:211], v122 offset:51200
	v_mfma_f32_16x16x32_bf16 v[16:19], v[134:137], v[92:95], v[16:19]
	v_mfma_f32_16x16x32_bf16 v[0:3], v[172:175], v[92:95], v[0:3]
	s_add_u32 m0, s44, 0xa000
	s_nop 0
	global_load_lds_dwordx4 v70, s[100:101]
	ds_read_b128 v[134:137], v122 offset:53248
	s_waitcnt lgkmcnt(2)
	v_mfma_f32_16x16x32_bf16 v[60:63], v[204:207], v[180:183], v[60:63]
	s_waitcnt lgkmcnt(1)
	v_mfma_f32_16x16x32_bf16 v[40:43], v[208:211], v[180:183], v[40:43]
	s_add_u32 m0, s44, 0xb000
	s_nop 0
	global_load_lds_dwordx4 v71, s[100:101]
	s_add_u32 s98, s98, 0x80
	s_addc_u32 s99, s99, 0
	s_add_u32 s100, s100, 0x80
	s_addc_u32 s101, s101, 0
	ds_read_b128 v[172:175], v122 offset:55296
	s_waitcnt lgkmcnt(1)
	v_mfma_f32_16x16x32_bf16 v[28:31], v[134:137], v[180:183], v[28:31]
	s_waitcnt lgkmcnt(0)
	v_mfma_f32_16x16x32_bf16 v[12:15], v[172:175], v[180:183], v[12:15]
	v_mfma_f32_16x16x32_bf16 v[56:59], v[204:207], v[188:191], v[56:59]
	v_mfma_f32_16x16x32_bf16 v[44:47], v[208:211], v[188:191], v[44:47]
	v_mfma_f32_16x16x32_bf16 v[24:27], v[134:137], v[188:191], v[24:27]
	v_mfma_f32_16x16x32_bf16 v[8:11], v[172:175], v[188:191], v[8:11]
	v_mfma_f32_16x16x32_bf16 v[52:55], v[204:207], v[192:195], v[52:55]
	v_mfma_f32_16x16x32_bf16 v[36:39], v[208:211], v[192:195], v[36:39]
	v_mfma_f32_16x16x32_bf16 v[20:23], v[134:137], v[192:195], v[20:23]
	v_mfma_f32_16x16x32_bf16 v[4:7], v[172:175], v[192:195], v[4:7]
	v_mfma_f32_16x16x32_bf16 v[48:51], v[204:207], v[200:203], v[48:51]
	v_mfma_f32_16x16x32_bf16 v[32:35], v[208:211], v[200:203], v[32:35]
	v_mfma_f32_16x16x32_bf16 v[16:19], v[134:137], v[200:203], v[16:19]
	v_mfma_f32_16x16x32_bf16 v[0:3], v[172:175], v[200:203], v[0:3]
	s_setprio 0
	s_mov_b32 s43, s42
	s_waitcnt vmcnt(0) lgkmcnt(0)
	s_barrier
	s_cmp_lt_u32 s43, 16
	s_cbranch_scc1 .LBB0_463
	s_mov_b32 s98, 0
	s_waitcnt vmcnt(6)
	v_add_u32_e32 v70, s1, v118
	s_addk_i32 s1, 0xf000
	s_ashr_i32 s1, s1, 10
	s_add_i32 s1, s1, 1
	s_and_b64 s[42:43], s[20:21], exec
	s_cselect_b32 s1, 0, s1
	s_mul_i32 s26, s1, 0x3000
	s_mul_hi_i32 s2, s1, 0x3000
	s_add_u32 s42, s4, s26
	s_addc_u32 s2, s5, s2
	v_or_b32_e32 v98, v70, v148
	s_add_u32 s44, s42, 0x2000
	s_addc_u32 s45, s2, 0
	s_add_i32 s1, s1, 5
	s_add_i32 s26, s26, 0xf000
	v_add_u32_e32 v66, 0xfffff000, v98
	v_mov_b32_e32 v67, v97
	s_mul_hi_u32 s1, s1, 0x3000
	s_add_u32 s2, s4, s26
	s_waitcnt vmcnt(5)
	v_lshlrev_b32_e32 v72, 12, v98
	v_mov_b32_e32 v73, v97
	v_lshlrev_b64 v[66:67], 12, v[66:67]
	s_addc_u32 s1, s5, s1
	v_or_b32_e32 v96, s0, v123
	v_lshl_add_u64 v[64:65], s[8:9], 0, v[72:73]
	v_lshl_add_u64 v[66:67], s[10:11], 0, v[66:67]
	v_cmp_gt_u32_e32 vcc, s48, v70
	s_add_u32 s42, s2, 0x1000
	s_waitcnt vmcnt(0)
	v_lshlrev_b64 v[92:93], 2, v[96:97]
	v_cndmask_b32_e32 v65, v67, v65, vcc
	v_cndmask_b32_e32 v64, v66, v64, vcc
	v_lshl_add_u64 v[68:69], s[44:45], 0, v[92:93]
	v_lshl_add_u64 v[76:77], v[64:65], 0, v[92:93]
	s_addc_u32 s43, s1, 0
	global_load_dwordx4 v[64:67], v[76:77], off nt
	global_load_dwordx4 v[100:103], v[68:69], off
	v_lshl_add_u64 v[68:69], s[42:43], 0, v[92:93]
	global_load_dwordx4 v[82:85], v[68:69], off
	v_lshl_add_u64 v[68:69], s[28:29], 0, v[92:93]
	global_load_dwordx4 v[86:89], v[68:69], off
	v_lshlrev_b32_e32 v99, 10, v98
	v_mov_b32_e32 v91, v97
	v_mov_b32_e32 v81, v97
	v_lshl_add_u64 v[70:71], s[12:13], 0, v[92:93]
	v_add_u32_e32 v80, 0xfffff010, v98
	v_or_b32_e32 v90, 0x4000, v99
	v_lshl_add_u64 v[78:79], v[70:71], 0, v[72:73]
	v_lshlrev_b64 v[80:81], 12, v[80:81]
	v_lshlrev_b64 v[72:73], 2, v[90:91]
	v_lshl_add_u64 v[80:81], s[10:11], 0, v[80:81]
	v_lshl_add_u64 v[106:107], s[8:9], 0, v[72:73]
	v_mov_b32_e32 v75, v97
	v_lshlrev_b32_e32 v74, 1, v96
	v_cndmask_b32_e32 v81, v81, v107, vcc
	v_cndmask_b32_e32 v80, v80, v106, vcc
	v_mov_b32_e32 v95, v97
	v_lshl_add_u64 v[104:105], s[22:23], 0, v[74:75]
	v_lshlrev_b32_e32 v94, 11, v98
	v_lshl_add_u64 v[74:75], v[104:105], 0, v[94:95]
	v_lshl_add_u64 v[80:81], v[80:81], 0, v[92:93]
	v_lshl_add_u64 v[94:95], s[22:23], 0, v[94:95]
	s_waitcnt vmcnt(2)
	v_pk_fma_f32 v[60:61], v[60:61], v[100:101], v[64:65]
	v_pk_fma_f32 v[62:63], v[62:63], v[102:103], v[66:67]
	s_waitcnt vmcnt(1)
	v_pk_add_f32 v[64:65], v[82:83], 1.0 op_sel_hi:[1,0]
	v_pk_add_f32 v[66:67], v[84:85], 1.0 op_sel_hi:[1,0]
	s_waitcnt vmcnt(0)
	v_pk_mul_f32 v[106:107], v[86:87], v[64:65]
	v_pk_mul_f32 v[108:109], v[88:89], v[66:67]
	v_pk_mul_f32 v[64:65], v[106:107], v[60:61]
	v_pk_mul_f32 v[66:67], v[108:109], v[62:63]
	v_cvt_pk_bf16_f32 v64, v64, v65
	v_cvt_pk_bf16_f32 v65, v66, v67
	global_store_dwordx4 v[78:79], v[60:63], off
	global_store_dwordx2 v[74:75], v[64:65], off
	global_load_dwordx4 v[64:67], v[80:81], off nt
	v_mov_b32_e32 v75, v97
	v_mov_b32_e32 v85, v97
	v_add_u32_e32 v84, 0xfffff020, v98
	v_or_b32_e32 v74, 0x8000, v99
	v_lshlrev_b64 v[86:87], 12, v[84:85]
	v_lshlrev_b64 v[84:85], 2, v[74:75]
	v_mov_b32_e32 v83, v97
	v_lshlrev_b32_e32 v82, 1, v90
	v_lshl_add_u64 v[86:87], s[10:11], 0, v[86:87]
	v_lshl_add_u64 v[110:111], s[8:9], 0, v[84:85]
	v_lshl_add_u64 v[88:89], v[70:71], 0, v[72:73]
	v_lshl_add_u64 v[90:91], v[104:105], 0, v[82:83]
	v_cndmask_b32_e32 v87, v87, v111, vcc
	v_cndmask_b32_e32 v86, v86, v110, vcc
	v_lshl_add_u64 v[86:87], v[86:87], 0, v[92:93]
	v_mov_b32_e32 v111, v97
	v_add_u32_e32 v110, 0xfffff030, v98
	v_lshlrev_b64 v[110:111], 12, v[110:111]
	v_lshl_add_u64 v[110:111], s[10:11], 0, v[110:111]
	v_lshl_add_u64 v[112:113], v[70:71], 0, v[84:85]
	v_pk_mul_f32 v[60:61], v[60:61], v[60:61]
	v_pk_mul_f32 v[62:63], v[62:63], v[62:63]
	v_add_f32_e32 v60, v61, v60
	v_add_f32_e32 v60, v62, v60
	s_waitcnt vmcnt(0)
	v_pk_fma_f32 v[56:57], v[56:57], v[100:101], v[64:65]
	v_pk_fma_f32 v[58:59], v[58:59], v[102:103], v[66:67]
	v_pk_mul_f32 v[64:65], v[106:107], v[56:57]
	v_pk_mul_f32 v[66:67], v[108:109], v[58:59]
	v_cvt_pk_bf16_f32 v64, v64, v65
	v_cvt_pk_bf16_f32 v65, v66, v67
	global_store_dwordx4 v[88:89], v[56:59], off
	global_store_dwordx2 v[90:91], v[64:65], off
	global_load_dwordx4 v[64:67], v[86:87], off nt
	v_mov_b32_e32 v89, v97
	v_or_b32_e32 v88, 0xc000, v99
	v_lshlrev_b32_e32 v90, 1, v74
	v_lshlrev_b64 v[74:75], 2, v[88:89]
	v_mov_b32_e32 v91, v97
	v_lshl_add_u64 v[126:127], s[8:9], 0, v[74:75]
	v_lshl_add_u64 v[114:115], v[104:105], 0, v[90:91]
	v_cndmask_b32_e32 v111, v111, v127, vcc
	v_cndmask_b32_e32 v110, v110, v126, vcc
	v_lshl_add_u64 v[92:93], v[110:111], 0, v[92:93]
	v_lshlrev_b32_e32 v88, 1, v88
	v_lshl_add_u64 v[104:105], v[104:105], 0, v[88:89]
	s_waitcnt vmcnt(0)
	v_pk_fma_f32 v[52:53], v[52:53], v[100:101], v[64:65]
	v_pk_fma_f32 v[54:55], v[54:55], v[102:103], v[66:67]
	v_pk_mul_f32 v[64:65], v[106:107], v[52:53]
	v_pk_mul_f32 v[66:67], v[108:109], v[54:55]
	v_cvt_pk_bf16_f32 v64, v64, v65
	v_cvt_pk_bf16_f32 v65, v66, v67
	global_store_dwordx4 v[112:113], v[52:55], off
	global_store_dwordx2 v[114:115], v[64:65], off
	global_load_dwordx4 v[64:67], v[92:93], off nt
	v_mov_b32_e32 v113, v97
	v_or_b32_e32 v112, 16, v96
	v_lshl_add_u64 v[114:115], v[70:71], 0, v[74:75]
	v_lshlrev_b64 v[110:111], 2, v[112:113]
	v_lshl_add_u64 v[126:127], s[44:45], 0, v[110:111]
	v_lshlrev_b32_e32 v112, 1, v112
	s_waitcnt vmcnt(0)
	v_pk_fma_f32 v[48:49], v[48:49], v[100:101], v[64:65]
	v_pk_fma_f32 v[50:51], v[50:51], v[102:103], v[66:67]
	v_pk_mul_f32 v[64:65], v[106:107], v[48:49]
	v_pk_mul_f32 v[66:67], v[108:109], v[50:51]
	v_cvt_pk_bf16_f32 v64, v64, v65
	v_cvt_pk_bf16_f32 v65, v66, v67
	global_store_dwordx4 v[114:115], v[48:51], off
	global_store_dwordx2 v[104:105], v[64:65], off
	global_load_dwordx4 v[64:67], v[76:77], off offset:64 nt
	s_nop 0
	global_load_dwordx4 v[100:103], v[126:127], off
	v_lshl_add_u64 v[104:105], s[42:43], 0, v[110:111]
	global_load_dwordx4 v[104:107], v[104:105], off
	s_nop 0
	global_load_dwordx4 v[108:111], v[68:69], off offset:64
	v_lshl_add_u64 v[114:115], v[94:95], 0, v[112:113]
	s_waitcnt vmcnt(2)
	v_pk_fma_f32 v[64:65], v[40:41], v[100:101], v[64:65]
	v_pk_fma_f32 v[66:67], v[42:43], v[102:103], v[66:67]
	s_waitcnt vmcnt(1)
	v_pk_add_f32 v[40:41], v[104:105], 1.0 op_sel_hi:[1,0]
	v_pk_add_f32 v[42:43], v[106:107], 1.0 op_sel_hi:[1,0]
	s_waitcnt vmcnt(0)
	v_pk_mul_f32 v[104:105], v[108:109], v[40:41]
	v_pk_mul_f32 v[106:107], v[110:111], v[42:43]
	v_pk_mul_f32 v[40:41], v[104:105], v[64:65]
	v_pk_mul_f32 v[42:43], v[106:107], v[66:67]
	v_cvt_pk_bf16_f32 v40, v40, v41
	v_cvt_pk_bf16_f32 v41, v42, v43
	global_store_dwordx4 v[78:79], v[64:67], off offset:64
	global_store_dwordx2 v[114:115], v[40:41], off
	global_load_dwordx4 v[40:43], v[80:81], off offset:64 nt
	v_lshl_add_u64 v[108:109], v[70:71], 0, 64
	v_lshl_add_u64 v[110:111], s[22:23], 0, v[112:113]
	v_lshl_add_u64 v[112:113], v[108:109], 0, v[72:73]
	v_lshl_add_u64 v[114:115], v[110:111], 0, v[82:83]
	s_waitcnt vmcnt(0)
	v_pk_fma_f32 v[40:41], v[44:45], v[100:101], v[40:41]
	v_pk_fma_f32 v[42:43], v[46:47], v[102:103], v[42:43]
	v_pk_mul_f32 v[44:45], v[104:105], v[40:41]
	v_pk_mul_f32 v[46:47], v[106:107], v[42:43]
	v_cvt_pk_bf16_f32 v44, v44, v45
	v_cvt_pk_bf16_f32 v45, v46, v47
	global_store_dwordx4 v[112:113], v[40:43], off
	global_store_dwordx2 v[114:115], v[44:45], off
	global_load_dwordx4 v[44:47], v[86:87], off offset:64 nt
	v_lshl_add_u64 v[112:113], v[108:109], 0, v[84:85]
	v_lshl_add_u64 v[114:115], v[110:111], 0, v[90:91]
	v_lshl_add_u64 v[108:109], v[108:109], 0, v[74:75]
	v_lshl_add_u64 v[110:111], v[110:111], 0, v[88:89]
	s_waitcnt vmcnt(0)
	v_pk_fma_f32 v[36:37], v[36:37], v[100:101], v[44:45]
	v_pk_fma_f32 v[38:39], v[38:39], v[102:103], v[46:47]
	v_pk_mul_f32 v[44:45], v[104:105], v[36:37]
	v_pk_mul_f32 v[46:47], v[106:107], v[38:39]
	v_cvt_pk_bf16_f32 v44, v44, v45
	v_cvt_pk_bf16_f32 v45, v46, v47
	global_store_dwordx4 v[112:113], v[36:39], off
	global_store_dwordx2 v[114:115], v[44:45], off
	global_load_dwordx4 v[44:47], v[92:93], off offset:64 nt
	v_mov_b32_e32 v113, v97
	v_or_b32_e32 v112, 32, v96
	v_lshlrev_b64 v[114:115], 2, v[112:113]
	v_lshl_add_u64 v[126:127], s[44:45], 0, v[114:115]
	v_lshlrev_b32_e32 v112, 1, v112
	v_or_b32_e32 v96, 48, v96
	s_waitcnt vmcnt(0)
	v_pk_fma_f32 v[32:33], v[32:33], v[100:101], v[44:45]
	v_pk_fma_f32 v[34:35], v[34:35], v[102:103], v[46:47]
	v_pk_mul_f32 v[44:45], v[104:105], v[32:33]
	v_pk_mul_f32 v[46:47], v[106:107], v[34:35]
	v_cvt_pk_bf16_f32 v44, v44, v45
	v_cvt_pk_bf16_f32 v45, v46, v47
	global_store_dwordx4 v[108:109], v[32:35], off
	global_store_dwordx2 v[110:111], v[44:45], off
	global_load_dwordx4 v[44:47], v[76:77], off offset:128 nt
	s_nop 0
	global_load_dwordx4 v[100:103], v[126:127], off
	v_lshl_add_u64 v[104:105], s[42:43], 0, v[114:115]
	global_load_dwordx4 v[104:107], v[104:105], off
	s_nop 0
	global_load_dwordx4 v[108:111], v[68:69], off offset:128
	v_lshl_add_u64 v[114:115], v[94:95], 0, v[112:113]
	s_waitcnt vmcnt(2)
	v_pk_fma_f32 v[28:29], v[28:29], v[100:101], v[44:45]
	v_pk_fma_f32 v[30:31], v[30:31], v[102:103], v[46:47]
	s_waitcnt vmcnt(1)
	v_pk_add_f32 v[44:45], v[104:105], 1.0 op_sel_hi:[1,0]
	v_pk_add_f32 v[46:47], v[106:107], 1.0 op_sel_hi:[1,0]
	s_waitcnt vmcnt(0)
	v_pk_mul_f32 v[104:105], v[108:109], v[44:45]
	v_pk_mul_f32 v[106:107], v[110:111], v[46:47]
	v_pk_mul_f32 v[44:45], v[104:105], v[28:29]
	v_pk_mul_f32 v[46:47], v[106:107], v[30:31]
	v_cvt_pk_bf16_f32 v44, v44, v45
	v_cvt_pk_bf16_f32 v45, v46, v47
	global_store_dwordx4 v[78:79], v[28:31], off offset:128
	global_store_dwordx2 v[114:115], v[44:45], off
	global_load_dwordx4 v[44:47], v[80:81], off offset:128 nt
	v_lshl_add_u64 v[108:109], v[70:71], 0, s[38:39]
	v_lshl_add_u64 v[110:111], s[22:23], 0, v[112:113]
	v_lshl_add_u64 v[112:113], v[108:109], 0, v[72:73]
	v_lshl_add_u64 v[114:115], v[110:111], 0, v[82:83]
	v_pk_mul_f32 v[28:29], v[28:29], v[28:29]
	v_pk_mul_f32 v[30:31], v[30:31], v[30:31]
	v_add_f32_e32 v28, v29, v28
	v_add_f32_e32 v28, v30, v28
	v_add_f32_e32 v28, v31, v28
	s_waitcnt vmcnt(0)
	v_pk_fma_f32 v[24:25], v[24:25], v[100:101], v[44:45]
	v_pk_fma_f32 v[26:27], v[26:27], v[102:103], v[46:47]
	v_pk_mul_f32 v[44:45], v[104:105], v[24:25]
	v_pk_mul_f32 v[46:47], v[106:107], v[26:27]
	v_cvt_pk_bf16_f32 v44, v44, v45
	v_cvt_pk_bf16_f32 v45, v46, v47
	global_store_dwordx4 v[112:113], v[24:27], off
	global_store_dwordx2 v[114:115], v[44:45], off
	global_load_dwordx4 v[44:47], v[86:87], off offset:128 nt
	v_lshl_add_u64 v[112:113], v[108:109], 0, v[84:85]
	v_lshl_add_u64 v[114:115], v[110:111], 0, v[90:91]
	v_lshl_add_u64 v[108:109], v[108:109], 0, v[74:75]
	v_lshl_add_u64 v[110:111], v[110:111], 0, v[88:89]
	s_waitcnt vmcnt(0)
	v_pk_fma_f32 v[20:21], v[20:21], v[100:101], v[44:45]
	v_pk_fma_f32 v[22:23], v[22:23], v[102:103], v[46:47]
	v_pk_mul_f32 v[44:45], v[104:105], v[20:21]
	v_pk_mul_f32 v[46:47], v[106:107], v[22:23]
	v_cvt_pk_bf16_f32 v44, v44, v45
	v_cvt_pk_bf16_f32 v45, v46, v47
	global_store_dwordx4 v[112:113], v[20:23], off
	global_store_dwordx2 v[114:115], v[44:45], off
	global_load_dwordx4 v[44:47], v[92:93], off offset:128 nt
	v_lshlrev_b64 v[112:113], 2, v[96:97]
	v_lshl_add_u64 v[114:115], s[44:45], 0, v[112:113]
	v_lshlrev_b32_e32 v96, 1, v96
	s_waitcnt vmcnt(0)
	v_pk_fma_f32 v[16:17], v[16:17], v[100:101], v[44:45]
	v_pk_fma_f32 v[18:19], v[18:19], v[102:103], v[46:47]
	v_pk_mul_f32 v[44:45], v[104:105], v[16:17]
	v_pk_mul_f32 v[46:47], v[106:107], v[18:19]
	v_cvt_pk_bf16_f32 v44, v44, v45
	v_cvt_pk_bf16_f32 v45, v46, v47
	global_store_dwordx4 v[108:109], v[16:19], off
	global_store_dwordx2 v[110:111], v[44:45], off
	global_load_dwordx4 v[44:47], v[76:77], off offset:192 nt
	s_nop 0
	global_load_dwordx4 v[100:103], v[114:115], off
	v_lshl_add_u64 v[76:77], s[42:43], 0, v[112:113]
	global_load_dwordx4 v[104:107], v[76:77], off
	global_load_dwordx4 v[108:111], v[68:69], off offset:192
	v_lshl_add_u64 v[68:69], v[94:95], 0, v[96:97]
	s_waitcnt vmcnt(2)
	v_pk_fma_f32 v[12:13], v[12:13], v[100:101], v[44:45]
	v_pk_fma_f32 v[14:15], v[14:15], v[102:103], v[46:47]
	s_waitcnt vmcnt(1)
	v_pk_add_f32 v[44:45], v[104:105], 1.0 op_sel_hi:[1,0]
	v_pk_add_f32 v[46:47], v[106:107], 1.0 op_sel_hi:[1,0]
	s_waitcnt vmcnt(0)
	v_pk_mul_f32 v[76:77], v[108:109], v[44:45]
	v_pk_mul_f32 v[94:95], v[110:111], v[46:47]
	v_pk_mul_f32 v[44:45], v[76:77], v[12:13]
	v_pk_mul_f32 v[46:47], v[94:95], v[14:15]
	v_cvt_pk_bf16_f32 v44, v44, v45
	v_cvt_pk_bf16_f32 v45, v46, v47
	global_store_dwordx4 v[78:79], v[12:15], off offset:192
	global_store_dwordx2 v[68:69], v[44:45], off
	global_load_dwordx4 v[44:47], v[80:81], off offset:192 nt
	v_lshl_add_u64 v[68:69], v[70:71], 0, s[40:41]
	v_lshl_add_u64 v[70:71], s[22:23], 0, v[96:97]
	v_lshl_add_u64 v[72:73], v[68:69], 0, v[72:73]
	v_lshl_add_u64 v[78:79], v[70:71], 0, v[82:83]
	v_pk_mul_f32 v[12:13], v[12:13], v[12:13]
	v_pk_mul_f32 v[14:15], v[14:15], v[14:15]
	v_add_f32_e32 v12, v13, v12
	v_add_f32_e32 v12, v14, v12
	v_add_f32_e32 v12, v15, v12
	v_lshlrev_b32_e32 v96, 2, v98
	s_waitcnt vmcnt(0)
	v_pk_fma_f32 v[8:9], v[8:9], v[100:101], v[44:45]
	v_pk_fma_f32 v[10:11], v[10:11], v[102:103], v[46:47]
	v_pk_mul_f32 v[44:45], v[76:77], v[8:9]
	v_pk_mul_f32 v[46:47], v[94:95], v[10:11]
	v_cvt_pk_bf16_f32 v44, v44, v45
	v_cvt_pk_bf16_f32 v45, v46, v47
	global_store_dwordx4 v[72:73], v[8:11], off
	global_store_dwordx2 v[78:79], v[44:45], off
	global_load_dwordx4 v[44:47], v[86:87], off offset:192 nt
	v_lshl_add_u64 v[72:73], v[68:69], 0, v[84:85]
	v_lshl_add_u64 v[78:79], v[70:71], 0, v[90:91]
	s_waitcnt vmcnt(0)
	v_pk_fma_f32 v[4:5], v[4:5], v[100:101], v[44:45]
	v_pk_fma_f32 v[6:7], v[6:7], v[102:103], v[46:47]
	v_pk_mul_f32 v[44:45], v[76:77], v[4:5]
	v_pk_mul_f32 v[46:47], v[94:95], v[6:7]
	v_cvt_pk_bf16_f32 v44, v44, v45
	v_cvt_pk_bf16_f32 v45, v46, v47
	global_store_dwordx4 v[72:73], v[4:7], off
	global_store_dwordx2 v[78:79], v[44:45], off
	global_load_dwordx4 v[44:47], v[92:93], off offset:192 nt
	v_add_f32_e32 v72, v63, v60
	v_pk_mul_f32 v[60:61], v[64:65], v[64:65]
	v_pk_mul_f32 v[62:63], v[66:67], v[66:67]
	v_add_f32_e32 v60, v61, v60
	v_add_f32_e32 v60, v62, v60
	v_add_f32_e32 v60, v63, v60
	v_add_f32_e32 v60, v72, v60
	v_add_f32_e32 v28, v60, v28
	v_add_f32_e32 v14, v28, v12
	ds_bpermute_b32 v15, v124, v14
	v_lshl_add_u64 v[12:13], v[68:69], 0, v[74:75]
	v_lshl_add_u64 v[28:29], v[70:71], 0, v[88:89]
	s_waitcnt lgkmcnt(0)
	v_add_f32_e32 v14, v14, v15
	ds_bpermute_b32 v15, v125, v14
	s_waitcnt vmcnt(0)
	v_pk_fma_f32 v[0:1], v[0:1], v[100:101], v[44:45]
	v_pk_fma_f32 v[2:3], v[2:3], v[102:103], v[46:47]
	global_store_dwordx4 v[12:13], v[0:3], off
	v_pk_mul_f32 v[12:13], v[76:77], v[0:1]
	v_pk_mul_f32 v[30:31], v[94:95], v[2:3]
	v_cvt_pk_bf16_f32 v12, v12, v13
	v_cvt_pk_bf16_f32 v13, v30, v31
	global_store_dwordx2 v[28:29], v[12:13], off
	v_lshl_add_u64 v[12:13], s[24:25], 0, v[96:97]
	s_and_saveexec_b64 s[42:43], s[6:7]
	s_cbranch_execz .LBB0_466
	s_waitcnt lgkmcnt(0)
	v_add_f32_e32 v14, v14, v15
	global_atomic_add_f32 v[12:13], v14, off

.LBB0_527:
	s_and_b32 s0, s43, 7
	s_or_b32 s0, s0, s3
	s_lshl_b32 s44, s0, 7
	v_or_b32_e32 v0, s44, v149
	v_lshl_or_b32 v160, v0, 11, v159
	v_lshl_add_u64 v[30:31], s[22:23], 0, v[160:161]
	v_add_co_u32_e32 v4, vcc, 0x10000, v30
	s_lshl_b32 s1, s43, 4
	s_nop 0
	v_addc_co_u32_e32 v5, vcc, 0, v31, vcc
	s_and_b32 s0, s1, 0x7fffff80
	v_add_co_u32_e32 v12, vcc, 0x20000, v30
	v_or_b32_e32 v0, s0, v149
	s_nop 0
	v_addc_co_u32_e32 v13, vcc, 0, v31, vcc
	v_lshl_or_b32 v24, v0, 11, v159
	v_add_co_u32_e32 v16, vcc, 0x30000, v30
	v_mov_b32_e32 v25, v161
	s_nop 0
	v_addc_co_u32_e32 v17, vcc, 0, v31, vcc
	v_lshl_add_u64 v[52:53], s[16:17], 0, v[24:25]
	v_add_co_u32_e32 v18, vcc, s38, v52
	s_nop 0
	v_addc_co_u32_e32 v19, vcc, 0, v53, vcc
	v_add_co_u32_e32 v28, vcc, s39, v52
	s_nop 0
	v_addc_co_u32_e32 v29, vcc, 0, v53, vcc
	v_add_co_u32_e32 v58, vcc, s40, v52
	s_nop 0
	v_addc_co_u32_e32 v59, vcc, 0, v53, vcc
	s_nop 0
	s_nop 0
	s_nop 0
	s_movk_i32 s1, 0x100
	s_mov_b32 s6, s37
	v_mov_b32_e32 v8, 0
	v_mov_b32_e32 v9, v161
	v_mov_b32_e32 v10, v161
	v_mov_b32_e32 v11, v161
	v_mov_b32_e32 v26, 0
	v_mov_b32_e32 v27, v161
	v_mov_b32_e32 v28, v161
	v_mov_b32_e32 v29, v161
	v_mov_b32_e32 v16, 0
	v_mov_b32_e32 v17, v161
	v_mov_b32_e32 v18, v161
	v_mov_b32_e32 v19, v161
	v_mov_b32_e32 v60, 0
	v_mov_b32_e32 v61, v161
	v_lshl_add_u64 v[58:59], v[52:53], 0, s[14:15]
	v_lshl_add_u64 v[104:105], v[52:53], 0, s[30:31]
	v_lshl_add_u64 v[106:107], v[52:53], 0, s[34:35]
	v_lshl_add_u64 v[108:109], v[30:31], 0, s[14:15]
	v_lshl_add_u64 v[110:111], v[30:31], 0, s[30:31]
	v_lshl_add_u64 v[112:113], v[30:31], 0, s[34:35]
	s_barrier
	v_mov_b32_e32 v88, 0
	v_mov_b32_e32 v89, v161
	v_mov_b32_e32 v90, v161
	v_mov_b32_e32 v91, v161
	v_mov_b32_e32 v76, 0
	v_mov_b32_e32 v77, v161
	v_mov_b32_e32 v78, v161
	v_mov_b32_e32 v79, v161
	v_mov_b32_e32 v80, 0
	v_mov_b32_e32 v81, v161
	v_mov_b32_e32 v82, v161
	v_mov_b32_e32 v83, v161
	v_mov_b32_e32 v84, 0
	v_mov_b32_e32 v85, v161
	v_mov_b32_e32 v86, v161
	v_mov_b32_e32 v87, v161
	v_mov_b32_e32 v74, v161
	v_mov_b32_e32 v75, v161
	v_mov_b32_e32 v62, v161
	v_mov_b32_e32 v63, v161
	v_mov_b32_e32 v36, 0
	v_mov_b32_e32 v37, v161
	v_mov_b32_e32 v38, v161
	v_mov_b32_e32 v39, v161
	v_mov_b32_e32 v54, 0
	v_mov_b32_e32 v55, v161
	v_mov_b32_e32 v56, v161
	v_mov_b32_e32 v57, v161
	v_mov_b32_e32 v32, 0
	v_mov_b32_e32 v33, v161
	v_mov_b32_e32 v34, v161
	v_mov_b32_e32 v35, v161
	v_mov_b32_e32 v64, 0
	v_mov_b32_e32 v65, v161
	v_mov_b32_e32 v66, v161
	v_mov_b32_e32 v67, v161
	v_mov_b32_e32 v40, 0
	v_mov_b32_e32 v41, v161
	v_mov_b32_e32 v42, v161
	v_mov_b32_e32 v43, v161
	v_mov_b32_e32 v48, 0
	v_mov_b32_e32 v49, v161
	v_mov_b32_e32 v50, v161
	v_mov_b32_e32 v51, v161
	v_mov_b32_e32 v68, 0
	v_mov_b32_e32 v69, v161
	v_mov_b32_e32 v70, v161
	v_mov_b32_e32 v71, v161
	v_mov_b32_e32 v72, 0
	v_mov_b32_e32 v73, v161
	v_readlane_b32 s8, v253, 0
	v_readlane_b32 s9, v253, 1
	s_load_dwordx2 s[8:9], s[8:9], 0x160
	v_lshrrev_b32_e32 v7, 6, v146
	s_nop 0
	v_readfirstlane_b32 s1, v7
	v_lshrrev_b32_e32 v5, 3, v146
	v_and_b32_e32 v6, 7, v146
	v_xor_b32_e32 v6, v5, v6
	v_and_b32_e32 v6, 7, v6
	v_lshlrev_b32_e32 v6, 4, v6
	v_lshl_or_b32 v4, v5, 11, v6
	v_add_u32_e32 v5, 0x10000, v4
	v_add_u32_e32 v6, 0x20000, v4
	v_add_u32_e32 v7, 0x30000, v4
	s_and_b32 s7, s43, 7
	s_and_b32 s36, s69, 7
	s_lshl_b32 s36, s36, 3
	s_or_b32 s7, s7, s36
	s_lshl_b32 s7, s7, 18
	s_add_u32 s7, s7, 0xdc40000
	s_lshr_b32 s36, s43, 3
	s_lshl_b32 s36, s36, 18
	s_add_u32 s36, s36, 0x7700000
	s_lshl_b32 s1, s1, 10
	s_waitcnt lgkmcnt(0)
	s_add_u32 s7, s8, s7
	s_addc_u32 m0, s9, 0
	s_add_u32 s36, s8, s36
	s_addc_u32 s9, s9, 0
	s_add_u32 s8, s7, 0x80
	s_cmp_eq_u32 s8, s98
	s_cbranch_scc0 .Lnp528_load
	s_add_u32 s8, s36, 0x80
	s_cmp_eq_u32 s8, s100
	s_cbranch_scc1 .Lnp528_have
.Lnp528_load:
	s_mov_b32 s98, s7
	s_mov_b32 s99, m0
	s_mov_b32 s100, s36
	s_mov_b32 s101, s9
	s_add_u32 m0, s1, 0x0
	s_nop 0
	global_load_lds_dwordx4 v4, s[98:99]
	s_add_u32 m0, s1, 0x1000
	s_nop 0
	global_load_lds_dwordx4 v5, s[98:99]
	s_add_u32 m0, s1, 0x2000
	s_nop 0
	global_load_lds_dwordx4 v6, s[98:99]
	s_add_u32 m0, s1, 0x3000
	s_nop 0
	global_load_lds_dwordx4 v7, s[98:99]
	s_add_u32 m0, s1, 0x8000
	s_nop 0
	global_load_lds_dwordx4 v4, s[100:101]
	s_add_u32 m0, s1, 0x9000
	s_nop 0
	global_load_lds_dwordx4 v5, s[100:101]
	s_add_u32 m0, s1, 0xa000
	s_nop 0
	global_load_lds_dwordx4 v6, s[100:101]
	s_add_u32 m0, s1, 0xb000
	s_nop 0
	global_load_lds_dwordx4 v7, s[100:101]
	s_add_u32 s98, s98, 0x80
	s_addc_u32 s99, s99, 0
	s_add_u32 s100, s100, 0x80
	s_addc_u32 s101, s101, 0
	s_waitcnt vmcnt(0)

.LBB0_528:
	s_add_i32 s2, s6, 2
	s_setprio 1
	ds_read_b128 v[114:117], v175 offset:32768
	ds_read_b128 v[122:125], v175 offset:34816
	ds_read_b128 v[118:121], v174
	ds_read_b128 v[136:139], v174 offset:2048
	ds_read_b128 v[140:143], v174 offset:4096
	ds_read_b128 v[162:165], v174 offset:6144
	s_waitcnt lgkmcnt(3)
	v_mfma_f32_16x16x32_bf16 v[8:11], v[114:117], v[118:121], v[8:11]
	ds_read_b128 v[166:169], v175 offset:36864
	v_mfma_f32_16x16x32_bf16 v[26:29], v[122:125], v[118:121], v[26:29]
	ds_read_b128 v[182:185], v175 offset:38912
	s_waitcnt lgkmcnt(1)
	v_mfma_f32_16x16x32_bf16 v[16:19], v[166:169], v[118:121], v[16:19]
	s_waitcnt lgkmcnt(0)
	v_mfma_f32_16x16x32_bf16 v[60:63], v[182:185], v[118:121], v[60:63]
	s_add_u32 m0, s1, 0x4000
	s_nop 0
	global_load_lds_dwordx4 v4, s[98:99]
	ds_read_b128 v[186:189], v176
	v_mfma_f32_16x16x32_bf16 v[36:39], v[114:117], v[136:139], v[36:39]
	v_mfma_f32_16x16x32_bf16 v[54:57], v[122:125], v[136:139], v[54:57]
	s_add_u32 m0, s1, 0x5000
	s_nop 0
	global_load_lds_dwordx4 v5, s[98:99]
	ds_read_b128 v[194:197], v176 offset:2048
	v_mfma_f32_16x16x32_bf16 v[32:35], v[166:169], v[136:139], v[32:35]
	v_mfma_f32_16x16x32_bf16 v[64:67], v[182:185], v[136:139], v[64:67]
	s_add_u32 m0, s1, 0x6000
	s_nop 0
	global_load_lds_dwordx4 v6, s[98:99]
	ds_read_b128 v[198:201], v176 offset:4096
	v_mfma_f32_16x16x32_bf16 v[40:43], v[114:117], v[140:143], v[40:43]
	v_mfma_f32_16x16x32_bf16 v[88:91], v[122:125], v[140:143], v[88:91]
	s_add_u32 m0, s1, 0x7000
	s_nop 0
	global_load_lds_dwordx4 v7, s[98:99]
	ds_read_b128 v[206:209], v176 offset:6144
	v_mfma_f32_16x16x32_bf16 v[48:51], v[166:169], v[140:143], v[48:51]
	v_mfma_f32_16x16x32_bf16 v[76:79], v[182:185], v[140:143], v[76:79]
	s_add_u32 m0, s1, 0xc000
	s_nop 0
	global_load_lds_dwordx4 v4, s[100:101]
	ds_read_b128 v[210:213], v177 offset:32768
	v_mfma_f32_16x16x32_bf16 v[80:83], v[114:117], v[162:165], v[80:83]
	v_mfma_f32_16x16x32_bf16 v[84:87], v[122:125], v[162:165], v[84:87]
	s_add_u32 m0, s1, 0xd000
	s_nop 0
	global_load_lds_dwordx4 v5, s[100:101]
	ds_read_b128 v[122:125], v177 offset:34816
	v_mfma_f32_16x16x32_bf16 v[68:71], v[166:169], v[162:165], v[68:71]
	v_mfma_f32_16x16x32_bf16 v[72:75], v[182:185], v[162:165], v[72:75]
	s_add_u32 m0, s1, 0xe000
	s_nop 0
	global_load_lds_dwordx4 v6, s[100:101]
	ds_read_b128 v[166:169], v177 offset:36864
	s_waitcnt lgkmcnt(2)
	v_mfma_f32_16x16x32_bf16 v[8:11], v[210:213], v[186:189], v[8:11]
	s_waitcnt lgkmcnt(1)
	v_mfma_f32_16x16x32_bf16 v[26:29], v[122:125], v[186:189], v[26:29]
	s_add_u32 m0, s1, 0xf000
	s_nop 0
	global_load_lds_dwordx4 v7, s[100:101]
	s_add_u32 s98, s98, 0x80
	s_addc_u32 s99, s99, 0
	s_add_u32 s100, s100, 0x80
	s_addc_u32 s101, s101, 0
	ds_read_b128 v[214:217], v177 offset:38912
	s_waitcnt lgkmcnt(1)
	v_mfma_f32_16x16x32_bf16 v[16:19], v[166:169], v[186:189], v[16:19]
	s_waitcnt lgkmcnt(0)
	v_mfma_f32_16x16x32_bf16 v[60:63], v[214:217], v[186:189], v[60:63]
	v_mfma_f32_16x16x32_bf16 v[36:39], v[210:213], v[194:197], v[36:39]
	v_mfma_f32_16x16x32_bf16 v[54:57], v[122:125], v[194:197], v[54:57]
	v_mfma_f32_16x16x32_bf16 v[32:35], v[166:169], v[194:197], v[32:35]
	v_mfma_f32_16x16x32_bf16 v[64:67], v[214:217], v[194:197], v[64:67]
	v_mfma_f32_16x16x32_bf16 v[40:43], v[210:213], v[198:201], v[40:43]
	v_mfma_f32_16x16x32_bf16 v[88:91], v[122:125], v[198:201], v[88:91]
	v_mfma_f32_16x16x32_bf16 v[48:51], v[166:169], v[198:201], v[48:51]
	v_mfma_f32_16x16x32_bf16 v[76:79], v[214:217], v[198:201], v[76:79]
	v_mfma_f32_16x16x32_bf16 v[80:83], v[210:213], v[206:209], v[80:83]
	v_mfma_f32_16x16x32_bf16 v[84:87], v[122:125], v[206:209], v[84:87]
	v_mfma_f32_16x16x32_bf16 v[68:71], v[166:169], v[206:209], v[68:71]
	v_mfma_f32_16x16x32_bf16 v[72:75], v[214:217], v[206:209], v[72:75]
	s_setprio 0
	s_waitcnt vmcnt(0) lgkmcnt(0)
	s_barrier
	s_cmp_lg_u32 s6, 14
	s_cbranch_scc1 .Lnh528_skip
	s_mov_b32 s7, 0
	s_add_i32 s36, s43, s96
	s_cmp_lt_u32 s36, 0x100
	s_cbranch_scc0 .Lnh528_skip
	s_lshr_b32 s8, s43, 3
	s_sub_u32 s8, s8, 16
	s_cmp_lt_u32 s8, 8
	s_cbranch_scc1 .Lnh528_skip
	s_and_b32 s9, s36, 7
	s_and_b32 m0, s43, 7
	s_sub_i32 s9, s9, m0
	s_lshl_b32 s9, s9, 18
	s_sub_i32 s9, s9, 0x800
	s_ashr_i32 m0, s9, 31
	s_add_u32 s98, s98, s9
	s_addc_u32 s99, s99, m0
	s_lshr_b32 s8, s36, 3
	s_lshr_b32 m0, s43, 3
	s_sub_i32 s8, s8, m0
	s_lshl_b32 s8, s8, 18
	s_sub_i32 s8, s8, 0x800
	s_ashr_i32 m0, s8, 31
	s_add_u32 s100, s100, s8
	s_addc_u32 s101, s101, m0
	s_mov_b32 s7, 1
.Lnh528_skip:
	s_setprio 1
	ds_read_b128 v[92:95], v175 offset:49152
	ds_read_b128 v[96:99], v175 offset:51200
	ds_read_b128 v[0:3], v174 offset:16384
	ds_read_b128 v[12:15], v174 offset:18432
	ds_read_b128 v[20:23], v174 offset:20480
	ds_read_b128 v[100:103], v174 offset:22528
	s_waitcnt lgkmcnt(3)
	v_mfma_f32_16x16x32_bf16 v[8:11], v[92:95], v[0:3], v[8:11]
	ds_read_b128 v[122:125], v175 offset:53248
	v_mfma_f32_16x16x32_bf16 v[26:29], v[96:99], v[0:3], v[26:29]
	ds_read_b128 v[166:169], v175 offset:55296
	s_waitcnt lgkmcnt(1)
	v_mfma_f32_16x16x32_bf16 v[16:19], v[122:125], v[0:3], v[16:19]
	s_waitcnt lgkmcnt(0)
	v_mfma_f32_16x16x32_bf16 v[60:63], v[166:169], v[0:3], v[60:63]
	s_add_u32 m0, s1, 0x0
	s_nop 0
	global_load_lds_dwordx4 v4, s[98:99]
	ds_read_b128 v[186:189], v176 offset:16384
	v_mfma_f32_16x16x32_bf16 v[36:39], v[92:95], v[12:15], v[36:39]
	v_mfma_f32_16x16x32_bf16 v[54:57], v[96:99], v[12:15], v[54:57]
	s_add_u32 m0, s1, 0x1000
	s_nop 0
	global_load_lds_dwordx4 v5, s[98:99]
	ds_read_b128 v[194:197], v176 offset:18432
	v_mfma_f32_16x16x32_bf16 v[32:35], v[122:125], v[12:15], v[32:35]
	v_mfma_f32_16x16x32_bf16 v[64:67], v[166:169], v[12:15], v[64:67]
	s_add_u32 m0, s1, 0x2000
	s_nop 0
	global_load_lds_dwordx4 v6, s[98:99]
	ds_read_b128 v[198:201], v176 offset:20480
	v_mfma_f32_16x16x32_bf16 v[40:43], v[92:95], v[20:23], v[40:43]
	v_mfma_f32_16x16x32_bf16 v[88:91], v[96:99], v[20:23], v[88:91]
	s_add_u32 m0, s1, 0x3000
	s_nop 0
	global_load_lds_dwordx4 v7, s[98:99]
	ds_read_b128 v[206:209], v176 offset:22528
	v_mfma_f32_16x16x32_bf16 v[48:51], v[122:125], v[20:23], v[48:51]
	v_mfma_f32_16x16x32_bf16 v[76:79], v[166:169], v[20:23], v[76:79]
	s_add_u32 m0, s1, 0x8000
	s_nop 0
	global_load_lds_dwordx4 v4, s[100:101]
	ds_read_b128 v[210:213], v177 offset:49152
	v_mfma_f32_16x16x32_bf16 v[80:83], v[92:95], v[100:103], v[80:83]
	v_mfma_f32_16x16x32_bf16 v[84:87], v[96:99], v[100:103], v[84:87]
	s_add_u32 m0, s1, 0x9000
	s_nop 0
	global_load_lds_dwordx4 v5, s[100:101]
	ds_read_b128 v[214:217], v177 offset:51200
	v_mfma_f32_16x16x32_bf16 v[68:71], v[122:125], v[100:103], v[68:71]
	v_mfma_f32_16x16x32_bf16 v[72:75], v[166:169], v[100:103], v[72:75]
	s_add_u32 m0, s1, 0xa000
	s_nop 0
	global_load_lds_dwordx4 v6, s[100:101]
	ds_read_b128 v[122:125], v177 offset:53248
	s_waitcnt lgkmcnt(2)
	v_mfma_f32_16x16x32_bf16 v[8:11], v[210:213], v[186:189], v[8:11]
	s_waitcnt lgkmcnt(1)
	v_mfma_f32_16x16x32_bf16 v[26:29], v[214:217], v[186:189], v[26:29]
	s_add_u32 m0, s1, 0xb000
	s_nop 0
	global_load_lds_dwordx4 v7, s[100:101]
	s_add_u32 s98, s98, 0x80
	s_addc_u32 s99, s99, 0
	s_add_u32 s100, s100, 0x80
	s_addc_u32 s101, s101, 0
	ds_read_b128 v[166:169], v177 offset:55296
	s_waitcnt lgkmcnt(1)
	v_mfma_f32_16x16x32_bf16 v[16:19], v[122:125], v[186:189], v[16:19]
	s_waitcnt lgkmcnt(0)
	v_mfma_f32_16x16x32_bf16 v[60:63], v[166:169], v[186:189], v[60:63]
	v_mfma_f32_16x16x32_bf16 v[36:39], v[210:213], v[194:197], v[36:39]
	v_mfma_f32_16x16x32_bf16 v[54:57], v[214:217], v[194:197], v[54:57]
	v_mfma_f32_16x16x32_bf16 v[32:35], v[122:125], v[194:197], v[32:35]
	v_mfma_f32_16x16x32_bf16 v[64:67], v[166:169], v[194:197], v[64:67]
	v_mfma_f32_16x16x32_bf16 v[40:43], v[210:213], v[198:201], v[40:43]
	v_mfma_f32_16x16x32_bf16 v[88:91], v[214:217], v[198:201], v[88:91]
	v_mfma_f32_16x16x32_bf16 v[48:51], v[122:125], v[198:201], v[48:51]
	v_mfma_f32_16x16x32_bf16 v[76:79], v[166:169], v[198:201], v[76:79]
	v_mfma_f32_16x16x32_bf16 v[80:83], v[210:213], v[206:209], v[80:83]
	v_mfma_f32_16x16x32_bf16 v[84:87], v[214:217], v[206:209], v[84:87]
	v_mfma_f32_16x16x32_bf16 v[68:71], v[122:125], v[206:209], v[68:71]
	v_mfma_f32_16x16x32_bf16 v[72:75], v[166:169], v[206:209], v[72:75]
	s_setprio 0
	s_mov_b32 s6, s2
	s_waitcnt vmcnt(0) lgkmcnt(0)
	s_barrier
	s_cmp_lt_u32 s6, 16
	s_cbranch_scc1 .LBB0_528
	s_cmp_eq_u32 s7, 1
	s_cbranch_scc1 .Lnx528_keep
	s_mov_b32 s98, 0
.Lnx528_keep:
	s_waitcnt vmcnt(5)
	v_add_u32_e32 v15, s44, v173
	v_or_b32_e32 v181, v15, v148
	v_or_b32_e32 v160, s0, v234
	s_add_i32 s0, s44, 0xfffff000
	v_lshlrev_b32_e32 v0, 2, v181
	s_ashr_i32 s0, s0, 10
	global_load_dword v14, v0, s[28:29]
	global_load_dword v30, v0, s[28:29] offset:64
	global_load_dword v31, v0, s[28:29] offset:128
	global_load_dword v44, v0, s[28:29] offset:192
	s_add_i32 s2, s0, 6
	s_and_b64 s[0:1], s[24:25], exec
	s_cselect_b32 s0, 5, s2
	s_mul_hi_u32 s1, s0, 0x4200
	s_mulk_i32 s0, 0x4200
	s_add_u32 s0, s4, s0
	s_addc_u32 s1, s5, s1
	v_mov_b32_e32 v135, v161
	v_lshl_add_u64 v[0:1], v[160:161], 2, s[0:1]
	v_lshl_add_u64 v[4:5], v[0:1], 0, v[134:135]
	global_load_dwordx4 v[22:25], v[4:5], off
	global_load_dwordx4 v[0:3], v[4:5], off offset:64
	global_load_dwordx4 v[92:95], v[4:5], off offset:128
	s_nop 0
	global_load_dwordx4 v[4:7], v[4:5], off offset:192
	v_mov_b32_e32 v12, v26
	v_mov_b32_e32 v13, v9
	v_mov_b32_e32 v9, v27
	s_waitcnt vmcnt(11)
	v_mov_b32_e32 v20, v54
	v_mov_b32_e32 v21, v37
	v_mov_b32_e32 v37, v55
	s_cmpk_lt_u32 s43, 0x80
	s_waitcnt vmcnt(7)
	v_fmamk_f32 v14, v14, 0x3a800000, v179
	s_waitcnt vmcnt(6)
	v_fmamk_f32 v26, v30, 0x3a800000, v179
	v_cmp_gt_f32_e64 s[6:7], s41, v26
	s_waitcnt vmcnt(4)
	v_fmamk_f32 v30, v44, 0x3a800000, v179
	v_mul_f32_e32 v44, 0x4b800000, v26
	v_fmamk_f32 v27, v31, 0x3a800000, v179
	v_mul_f32_e32 v46, 0x4b800000, v30
	v_cndmask_b32_e64 v26, v26, v44, s[6:7]
	v_cmp_gt_f32_e64 s[10:11], s41, v30
	v_mul_f32_e32 v31, 0x4b800000, v14
	v_mul_f32_e32 v45, 0x4b800000, v27
	v_cmp_gt_f32_e32 vcc, s41, v14
	v_cmp_gt_f32_e64 s[8:9], s41, v27
	v_cndmask_b32_e64 v30, v30, v46, s[10:11]
	v_rsq_f32_e32 v26, v26
	v_cndmask_b32_e32 v14, v14, v31, vcc
	v_cndmask_b32_e64 v27, v27, v45, s[8:9]
	v_rsq_f32_e32 v30, v30
	v_rsq_f32_e32 v14, v14
	v_rsq_f32_e32 v27, v27
	s_waitcnt vmcnt(2)
	v_mov_b32_e32 v97, v3
	v_mul_f32_e32 v3, 0x45800000, v26
	v_mov_b32_e32 v96, v25
	v_mul_f32_e32 v25, 0x45800000, v30
	v_cndmask_b32_e64 v102, v26, v3, s[6:7]
	v_mul_f32_e32 v31, 0x45800000, v14
	s_waitcnt vmcnt(0)
	v_mov_b32_e32 v99, v7
	v_mul_f32_e32 v7, 0x45800000, v27
	v_cndmask_b32_e64 v106, v30, v25, s[10:11]
	v_fma_f32 v30, v56, v102, v2
	v_mov_b32_e32 v56, v39
	v_mov_b32_e32 v53, v1
	v_mov_b32_e32 v1, v23
	v_cndmask_b32_e32 v100, v14, v31, vcc
	v_cndmask_b32_e64 v104, v27, v7, s[8:9]
	v_pk_fma_f32 v[140:141], v[56:57], v[102:103], v[96:97] op_sel_hi:[1,0,1]
	v_mov_b32_e32 v56, v88
	v_mov_b32_e32 v57, v41
	v_mov_b32_e32 v98, v95
	v_mov_b32_e32 v52, v22
	v_fma_f32 v14, v28, v100, v2
	v_mov_b32_e32 v28, v11
	v_fma_f32 v26, v38, v102, v24
	v_fma_f32 v38, v66, v102, v6
	v_mov_b32_e32 v66, v35
	v_mov_b32_e32 v41, v89
	v_pk_fma_f32 v[162:163], v[56:57], v[104:105], v[0:1] op_sel_hi:[1,0,1]
	v_mov_b32_e32 v56, v80
	v_mov_b32_e32 v57, v85
	v_mov_b32_e32 v85, v81
	v_fma_f32 v10, v10, v100, v24
	v_fma_f32 v42, v42, v104, v24
	v_fma_f32 v58, v82, v106, v24
	v_pk_fma_f32 v[8:9], v[8:9], v[100:101], v[52:53] op_sel_hi:[1,0,1]
	v_pk_fma_f32 v[136:137], v[12:13], v[100:101], v[0:1] op_sel_hi:[1,0,1]
	v_pk_fma_f32 v[24:25], v[36:37], v[102:103], v[52:53] op_sel_hi:[1,0,1]
	v_pk_fma_f32 v[20:21], v[20:21], v[102:103], v[0:1] op_sel_hi:[1,0,1]
	v_pk_fma_f32 v[138:139], v[28:29], v[100:101], v[96:97] op_sel_hi:[1,0,1]
	v_pk_fma_f32 v[28:29], v[66:67], v[102:103], v[98:99] op_sel_hi:[1,0,1]
	v_pk_fma_f32 v[40:41], v[40:41], v[104:105], v[52:53] op_sel_hi:[1,0,1]
	v_pk_fma_f32 v[56:57], v[56:57], v[106:107], v[52:53] op_sel_hi:[1,0,1]
	v_pk_fma_f32 v[52:53], v[84:85], v[106:107], v[0:1] op_sel_hi:[1,0,1]
	v_mov_b32_e32 v0, v60
	v_mov_b32_e32 v1, v17
	v_mov_b32_e32 v66, v4
	v_mov_b32_e32 v67, v93
	v_pk_fma_f32 v[142:143], v[0:1], v[100:101], v[66:67] op_sel_hi:[1,0,1]
	v_mov_b32_e32 v0, v64
	v_mov_b32_e32 v1, v33
	v_pk_fma_f32 v[164:165], v[0:1], v[102:103], v[66:67] op_sel_hi:[1,0,1]
	v_mov_b32_e32 v0, v76
	v_mov_b32_e32 v1, v49
	v_fma_f32 v22, v62, v100, v6
	v_mov_b32_e32 v62, v19
	v_fma_f32 v46, v90, v104, v2
	v_mov_b32_e32 v90, v43
	v_fma_f32 v54, v78, v104, v6
	v_mov_b32_e32 v78, v51
	v_fmac_f32_e32 v2, v86, v106
	v_mov_b32_e32 v86, v83
	v_mov_b32_e32 v17, v61
	v_mov_b32_e32 v93, v5
	v_mov_b32_e32 v33, v65
	v_pk_fma_f32 v[168:169], v[0:1], v[104:105], v[66:67] op_sel_hi:[1,0,1]
	v_mov_b32_e32 v49, v77
	v_mov_b32_e32 v0, v68
	v_mov_b32_e32 v1, v73
	v_mov_b32_e32 v73, v69
	v_fmac_f32_e32 v6, v74, v106
	v_mov_b32_e32 v74, v71
	s_cselect_b64 s[8:9], -1, 0
	s_and_b32 s0, s43, 0x7fffffc0
	v_fma_f32 v18, v18, v100, v94
	v_fma_f32 v34, v34, v102, v94
	v_fma_f32 v50, v50, v104, v94
	v_pk_fma_f32 v[12:13], v[62:63], v[100:101], v[98:99] op_sel_hi:[1,0,1]
	v_pk_fma_f32 v[36:37], v[90:91], v[104:105], v[96:97] op_sel_hi:[1,0,1]
	v_pk_fma_f32 v[44:45], v[78:79], v[104:105], v[98:99] op_sel_hi:[1,0,1]
	v_pk_fma_f32 v[166:167], v[86:87], v[106:107], v[96:97] op_sel_hi:[1,0,1]
	v_fma_f32 v62, v70, v106, v94
	v_pk_fma_f32 v[16:17], v[16:17], v[100:101], v[92:93] op_sel_hi:[1,0,1]
	v_pk_fma_f32 v[32:33], v[32:33], v[102:103], v[92:93] op_sel_hi:[1,0,1]
	v_pk_fma_f32 v[48:49], v[48:49], v[104:105], v[92:93] op_sel_hi:[1,0,1]
	v_pk_fma_f32 v[60:61], v[0:1], v[106:107], v[92:93] op_sel_hi:[1,0,1]
	v_pk_fma_f32 v[0:1], v[72:73], v[106:107], v[66:67] op_sel_hi:[1,0,1]
	v_pk_fma_f32 v[170:171], v[74:75], v[106:107], v[98:99] op_sel_hi:[1,0,1]
	s_cmpk_lg_i32 s0, 0x80
	s_mov_b64 s[6:7], -1
	s_cbranch_scc0 .LBB0_543
	v_lshlrev_b32_e32 v3, 1, v15
	s_and_b64 s[0:1], s[26:27], s[8:9]
	v_and_b32_e32 v4, 0x780, v3
	v_mov_b32_e32 v5, v161
	v_cndmask_b32_e64 v3, 0, 1, s[0:1]
	v_cmp_ne_u32_e64 s[6:7], 1, v3
	s_andn2_b64 vcc, exec, s[0:1]
	v_lshl_add_u64 v[112:113], v[130:131], 0, v[4:5]
	s_cbranch_vccnz .LBB0_532
	v_lshlrev_b32_e32 v3, 7, v181
	global_load_dwordx4 v[64:67], v[112:113], off
	global_load_dwordx4 v[68:71], v[112:113], off offset:16
	v_mov_b32_e32 v5, v161
	v_and_b32_e32 v4, 0x780, v3
	v_lshl_add_u64 v[4:5], v[130:131], 0, v[4:5]
	global_load_dwordx4 v[72:75], v[4:5], off
	global_load_dwordx4 v[76:79], v[4:5], off offset:16
	v_mov_b32_e32 v4, v136
	v_mov_b32_e32 v5, v9
	v_mov_b32_e32 v80, v8
	v_mov_b32_e32 v81, v137
	v_mov_b32_e32 v82, v142
	v_mov_b32_e32 v83, v17
	v_mov_b32_e32 v84, v16
	v_mov_b32_e32 v85, v143
	s_waitcnt vmcnt(3)
	v_mov_b32_e32 v86, v65
	v_mov_b32_e32 v87, v66
	v_mov_b32_e32 v88, v64
	v_mov_b32_e32 v89, v67
	v_mov_b32_e32 v90, v65
	v_mov_b32_e32 v91, v67
	v_mov_b32_e32 v65, v66
	s_waitcnt vmcnt(2)
	v_mul_f32_e32 v66, v10, v68
	v_mul_f32_e32 v92, v14, v69
	v_mul_f32_e32 v94, v14, v68
	v_mul_f32_e32 v96, v10, v69
	v_pk_mul_f32 v[68:69], v[138:139], v[70:71]
	v_pk_mul_f32 v[88:89], v[136:137], v[88:89]
	v_pk_mul_f32 v[4:5], v[4:5], v[90:91]
	v_mov_b32_e32 v67, v68
	v_mov_b32_e32 v93, v69
	v_pk_mul_f32 v[70:71], v[138:139], v[70:71] op_sel:[1,0] op_sel_hi:[0,1]
	v_pk_fma_f32 v[64:65], v[80:81], v[64:65], v[4:5] neg_lo:[0,0,1] neg_hi:[0,0,1]
	v_pk_add_f32 v[66:67], v[66:67], v[92:93] neg_lo:[0,1] neg_hi:[0,1]
	v_pk_fma_f32 v[68:69], v[8:9], v[86:87], v[88:89]
	s_waitcnt vmcnt(1)
	v_mov_b32_e32 v4, v73
	v_mov_b32_e32 v5, v74
	v_mov_b32_e32 v80, v72
	v_mov_b32_e32 v81, v75
	v_mov_b32_e32 v86, v73
	v_mov_b32_e32 v87, v75
	v_mov_b32_e32 v73, v74
	s_waitcnt vmcnt(0)
	v_mul_f32_e32 v74, v18, v76
	v_mul_f32_e32 v88, v22, v77
	v_mul_f32_e32 v90, v22, v76
	v_mul_f32_e32 v92, v18, v77
	v_pk_mul_f32 v[76:77], v[12:13], v[78:79]
	v_pk_mul_f32 v[78:79], v[12:13], v[78:79] op_sel:[1,0] op_sel_hi:[0,1]
	v_mov_b32_e32 v95, v70
	v_mov_b32_e32 v97, v71
	v_pk_mul_f32 v[80:81], v[142:143], v[80:81]
	v_pk_mul_f32 v[82:83], v[82:83], v[86:87]
	v_mov_b32_e32 v75, v76
	v_mov_b32_e32 v89, v77
	v_mov_b32_e32 v91, v78
	v_mov_b32_e32 v93, v79
	v_pk_add_f32 v[70:71], v[94:95], v[96:97]
	v_pk_fma_f32 v[72:73], v[84:85], v[72:73], v[82:83] neg_lo:[0,0,1] neg_hi:[0,0,1]
	v_pk_add_f32 v[74:75], v[74:75], v[88:89] neg_lo:[0,1] neg_hi:[0,1]
	v_pk_fma_f32 v[76:77], v[16:17], v[4:5], v[80:81]
	v_pk_add_f32 v[78:79], v[90:91], v[92:93]
	s_branch .LBB0_533

.LBB0_676:
	s_add_i32 s33, s42, 2
	s_setprio 1
	ds_read_b128 v[126:129], v119 offset:32768
	ds_read_b128 v[134:137], v119 offset:34816
	ds_read_b128 v[130:133], v118
	ds_read_b128 v[138:141], v118 offset:2048
	ds_read_b128 v[162:165], v118 offset:4096
	ds_read_b128 v[166:169], v118 offset:6144
	s_waitcnt lgkmcnt(3)
	v_mfma_f32_16x16x32_bf16 v[64:67], v[126:129], v[130:133], v[64:67]
	ds_read_b128 v[170:173], v119 offset:36864
	v_mfma_f32_16x16x32_bf16 v[40:43], v[134:137], v[130:133], v[40:43]
	ds_read_b128 v[174:177], v119 offset:38912
	s_waitcnt lgkmcnt(1)
	v_mfma_f32_16x16x32_bf16 v[28:31], v[170:173], v[130:133], v[28:31]
	s_waitcnt lgkmcnt(0)
	v_mfma_f32_16x16x32_bf16 v[12:15], v[174:177], v[130:133], v[12:15]
	s_add_u32 m0, s44, 0x4000
	s_nop 0
	global_load_lds_dwordx4 v68, s[98:99]
	ds_read_b128 v[178:181], v120
	v_mfma_f32_16x16x32_bf16 v[60:63], v[126:129], v[138:141], v[60:63]
	v_mfma_f32_16x16x32_bf16 v[44:47], v[134:137], v[138:141], v[44:47]
	s_add_u32 m0, s44, 0x5000
	s_nop 0
	global_load_lds_dwordx4 v69, s[98:99]
	ds_read_b128 v[186:189], v120 offset:2048
	v_mfma_f32_16x16x32_bf16 v[24:27], v[170:173], v[138:141], v[24:27]
	v_mfma_f32_16x16x32_bf16 v[8:11], v[174:177], v[138:141], v[8:11]
	s_add_u32 m0, s44, 0x6000
	s_nop 0
	global_load_lds_dwordx4 v70, s[98:99]
	ds_read_b128 v[190:193], v120 offset:4096
	v_mfma_f32_16x16x32_bf16 v[52:55], v[126:129], v[162:165], v[52:55]
	v_mfma_f32_16x16x32_bf16 v[36:39], v[134:137], v[162:165], v[36:39]
	s_add_u32 m0, s44, 0x7000
	s_nop 0
	global_load_lds_dwordx4 v71, s[98:99]
	ds_read_b128 v[198:201], v120 offset:6144
	v_mfma_f32_16x16x32_bf16 v[20:23], v[170:173], v[162:165], v[20:23]
	v_mfma_f32_16x16x32_bf16 v[4:7], v[174:177], v[162:165], v[4:7]
	s_add_u32 m0, s44, 0xc000
	s_nop 0
	global_load_lds_dwordx4 v68, s[100:101]
	ds_read_b128 v[202:205], v121 offset:32768
	v_mfma_f32_16x16x32_bf16 v[48:51], v[126:129], v[166:169], v[48:51]
	v_mfma_f32_16x16x32_bf16 v[32:35], v[134:137], v[166:169], v[32:35]
	s_add_u32 m0, s44, 0xd000
	s_nop 0
	global_load_lds_dwordx4 v69, s[100:101]
	ds_read_b128 v[134:137], v121 offset:34816
	v_mfma_f32_16x16x32_bf16 v[16:19], v[170:173], v[166:169], v[16:19]
	v_mfma_f32_16x16x32_bf16 v[0:3], v[174:177], v[166:169], v[0:3]
	s_add_u32 m0, s44, 0xe000
	s_nop 0
	global_load_lds_dwordx4 v70, s[100:101]
	ds_read_b128 v[170:173], v121 offset:36864
	s_waitcnt lgkmcnt(2)
	v_mfma_f32_16x16x32_bf16 v[64:67], v[202:205], v[178:181], v[64:67]
	s_waitcnt lgkmcnt(1)
	v_mfma_f32_16x16x32_bf16 v[40:43], v[134:137], v[178:181], v[40:43]
	s_add_u32 m0, s44, 0xf000
	s_nop 0
	global_load_lds_dwordx4 v71, s[100:101]
	s_add_u32 s98, s98, 0x80
	s_addc_u32 s99, s99, 0
	s_add_u32 s100, s100, 0x80
	s_addc_u32 s101, s101, 0
	ds_read_b128 v[206:209], v121 offset:38912
	s_waitcnt lgkmcnt(1)
	v_mfma_f32_16x16x32_bf16 v[28:31], v[170:173], v[178:181], v[28:31]
	s_waitcnt lgkmcnt(0)
	v_mfma_f32_16x16x32_bf16 v[12:15], v[206:209], v[178:181], v[12:15]
	v_mfma_f32_16x16x32_bf16 v[60:63], v[202:205], v[186:189], v[60:63]
	v_mfma_f32_16x16x32_bf16 v[44:47], v[134:137], v[186:189], v[44:47]
	v_mfma_f32_16x16x32_bf16 v[24:27], v[170:173], v[186:189], v[24:27]
	v_mfma_f32_16x16x32_bf16 v[8:11], v[206:209], v[186:189], v[8:11]
	v_mfma_f32_16x16x32_bf16 v[52:55], v[202:205], v[190:193], v[52:55]
	v_mfma_f32_16x16x32_bf16 v[36:39], v[134:137], v[190:193], v[36:39]
	v_mfma_f32_16x16x32_bf16 v[20:23], v[170:173], v[190:193], v[20:23]
	v_mfma_f32_16x16x32_bf16 v[4:7], v[206:209], v[190:193], v[4:7]
	v_mfma_f32_16x16x32_bf16 v[48:51], v[202:205], v[198:201], v[48:51]
	v_mfma_f32_16x16x32_bf16 v[32:35], v[134:137], v[198:201], v[32:35]
	v_mfma_f32_16x16x32_bf16 v[16:19], v[170:173], v[198:201], v[16:19]
	v_mfma_f32_16x16x32_bf16 v[0:3], v[206:209], v[198:201], v[0:3]
	s_setprio 0
	s_waitcnt vmcnt(0) lgkmcnt(0)
	s_barrier
	s_setprio 1
	ds_read_b128 v[84:87], v119 offset:49152
	ds_read_b128 v[88:91], v119 offset:51200
	ds_read_b128 v[56:59], v118 offset:16384
	ds_read_b128 v[72:75], v118 offset:18432
	ds_read_b128 v[76:79], v118 offset:20480
	ds_read_b128 v[92:95], v118 offset:22528
	s_waitcnt lgkmcnt(3)
	v_mfma_f32_16x16x32_bf16 v[64:67], v[84:87], v[56:59], v[64:67]
	ds_read_b128 v[134:137], v119 offset:53248
	v_mfma_f32_16x16x32_bf16 v[40:43], v[88:91], v[56:59], v[40:43]
	ds_read_b128 v[170:173], v119 offset:55296
	s_waitcnt lgkmcnt(1)
	v_mfma_f32_16x16x32_bf16 v[28:31], v[134:137], v[56:59], v[28:31]
	s_waitcnt lgkmcnt(0)
	v_mfma_f32_16x16x32_bf16 v[12:15], v[170:173], v[56:59], v[12:15]
	s_add_u32 m0, s44, 0x0
	s_nop 0
	global_load_lds_dwordx4 v68, s[98:99]
	ds_read_b128 v[178:181], v120 offset:16384
	v_mfma_f32_16x16x32_bf16 v[60:63], v[84:87], v[72:75], v[60:63]
	v_mfma_f32_16x16x32_bf16 v[44:47], v[88:91], v[72:75], v[44:47]
	s_add_u32 m0, s44, 0x1000
	s_nop 0
	global_load_lds_dwordx4 v69, s[98:99]
	ds_read_b128 v[186:189], v120 offset:18432
	v_mfma_f32_16x16x32_bf16 v[24:27], v[134:137], v[72:75], v[24:27]
	v_mfma_f32_16x16x32_bf16 v[8:11], v[170:173], v[72:75], v[8:11]
	s_add_u32 m0, s44, 0x2000
	s_nop 0
	global_load_lds_dwordx4 v70, s[98:99]
	ds_read_b128 v[190:193], v120 offset:20480
	v_mfma_f32_16x16x32_bf16 v[52:55], v[84:87], v[76:79], v[52:55]
	v_mfma_f32_16x16x32_bf16 v[36:39], v[88:91], v[76:79], v[36:39]
	s_add_u32 m0, s44, 0x3000
	s_nop 0
	global_load_lds_dwordx4 v71, s[98:99]
	ds_read_b128 v[198:201], v120 offset:22528
	v_mfma_f32_16x16x32_bf16 v[20:23], v[134:137], v[76:79], v[20:23]
	v_mfma_f32_16x16x32_bf16 v[4:7], v[170:173], v[76:79], v[4:7]
	s_add_u32 m0, s44, 0x8000
	s_nop 0
	global_load_lds_dwordx4 v68, s[100:101]
	ds_read_b128 v[202:205], v121 offset:49152
	v_mfma_f32_16x16x32_bf16 v[48:51], v[84:87], v[92:95], v[48:51]
	v_mfma_f32_16x16x32_bf16 v[32:35], v[88:91], v[92:95], v[32:35]
	s_add_u32 m0, s44, 0x9000
	s_nop 0
	global_load_lds_dwordx4 v69, s[100:101]
	ds_read_b128 v[206:209], v121 offset:51200
	v_mfma_f32_16x16x32_bf16 v[16:19], v[134:137], v[92:95], v[16:19]
	v_mfma_f32_16x16x32_bf16 v[0:3], v[170:173], v[92:95], v[0:3]
	s_add_u32 m0, s44, 0xa000
	s_nop 0
	global_load_lds_dwordx4 v70, s[100:101]
	ds_read_b128 v[134:137], v121 offset:53248
	s_waitcnt lgkmcnt(2)
	v_mfma_f32_16x16x32_bf16 v[64:67], v[202:205], v[178:181], v[64:67]
	s_waitcnt lgkmcnt(1)
	v_mfma_f32_16x16x32_bf16 v[40:43], v[206:209], v[178:181], v[40:43]
	s_add_u32 m0, s44, 0xb000
	s_nop 0
	global_load_lds_dwordx4 v71, s[100:101]
	s_add_u32 s98, s98, 0x80
	s_addc_u32 s99, s99, 0
	s_add_u32 s100, s100, 0x80
	s_addc_u32 s101, s101, 0
	ds_read_b128 v[170:173], v121 offset:55296
	s_waitcnt lgkmcnt(1)
	v_mfma_f32_16x16x32_bf16 v[28:31], v[134:137], v[178:181], v[28:31]
	s_waitcnt lgkmcnt(0)
	v_mfma_f32_16x16x32_bf16 v[12:15], v[170:173], v[178:181], v[12:15]
	v_mfma_f32_16x16x32_bf16 v[60:63], v[202:205], v[186:189], v[60:63]
	v_mfma_f32_16x16x32_bf16 v[44:47], v[206:209], v[186:189], v[44:47]
	v_mfma_f32_16x16x32_bf16 v[24:27], v[134:137], v[186:189], v[24:27]
	v_mfma_f32_16x16x32_bf16 v[8:11], v[170:173], v[186:189], v[8:11]
	v_mfma_f32_16x16x32_bf16 v[52:55], v[202:205], v[190:193], v[52:55]
	v_mfma_f32_16x16x32_bf16 v[36:39], v[206:209], v[190:193], v[36:39]
	v_mfma_f32_16x16x32_bf16 v[20:23], v[134:137], v[190:193], v[20:23]
	v_mfma_f32_16x16x32_bf16 v[4:7], v[170:173], v[190:193], v[4:7]
	v_mfma_f32_16x16x32_bf16 v[48:51], v[202:205], v[198:201], v[48:51]
	v_mfma_f32_16x16x32_bf16 v[32:35], v[206:209], v[198:201], v[32:35]
	v_mfma_f32_16x16x32_bf16 v[16:19], v[134:137], v[198:201], v[16:19]
	v_mfma_f32_16x16x32_bf16 v[0:3], v[170:173], v[198:201], v[0:3]
	s_setprio 0
	s_mov_b32 s42, s33
	s_waitcnt vmcnt(0) lgkmcnt(0)
	s_barrier
	s_cmp_lt_u32 s42, 16
	s_cbranch_scc1 .LBB0_676
	s_mov_b32 s98, 0
	s_waitcnt vmcnt(1)
	v_add_u32_e32 v88, s1, v122
	s_addk_i32 s1, 0xf000
	s_ashr_i32 s1, s1, 10
	s_add_i32 s1, s1, 1
	s_and_b64 s[42:43], s[22:23], exec
	s_cselect_b32 s1, 0, s1
	s_mul_i32 s2, s1, 0x3000
	s_add_i32 s28, s1, 5
	s_add_i32 s33, s2, 0xf000
	s_mul_hi_u32 s28, s28, 0x3000
	s_add_u32 s33, s4, s33
	s_addc_u32 s28, s5, s28
	s_add_u32 s44, s33, 0x2000
	s_addc_u32 s45, s28, 0
	s_add_i32 s1, s1, 10
	s_add_i32 s2, s2, 0x1e000
	s_mul_hi_u32 s1, s1, 0x3000
	s_add_u32 s2, s4, s2
	s_addc_u32 s1, s5, s1
	s_add_u32 s42, s2, 0x1000
	v_or_b32_e32 v96, s0, v123
	v_lshlrev_b64 v[72:73], 2, v[96:97]
	s_addc_u32 s43, s1, 0
	v_lshl_add_u64 v[56:57], s[44:45], 0, v[72:73]
	v_lshl_add_u64 v[70:71], s[12:13], 0, v[72:73]
	v_lshlrev_b32_e32 v58, 12, v88
	v_mov_b32_e32 v59, v97
	v_lshl_add_u64 v[74:75], s[42:43], 0, v[72:73]
	v_lshl_add_u64 v[68:69], v[70:71], 0, v[58:59]
	global_load_dwordx4 v[90:93], v[56:57], off
	s_nop 0
	global_load_dwordx4 v[56:59], v[68:69], off
	global_load_dwordx4 v[78:81], v[74:75], off
	v_lshl_add_u64 v[72:73], s[14:15], 0, v[72:73]
	global_load_dwordx4 v[82:85], v[72:73], off
	v_mov_b32_e32 v75, v97
	v_lshlrev_b32_e32 v74, 1, v96
	v_lshlrev_b32_e32 v89, 10, v88
	v_mov_b32_e32 v87, v97
	v_lshlrev_b32_e32 v86, 11, v88
	s_waitcnt vmcnt(4)
	v_lshl_add_u64 v[94:95], s[24:25], 0, v[74:75]
	v_or_b32_e32 v104, 0x4000, v89
	v_mov_b32_e32 v77, v97
	v_lshl_add_u64 v[74:75], v[94:95], 0, v[86:87]
	v_lshlrev_b32_e32 v76, 2, v104
	v_lshl_add_u64 v[98:99], v[70:71], 0, v[76:77]
	v_mov_b32_e32 v107, v97
	v_or_b32_e32 v106, 16, v96
	v_lshl_add_u64 v[86:87], s[24:25], 0, v[86:87]
	s_waitcnt vmcnt(2)
	v_pk_fma_f32 v[64:65], v[64:65], v[90:91], v[56:57]
	v_pk_fma_f32 v[66:67], v[66:67], v[92:93], v[58:59]
	s_waitcnt vmcnt(1)
	v_pk_add_f32 v[56:57], v[78:79], 1.0 op_sel_hi:[1,0]
	v_pk_add_f32 v[58:59], v[80:81], 1.0 op_sel_hi:[1,0]
	s_waitcnt vmcnt(0)
	v_pk_mul_f32 v[100:101], v[82:83], v[56:57]
	v_pk_mul_f32 v[102:103], v[84:85], v[58:59]
	v_pk_mul_f32 v[56:57], v[100:101], v[64:65]
	v_pk_mul_f32 v[58:59], v[102:103], v[66:67]
	v_cvt_pk_bf16_f32 v56, v56, v57
	v_cvt_pk_bf16_f32 v57, v58, v59
	global_store_dwordx4 v[68:69], v[64:67], off
	global_store_dwordx2 v[74:75], v[56:57], off
	global_load_dwordx4 v[56:59], v[98:99], off
	v_mov_b32_e32 v79, v97
	v_or_b32_e32 v82, 0x8000, v89
	v_lshlrev_b32_e32 v78, 1, v104
	v_mov_b32_e32 v81, v97
	v_lshlrev_b32_e32 v80, 2, v82
	v_lshl_add_u64 v[74:75], v[94:95], 0, v[78:79]
	v_lshl_add_u64 v[104:105], v[70:71], 0, v[80:81]
	v_mov_b32_e32 v83, v97
	v_or_b32_e32 v89, 0xc000, v89
	v_lshlrev_b32_e32 v82, 1, v82
	v_mov_b32_e32 v85, v97
	v_lshlrev_b32_e32 v84, 2, v89
	v_pk_mul_f32 v[64:65], v[64:65], v[64:65]
	v_pk_mul_f32 v[66:67], v[66:67], v[66:67]
	v_add_f32_e32 v64, v64, v65
	v_add_f32_e32 v64, v66, v64
	v_add_f32_e32 v64, v67, v64
	s_waitcnt vmcnt(0)
	v_pk_fma_f32 v[56:57], v[60:61], v[90:91], v[56:57]
	v_pk_fma_f32 v[58:59], v[62:63], v[92:93], v[58:59]
	v_pk_mul_f32 v[60:61], v[100:101], v[56:57]
	v_pk_mul_f32 v[62:63], v[102:103], v[58:59]
	v_cvt_pk_bf16_f32 v60, v60, v61
	v_cvt_pk_bf16_f32 v61, v62, v63
	global_store_dwordx4 v[98:99], v[56:59], off
	global_store_dwordx2 v[74:75], v[60:61], off
	global_load_dwordx4 v[60:63], v[104:105], off
	v_lshl_add_u64 v[74:75], v[94:95], 0, v[82:83]
	v_lshl_add_u64 v[98:99], v[70:71], 0, v[84:85]
	s_waitcnt vmcnt(0)
	v_pk_fma_f32 v[52:53], v[52:53], v[90:91], v[60:61]
	v_pk_fma_f32 v[54:55], v[54:55], v[92:93], v[62:63]
	v_pk_mul_f32 v[60:61], v[100:101], v[52:53]
	v_pk_mul_f32 v[62:63], v[102:103], v[54:55]
	v_cvt_pk_bf16_f32 v60, v60, v61
	v_cvt_pk_bf16_f32 v61, v62, v63
	global_store_dwordx4 v[104:105], v[52:55], off
	global_store_dwordx2 v[74:75], v[60:61], off
	global_load_dwordx4 v[60:63], v[98:99], off
	v_mov_b32_e32 v75, v97
	v_lshlrev_b32_e32 v74, 1, v89
	v_lshlrev_b64 v[104:105], 2, v[106:107]
	v_lshl_add_u64 v[94:95], v[94:95], 0, v[74:75]
	v_lshl_add_u64 v[108:109], s[44:45], 0, v[104:105]
	s_waitcnt vmcnt(0)
	v_pk_fma_f32 v[48:49], v[48:49], v[90:91], v[60:61]
	v_pk_fma_f32 v[50:51], v[50:51], v[92:93], v[62:63]
	v_pk_mul_f32 v[60:61], v[100:101], v[48:49]
	v_pk_mul_f32 v[62:63], v[102:103], v[50:51]
	v_cvt_pk_bf16_f32 v60, v60, v61
	v_cvt_pk_bf16_f32 v61, v62, v63
	global_store_dwordx4 v[98:99], v[48:51], off
	global_store_dwordx2 v[94:95], v[60:61], off
	global_load_dwordx4 v[90:93], v[108:109], off
	s_nop 0
	global_load_dwordx4 v[60:63], v[68:69], off offset:64
	v_lshl_add_u64 v[94:95], s[42:43], 0, v[104:105]
	global_load_dwordx4 v[98:101], v[94:95], off
	global_load_dwordx4 v[102:105], v[72:73], off offset:64
	v_mov_b32_e32 v95, v97
	v_lshlrev_b32_e32 v94, 1, v106
	v_lshl_add_u64 v[106:107], v[70:71], 0, 64
	v_lshl_add_u64 v[108:109], v[86:87], 0, v[94:95]
	v_lshl_add_u64 v[110:111], v[106:107], 0, v[76:77]
	v_lshl_add_u64 v[94:95], s[24:25], 0, v[94:95]
	s_waitcnt vmcnt(2)
	v_pk_fma_f32 v[60:61], v[40:41], v[90:91], v[60:61]
	v_pk_fma_f32 v[62:63], v[42:43], v[92:93], v[62:63]
	s_waitcnt vmcnt(1)
	v_pk_add_f32 v[40:41], v[98:99], 1.0 op_sel_hi:[1,0]
	v_pk_add_f32 v[42:43], v[100:101], 1.0 op_sel_hi:[1,0]
	s_waitcnt vmcnt(0)
	v_pk_mul_f32 v[98:99], v[102:103], v[40:41]
	v_pk_mul_f32 v[100:101], v[104:105], v[42:43]
	v_pk_mul_f32 v[40:41], v[98:99], v[60:61]
	v_pk_mul_f32 v[42:43], v[100:101], v[62:63]
	v_cvt_pk_bf16_f32 v40, v40, v41
	v_cvt_pk_bf16_f32 v41, v42, v43
	global_store_dwordx4 v[68:69], v[60:63], off offset:64
	global_store_dwordx2 v[108:109], v[40:41], off
	global_load_dwordx4 v[40:43], v[110:111], off
	v_lshl_add_u64 v[102:103], v[94:95], 0, v[78:79]
	v_lshl_add_u64 v[104:105], v[106:107], 0, v[80:81]
	v_lshl_add_u64 v[106:107], v[106:107], 0, v[84:85]
	v_mov_b32_e32 v109, v97
	v_or_b32_e32 v108, 32, v96
	v_or_b32_e32 v96, 48, v96
	v_pk_mul_f32 v[60:61], v[60:61], v[60:61]
	v_pk_mul_f32 v[62:63], v[62:63], v[62:63]
	v_add_f32_e32 v60, v60, v61
	v_add_f32_e32 v60, v62, v60
	v_add_f32_e32 v60, v63, v60
	v_add_f32_e32 v60, v64, v60
	s_waitcnt vmcnt(0)
	v_pk_fma_f32 v[40:41], v[44:45], v[90:91], v[40:41]
	v_pk_fma_f32 v[42:43], v[46:47], v[92:93], v[42:43]
	v_pk_mul_f32 v[44:45], v[98:99], v[40:41]
	v_pk_mul_f32 v[46:47], v[100:101], v[42:43]
	v_cvt_pk_bf16_f32 v44, v44, v45
	v_cvt_pk_bf16_f32 v45, v46, v47
	global_store_dwordx4 v[110:111], v[40:43], off
	global_store_dwordx2 v[102:103], v[44:45], off
	global_load_dwordx4 v[44:47], v[104:105], off
	v_lshl_add_u64 v[102:103], v[94:95], 0, v[82:83]
	v_lshl_add_u64 v[94:95], v[94:95], 0, v[74:75]
	s_waitcnt vmcnt(0)
	v_pk_fma_f32 v[36:37], v[36:37], v[90:91], v[44:45]
	v_pk_fma_f32 v[38:39], v[38:39], v[92:93], v[46:47]
	v_pk_mul_f32 v[44:45], v[98:99], v[36:37]
	v_pk_mul_f32 v[46:47], v[100:101], v[38:39]
	v_cvt_pk_bf16_f32 v44, v44, v45
	v_cvt_pk_bf16_f32 v45, v46, v47
	global_store_dwordx4 v[104:105], v[36:39], off
	global_store_dwordx2 v[102:103], v[44:45], off
	global_load_dwordx4 v[44:47], v[106:107], off
	v_lshlrev_b64 v[102:103], 2, v[108:109]
	v_lshl_add_u64 v[104:105], s[44:45], 0, v[102:103]
	s_waitcnt vmcnt(0)
	v_pk_fma_f32 v[32:33], v[32:33], v[90:91], v[44:45]
	v_pk_fma_f32 v[34:35], v[34:35], v[92:93], v[46:47]
	v_pk_mul_f32 v[44:45], v[98:99], v[32:33]
	v_pk_mul_f32 v[46:47], v[100:101], v[34:35]
	v_cvt_pk_bf16_f32 v44, v44, v45
	v_cvt_pk_bf16_f32 v45, v46, v47
	global_store_dwordx4 v[106:107], v[32:35], off
	global_store_dwordx2 v[94:95], v[44:45], off
	global_load_dwordx4 v[44:47], v[104:105], off
	s_nop 0
	global_load_dwordx4 v[90:93], v[68:69], off offset:128
	v_lshl_add_u64 v[94:95], s[42:43], 0, v[102:103]
	global_load_dwordx4 v[98:101], v[94:95], off
	global_load_dwordx4 v[102:105], v[72:73], off offset:128
	v_mov_b32_e32 v95, v97
	v_lshlrev_b32_e32 v94, 1, v108
	v_lshl_add_u64 v[106:107], v[70:71], 0, s[38:39]
	v_lshl_add_u64 v[108:109], v[86:87], 0, v[94:95]
	v_lshl_add_u64 v[110:111], v[106:107], 0, v[76:77]
	v_lshl_add_u64 v[94:95], s[24:25], 0, v[94:95]
	s_waitcnt vmcnt(2)
	v_pk_fma_f32 v[28:29], v[28:29], v[44:45], v[90:91]
	v_pk_fma_f32 v[30:31], v[30:31], v[46:47], v[92:93]
	s_waitcnt vmcnt(1)
	v_pk_add_f32 v[90:91], v[98:99], 1.0 op_sel_hi:[1,0]
	v_pk_add_f32 v[92:93], v[100:101], 1.0 op_sel_hi:[1,0]
	s_waitcnt vmcnt(0)
	v_pk_mul_f32 v[98:99], v[102:103], v[90:91]
	v_pk_mul_f32 v[100:101], v[104:105], v[92:93]
	v_pk_mul_f32 v[90:91], v[98:99], v[28:29]
	v_pk_mul_f32 v[92:93], v[100:101], v[30:31]
	v_cvt_pk_bf16_f32 v90, v90, v91
	v_cvt_pk_bf16_f32 v91, v92, v93
	global_store_dwordx4 v[68:69], v[28:31], off offset:128
	global_store_dwordx2 v[108:109], v[90:91], off
	global_load_dwordx4 v[90:93], v[110:111], off
	v_lshl_add_u64 v[102:103], v[94:95], 0, v[78:79]
	v_lshl_add_u64 v[104:105], v[106:107], 0, v[80:81]
	v_lshl_add_u64 v[106:107], v[106:107], 0, v[84:85]
	v_pk_mul_f32 v[28:29], v[28:29], v[28:29]
	v_pk_mul_f32 v[30:31], v[30:31], v[30:31]
	v_add_f32_e32 v28, v28, v29
	v_add_f32_e32 v28, v30, v28
	v_add_f32_e32 v28, v31, v28
	v_add_f32_e32 v28, v60, v28
	s_waitcnt vmcnt(0)
	v_pk_fma_f32 v[24:25], v[24:25], v[44:45], v[90:91]
	v_pk_fma_f32 v[26:27], v[26:27], v[46:47], v[92:93]
	v_pk_mul_f32 v[90:91], v[98:99], v[24:25]
	v_pk_mul_f32 v[92:93], v[100:101], v[26:27]
	v_cvt_pk_bf16_f32 v90, v90, v91
	v_cvt_pk_bf16_f32 v91, v92, v93
	global_store_dwordx4 v[110:111], v[24:27], off
	global_store_dwordx2 v[102:103], v[90:91], off
	global_load_dwordx4 v[90:93], v[104:105], off
	v_lshl_add_u64 v[102:103], v[94:95], 0, v[82:83]
	v_lshl_add_u64 v[94:95], v[94:95], 0, v[74:75]
	s_waitcnt vmcnt(0)
	v_pk_fma_f32 v[20:21], v[20:21], v[44:45], v[90:91]
	v_pk_fma_f32 v[22:23], v[22:23], v[46:47], v[92:93]
	v_pk_mul_f32 v[90:91], v[98:99], v[20:21]
	v_pk_mul_f32 v[92:93], v[100:101], v[22:23]
	v_cvt_pk_bf16_f32 v90, v90, v91
	v_cvt_pk_bf16_f32 v91, v92, v93
	global_store_dwordx4 v[104:105], v[20:23], off
	global_store_dwordx2 v[102:103], v[90:91], off
	global_load_dwordx4 v[90:93], v[106:107], off
	v_lshlrev_b64 v[102:103], 2, v[96:97]
	v_lshl_add_u64 v[104:105], s[44:45], 0, v[102:103]
	v_lshlrev_b32_e32 v96, 1, v96
	s_waitcnt vmcnt(0)
	v_pk_fma_f32 v[16:17], v[16:17], v[44:45], v[90:91]
	v_pk_fma_f32 v[18:19], v[18:19], v[46:47], v[92:93]
	v_pk_mul_f32 v[44:45], v[98:99], v[16:17]
	v_pk_mul_f32 v[46:47], v[100:101], v[18:19]
	v_cvt_pk_bf16_f32 v44, v44, v45
	v_cvt_pk_bf16_f32 v45, v46, v47
	global_store_dwordx4 v[106:107], v[16:19], off
	global_store_dwordx2 v[94:95], v[44:45], off
	global_load_dwordx4 v[44:47], v[104:105], off
	s_nop 0
	global_load_dwordx4 v[90:93], v[68:69], off offset:192
	v_lshl_add_u64 v[94:95], s[42:43], 0, v[102:103]
	global_load_dwordx4 v[98:101], v[94:95], off
	global_load_dwordx4 v[102:105], v[72:73], off offset:192
	v_lshl_add_u64 v[72:73], v[70:71], 0, s[40:41]
	v_lshl_add_u64 v[70:71], v[86:87], 0, v[96:97]
	v_lshl_add_u64 v[76:77], v[72:73], 0, v[76:77]
	v_lshl_add_u64 v[80:81], v[72:73], 0, v[80:81]
	v_lshl_add_u64 v[72:73], v[72:73], 0, v[84:85]
	s_waitcnt vmcnt(2)
	v_pk_fma_f32 v[12:13], v[12:13], v[44:45], v[90:91]
	s_waitcnt vmcnt(1)
	v_pk_add_f32 v[86:87], v[98:99], 1.0 op_sel_hi:[1,0]
	v_pk_add_f32 v[90:91], v[100:101], 1.0 op_sel_hi:[1,0]
	v_pk_fma_f32 v[14:15], v[14:15], v[46:47], v[92:93]
	s_waitcnt vmcnt(0)
	v_pk_mul_f32 v[86:87], v[102:103], v[86:87]
	v_pk_mul_f32 v[90:91], v[104:105], v[90:91]
	global_store_dwordx4 v[68:69], v[12:15], off offset:192
	v_pk_mul_f32 v[68:69], v[86:87], v[12:13]
	v_pk_mul_f32 v[92:93], v[90:91], v[14:15]
	v_cvt_pk_bf16_f32 v68, v68, v69
	v_cvt_pk_bf16_f32 v69, v92, v93
	global_store_dwordx2 v[70:71], v[68:69], off
	global_load_dwordx4 v[68:71], v[76:77], off
	v_lshl_add_u64 v[92:93], s[24:25], 0, v[96:97]
	v_lshl_add_u64 v[78:79], v[92:93], 0, v[78:79]
	v_pk_mul_f32 v[12:13], v[12:13], v[12:13]
	v_pk_mul_f32 v[14:15], v[14:15], v[14:15]
	v_add_f32_e32 v12, v12, v13
	v_add_f32_e32 v12, v14, v12
	v_add_f32_e32 v12, v15, v12
	v_add_f32_e32 v14, v28, v12
	ds_bpermute_b32 v15, v124, v14
	v_lshlrev_b32_e32 v96, 2, v88
	v_lshl_add_u64 v[12:13], v[92:93], 0, v[74:75]
	s_waitcnt lgkmcnt(0)
	v_add_f32_e32 v14, v14, v15
	ds_bpermute_b32 v15, v125, v14
	s_waitcnt vmcnt(0)
	v_pk_fma_f32 v[8:9], v[8:9], v[44:45], v[68:69]
	v_pk_fma_f32 v[10:11], v[10:11], v[46:47], v[70:71]
	v_pk_mul_f32 v[68:69], v[86:87], v[8:9]
	v_pk_mul_f32 v[70:71], v[90:91], v[10:11]
	v_cvt_pk_bf16_f32 v68, v68, v69
	v_cvt_pk_bf16_f32 v69, v70, v71
	global_store_dwordx4 v[76:77], v[8:11], off
	global_store_dwordx2 v[78:79], v[68:69], off
	global_load_dwordx4 v[68:71], v[80:81], off
	v_lshl_add_u64 v[76:77], v[92:93], 0, v[82:83]
	s_waitcnt vmcnt(0)
	v_pk_fma_f32 v[4:5], v[4:5], v[44:45], v[68:69]
	v_pk_fma_f32 v[6:7], v[6:7], v[46:47], v[70:71]
	v_pk_mul_f32 v[68:69], v[86:87], v[4:5]
	v_pk_mul_f32 v[70:71], v[90:91], v[6:7]
	v_cvt_pk_bf16_f32 v68, v68, v69
	v_cvt_pk_bf16_f32 v69, v70, v71
	global_store_dwordx4 v[80:81], v[4:7], off
	global_store_dwordx2 v[76:77], v[68:69], off
	global_load_dwordx4 v[68:71], v[72:73], off
	s_waitcnt vmcnt(0)
	v_pk_fma_f32 v[0:1], v[0:1], v[44:45], v[68:69]
	v_pk_fma_f32 v[2:3], v[2:3], v[46:47], v[70:71]
	v_pk_mul_f32 v[28:29], v[86:87], v[0:1]
	v_pk_mul_f32 v[30:31], v[90:91], v[2:3]
	v_cvt_pk_bf16_f32 v28, v28, v29
	v_cvt_pk_bf16_f32 v29, v30, v31
	global_store_dwordx4 v[72:73], v[0:3], off
	global_store_dwordx2 v[12:13], v[28:29], off
	v_lshl_add_u64 v[12:13], s[26:27], 0, v[96:97]
	s_and_saveexec_b64 s[42:43], s[10:11]
	s_cbranch_execz .LBB0_679
	s_waitcnt lgkmcnt(0)
	v_add_f32_e32 v14, v14, v15
	global_atomic_add_f32 v[12:13], v14, off

.LBB0_739:
	s_and_b32 s8, s7, 7
	s_or_b32 s8, s8, s0
	s_lshl_b32 s8, s8, 7
	v_or_b32_e32 v0, s8, v149
	v_lshl_or_b32 v96, v0, 11, v116
	s_waitcnt vmcnt(1)
	v_lshl_add_u64 v[100:101], s[18:19], 0, v[96:97]
	v_add_co_u32_e32 v2, vcc, 0x10000, v100
	s_lshl_b32 s9, s7, 4
	s_nop 0
	v_addc_co_u32_e32 v3, vcc, 0, v101, vcc
	s_and_b32 s9, s9, 0x7fffff80
	v_add_co_u32_e32 v4, vcc, 0x20000, v100
	v_or_b32_e32 v0, s9, v149
	s_nop 0
	v_addc_co_u32_e32 v5, vcc, 0, v101, vcc
	v_lshl_or_b32 v98, v0, 11, v116
	v_add_co_u32_e32 v6, vcc, 0x30000, v100
	v_mov_b32_e32 v99, v97
	s_nop 0
	v_addc_co_u32_e32 v7, vcc, 0, v101, vcc
	v_lshl_add_u64 v[102:103], s[16:17], 0, v[98:99]
	v_add_co_u32_e32 v12, vcc, s3, v102
	s_nop 0
	v_addc_co_u32_e32 v13, vcc, 0, v103, vcc
	v_add_co_u32_e32 v14, vcc, s4, v102
	s_nop 0
	v_addc_co_u32_e32 v15, vcc, 0, v103, vcc
	v_add_co_u32_e32 v48, vcc, s5, v102
	s_nop 0
	v_addc_co_u32_e32 v49, vcc, 0, v103, vcc
	s_movk_i32 s10, 0x100
	s_mov_b32 s12, s35
	v_mov_b32_e32 v8, 0
	v_mov_b32_e32 v9, v97
	v_mov_b32_e32 v10, v97
	v_mov_b32_e32 v11, v97
	v_mov_b32_e32 v0, 0
	v_mov_b32_e32 v1, v97
	v_mov_b32_e32 v2, v97
	v_mov_b32_e32 v3, v97
	v_mov_b32_e32 v12, 0
	v_mov_b32_e32 v13, v97
	v_mov_b32_e32 v14, v97
	v_mov_b32_e32 v15, v97
	v_mov_b32_e32 v4, 0
	v_mov_b32_e32 v5, v97
	v_lshl_add_u64 v[104:105], v[102:103], 0, s[26:27]
	v_lshl_add_u64 v[106:107], v[102:103], 0, s[28:29]
	v_lshl_add_u64 v[108:109], v[102:103], 0, s[30:31]
	v_lshl_add_u64 v[110:111], v[100:101], 0, s[26:27]
	v_lshl_add_u64 v[112:113], v[100:101], 0, s[28:29]
	v_lshl_add_u64 v[114:115], v[100:101], 0, s[30:31]
	s_barrier
	v_mov_b32_e32 v6, v97
	v_mov_b32_e32 v7, v97
	v_mov_b32_e32 v48, 0
	v_mov_b32_e32 v49, v97
	v_mov_b32_e32 v50, v97
	v_mov_b32_e32 v51, v97
	v_mov_b32_e32 v60, 0
	v_mov_b32_e32 v61, v97
	v_mov_b32_e32 v62, v97
	v_mov_b32_e32 v63, v97
	v_mov_b32_e32 v56, 0
	v_mov_b32_e32 v57, v97
	v_mov_b32_e32 v58, v97
	v_mov_b32_e32 v59, v97
	v_mov_b32_e32 v52, 0
	v_mov_b32_e32 v53, v97
	v_mov_b32_e32 v54, v97
	v_mov_b32_e32 v55, v97
	v_mov_b32_e32 v32, 0
	v_mov_b32_e32 v33, v97
	v_mov_b32_e32 v34, v97
	v_mov_b32_e32 v35, v97
	v_mov_b32_e32 v24, 0
	v_mov_b32_e32 v25, v97
	v_mov_b32_e32 v26, v97
	v_mov_b32_e32 v27, v97
	v_mov_b32_e32 v20, 0
	v_mov_b32_e32 v21, v97
	v_mov_b32_e32 v22, v97
	v_mov_b32_e32 v23, v97
	v_mov_b32_e32 v16, 0
	v_mov_b32_e32 v17, v97
	v_mov_b32_e32 v18, v97
	v_mov_b32_e32 v19, v97
	v_mov_b32_e32 v40, 0
	v_mov_b32_e32 v41, v97
	v_mov_b32_e32 v42, v97
	v_mov_b32_e32 v43, v97
	v_mov_b32_e32 v36, 0
	v_mov_b32_e32 v37, v97
	v_mov_b32_e32 v38, v97
	v_mov_b32_e32 v39, v97
	v_mov_b32_e32 v28, 0
	v_mov_b32_e32 v29, v97
	v_mov_b32_e32 v30, v97
	v_mov_b32_e32 v31, v97
	v_mov_b32_e32 v44, 0
	v_mov_b32_e32 v45, v97
	v_mov_b32_e32 v46, v97
	v_mov_b32_e32 v47, v97
	v_readlane_b32 s14, v253, 0
	v_readlane_b32 s15, v253, 1
	s_load_dwordx2 s[14:15], s[14:15], 0x160
	v_lshrrev_b32_e32 v71, 6, v146
	s_nop 0
	v_readfirstlane_b32 s10, v71
	v_lshrrev_b32_e32 v69, 3, v146
	v_and_b32_e32 v70, 7, v146
	v_xor_b32_e32 v70, v69, v70
	v_and_b32_e32 v70, 7, v70
	v_lshlrev_b32_e32 v70, 4, v70
	v_lshl_or_b32 v68, v69, 11, v70
	v_add_u32_e32 v69, 0x10000, v68
	v_add_u32_e32 v70, 0x20000, v68
	v_add_u32_e32 v71, 0x30000, v68
	s_and_b32 s13, s7, 7
	s_and_b32 s34, s69, 7
	s_lshl_b32 s34, s34, 3
	s_or_b32 s13, s13, s34
	s_lshl_b32 s13, s13, 18
	s_add_u32 s13, s13, 0xdc40000
	s_lshr_b32 s34, s7, 3
	s_lshl_b32 s34, s34, 18
	s_add_u32 s34, s34, 0x7f00000
	s_lshl_b32 s10, s10, 10
	s_waitcnt lgkmcnt(0)
	s_add_u32 s13, s14, s13
	s_addc_u32 m0, s15, 0
	s_add_u32 s34, s14, s34
	s_addc_u32 s15, s15, 0
	s_add_u32 s14, s13, 0x80
	s_cmp_eq_u32 s14, s98
	s_cbranch_scc0 .Lnp740_load
	s_add_u32 s14, s34, 0x80
	s_cmp_eq_u32 s14, s100
	s_cbranch_scc1 .Lnp740_have
.Lnp740_load:
	s_mov_b32 s98, s13
	s_mov_b32 s99, m0
	s_mov_b32 s100, s34
	s_mov_b32 s101, s15
	s_add_u32 m0, s10, 0x0
	s_nop 0
	global_load_lds_dwordx4 v68, s[98:99]
	s_add_u32 m0, s10, 0x1000
	s_nop 0
	global_load_lds_dwordx4 v69, s[98:99]
	s_add_u32 m0, s10, 0x2000
	s_nop 0
	global_load_lds_dwordx4 v70, s[98:99]
	s_add_u32 m0, s10, 0x3000
	s_nop 0
	global_load_lds_dwordx4 v71, s[98:99]
	s_add_u32 m0, s10, 0x8000
	s_nop 0
	global_load_lds_dwordx4 v68, s[100:101]
	s_add_u32 m0, s10, 0x9000
	s_nop 0
	global_load_lds_dwordx4 v69, s[100:101]
	s_add_u32 m0, s10, 0xa000
	s_nop 0
	global_load_lds_dwordx4 v70, s[100:101]
	s_add_u32 m0, s10, 0xb000
	s_nop 0
	global_load_lds_dwordx4 v71, s[100:101]
	s_add_u32 s98, s98, 0x80
	s_addc_u32 s99, s99, 0
	s_add_u32 s100, s100, 0x80
	s_addc_u32 s101, s101, 0
	s_waitcnt vmcnt(0)

.LBB0_740:
	s_add_i32 s11, s12, 2
	s_setprio 1
	ds_read_b128 v[124:127], v119 offset:32768
	ds_read_b128 v[132:135], v119 offset:34816
	ds_read_b128 v[128:131], v118
	ds_read_b128 v[136:139], v118 offset:2048
	ds_read_b128 v[140:143], v118 offset:4096
	ds_read_b128 v[162:165], v118 offset:6144
	s_waitcnt lgkmcnt(3)
	v_mfma_f32_16x16x32_bf16 v[8:11], v[124:127], v[128:131], v[8:11]
	ds_read_b128 v[166:169], v119 offset:36864
	v_mfma_f32_16x16x32_bf16 v[0:3], v[132:135], v[128:131], v[0:3]
	ds_read_b128 v[170:173], v119 offset:38912
	s_waitcnt lgkmcnt(1)
	v_mfma_f32_16x16x32_bf16 v[12:15], v[166:169], v[128:131], v[12:15]
	s_waitcnt lgkmcnt(0)
	v_mfma_f32_16x16x32_bf16 v[4:7], v[170:173], v[128:131], v[4:7]
	s_add_u32 m0, s10, 0x4000
	s_nop 0
	global_load_lds_dwordx4 v68, s[98:99]
	ds_read_b128 v[174:177], v120
	v_mfma_f32_16x16x32_bf16 v[32:35], v[124:127], v[136:139], v[32:35]
	v_mfma_f32_16x16x32_bf16 v[24:27], v[132:135], v[136:139], v[24:27]
	s_add_u32 m0, s10, 0x5000
	s_nop 0
	global_load_lds_dwordx4 v69, s[98:99]
	ds_read_b128 v[182:185], v120 offset:2048
	v_mfma_f32_16x16x32_bf16 v[20:23], v[166:169], v[136:139], v[20:23]
	v_mfma_f32_16x16x32_bf16 v[16:19], v[170:173], v[136:139], v[16:19]
	s_add_u32 m0, s10, 0x6000
	s_nop 0
	global_load_lds_dwordx4 v70, s[98:99]
	ds_read_b128 v[186:189], v120 offset:4096
	v_mfma_f32_16x16x32_bf16 v[48:51], v[124:127], v[140:143], v[48:51]
	v_mfma_f32_16x16x32_bf16 v[40:43], v[132:135], v[140:143], v[40:43]
	s_add_u32 m0, s10, 0x7000
	s_nop 0
	global_load_lds_dwordx4 v71, s[98:99]
	ds_read_b128 v[194:197], v120 offset:6144
	v_mfma_f32_16x16x32_bf16 v[36:39], v[166:169], v[140:143], v[36:39]
	v_mfma_f32_16x16x32_bf16 v[28:31], v[170:173], v[140:143], v[28:31]
	s_add_u32 m0, s10, 0xc000
	s_nop 0
	global_load_lds_dwordx4 v68, s[100:101]
	ds_read_b128 v[198:201], v121 offset:32768
	v_mfma_f32_16x16x32_bf16 v[60:63], v[124:127], v[162:165], v[60:63]
	v_mfma_f32_16x16x32_bf16 v[56:59], v[132:135], v[162:165], v[56:59]
	s_add_u32 m0, s10, 0xd000
	s_nop 0
	global_load_lds_dwordx4 v69, s[100:101]
	ds_read_b128 v[132:135], v121 offset:34816
	v_mfma_f32_16x16x32_bf16 v[52:55], v[166:169], v[162:165], v[52:55]
	v_mfma_f32_16x16x32_bf16 v[44:47], v[170:173], v[162:165], v[44:47]
	s_add_u32 m0, s10, 0xe000
	s_nop 0
	global_load_lds_dwordx4 v70, s[100:101]
	ds_read_b128 v[166:169], v121 offset:36864
	s_waitcnt lgkmcnt(2)
	v_mfma_f32_16x16x32_bf16 v[8:11], v[198:201], v[174:177], v[8:11]
	s_waitcnt lgkmcnt(1)
	v_mfma_f32_16x16x32_bf16 v[0:3], v[132:135], v[174:177], v[0:3]
	s_add_u32 m0, s10, 0xf000
	s_nop 0
	global_load_lds_dwordx4 v71, s[100:101]
	s_add_u32 s98, s98, 0x80
	s_addc_u32 s99, s99, 0
	s_add_u32 s100, s100, 0x80
	s_addc_u32 s101, s101, 0
	ds_read_b128 v[202:205], v121 offset:38912
	s_waitcnt lgkmcnt(1)
	v_mfma_f32_16x16x32_bf16 v[12:15], v[166:169], v[174:177], v[12:15]
	s_waitcnt lgkmcnt(0)
	v_mfma_f32_16x16x32_bf16 v[4:7], v[202:205], v[174:177], v[4:7]
	v_mfma_f32_16x16x32_bf16 v[32:35], v[198:201], v[182:185], v[32:35]
	v_mfma_f32_16x16x32_bf16 v[24:27], v[132:135], v[182:185], v[24:27]
	v_mfma_f32_16x16x32_bf16 v[20:23], v[166:169], v[182:185], v[20:23]
	v_mfma_f32_16x16x32_bf16 v[16:19], v[202:205], v[182:185], v[16:19]
	v_mfma_f32_16x16x32_bf16 v[48:51], v[198:201], v[186:189], v[48:51]
	v_mfma_f32_16x16x32_bf16 v[40:43], v[132:135], v[186:189], v[40:43]
	v_mfma_f32_16x16x32_bf16 v[36:39], v[166:169], v[186:189], v[36:39]
	v_mfma_f32_16x16x32_bf16 v[28:31], v[202:205], v[186:189], v[28:31]
	v_mfma_f32_16x16x32_bf16 v[60:63], v[198:201], v[194:197], v[60:63]
	v_mfma_f32_16x16x32_bf16 v[56:59], v[132:135], v[194:197], v[56:59]
	v_mfma_f32_16x16x32_bf16 v[52:55], v[166:169], v[194:197], v[52:55]
	v_mfma_f32_16x16x32_bf16 v[44:47], v[202:205], v[194:197], v[44:47]
	s_setprio 0
	s_waitcnt vmcnt(0) lgkmcnt(0)
	s_barrier
	s_cmp_lg_u32 s12, 14
	s_cbranch_scc1 .Lnh740_skip
	s_mov_b32 s13, 0
	s_add_i32 s34, s7, s96
	s_cmp_lt_u32 s34, 0x100
	s_cbranch_scc0 .Lnh740_skip
	s_and_b32 s15, s34, 7
	s_and_b32 m0, s7, 7
	s_sub_i32 s15, s15, m0
	s_lshl_b32 s15, s15, 18
	s_sub_i32 s15, s15, 0x800
	s_ashr_i32 m0, s15, 31
	s_add_u32 s98, s98, s15
	s_addc_u32 s99, s99, m0
	s_lshr_b32 s14, s34, 3
	s_lshr_b32 m0, s7, 3
	s_sub_i32 s14, s14, m0
	s_lshl_b32 s14, s14, 18
	s_sub_i32 s14, s14, 0x800
	s_ashr_i32 m0, s14, 31
	s_add_u32 s100, s100, s14
	s_addc_u32 s101, s101, m0
	s_mov_b32 s13, 1
.Lnh740_skip:
	s_setprio 1
	ds_read_b128 v[84:87], v119 offset:49152
	ds_read_b128 v[88:91], v119 offset:51200
	ds_read_b128 v[64:67], v118 offset:16384
	ds_read_b128 v[72:75], v118 offset:18432
	ds_read_b128 v[76:79], v118 offset:20480
	ds_read_b128 v[92:95], v118 offset:22528
	s_waitcnt lgkmcnt(3)
	v_mfma_f32_16x16x32_bf16 v[8:11], v[84:87], v[64:67], v[8:11]
	ds_read_b128 v[132:135], v119 offset:53248
	v_mfma_f32_16x16x32_bf16 v[0:3], v[88:91], v[64:67], v[0:3]
	ds_read_b128 v[166:169], v119 offset:55296
	s_waitcnt lgkmcnt(1)
	v_mfma_f32_16x16x32_bf16 v[12:15], v[132:135], v[64:67], v[12:15]
	s_waitcnt lgkmcnt(0)
	v_mfma_f32_16x16x32_bf16 v[4:7], v[166:169], v[64:67], v[4:7]
	s_add_u32 m0, s10, 0x0
	s_nop 0
	global_load_lds_dwordx4 v68, s[98:99]
	ds_read_b128 v[174:177], v120 offset:16384
	v_mfma_f32_16x16x32_bf16 v[32:35], v[84:87], v[72:75], v[32:35]
	v_mfma_f32_16x16x32_bf16 v[24:27], v[88:91], v[72:75], v[24:27]
	s_add_u32 m0, s10, 0x1000
	s_nop 0
	global_load_lds_dwordx4 v69, s[98:99]
	ds_read_b128 v[182:185], v120 offset:18432
	v_mfma_f32_16x16x32_bf16 v[20:23], v[132:135], v[72:75], v[20:23]
	v_mfma_f32_16x16x32_bf16 v[16:19], v[166:169], v[72:75], v[16:19]
	s_add_u32 m0, s10, 0x2000
	s_nop 0
	global_load_lds_dwordx4 v70, s[98:99]
	ds_read_b128 v[186:189], v120 offset:20480
	v_mfma_f32_16x16x32_bf16 v[48:51], v[84:87], v[76:79], v[48:51]
	v_mfma_f32_16x16x32_bf16 v[40:43], v[88:91], v[76:79], v[40:43]
	s_add_u32 m0, s10, 0x3000
	s_nop 0
	global_load_lds_dwordx4 v71, s[98:99]
	ds_read_b128 v[194:197], v120 offset:22528
	v_mfma_f32_16x16x32_bf16 v[36:39], v[132:135], v[76:79], v[36:39]
	v_mfma_f32_16x16x32_bf16 v[28:31], v[166:169], v[76:79], v[28:31]
	s_add_u32 m0, s10, 0x8000
	s_nop 0
	global_load_lds_dwordx4 v68, s[100:101]
	ds_read_b128 v[198:201], v121 offset:49152
	v_mfma_f32_16x16x32_bf16 v[60:63], v[84:87], v[92:95], v[60:63]
	v_mfma_f32_16x16x32_bf16 v[56:59], v[88:91], v[92:95], v[56:59]
	s_add_u32 m0, s10, 0x9000
	s_nop 0
	global_load_lds_dwordx4 v69, s[100:101]
	ds_read_b128 v[202:205], v121 offset:51200
	v_mfma_f32_16x16x32_bf16 v[52:55], v[132:135], v[92:95], v[52:55]
	v_mfma_f32_16x16x32_bf16 v[44:47], v[166:169], v[92:95], v[44:47]
	s_add_u32 m0, s10, 0xa000
	s_nop 0
	global_load_lds_dwordx4 v70, s[100:101]
	ds_read_b128 v[132:135], v121 offset:53248
	s_waitcnt lgkmcnt(2)
	v_mfma_f32_16x16x32_bf16 v[8:11], v[198:201], v[174:177], v[8:11]
	s_waitcnt lgkmcnt(1)
	v_mfma_f32_16x16x32_bf16 v[0:3], v[202:205], v[174:177], v[0:3]
	s_add_u32 m0, s10, 0xb000
	s_nop 0
	global_load_lds_dwordx4 v71, s[100:101]
	s_add_u32 s98, s98, 0x80
	s_addc_u32 s99, s99, 0
	s_add_u32 s100, s100, 0x80
	s_addc_u32 s101, s101, 0
	ds_read_b128 v[166:169], v121 offset:55296
	s_waitcnt lgkmcnt(1)
	v_mfma_f32_16x16x32_bf16 v[12:15], v[132:135], v[174:177], v[12:15]
	s_waitcnt lgkmcnt(0)
	v_mfma_f32_16x16x32_bf16 v[4:7], v[166:169], v[174:177], v[4:7]
	v_mfma_f32_16x16x32_bf16 v[32:35], v[198:201], v[182:185], v[32:35]
	v_mfma_f32_16x16x32_bf16 v[24:27], v[202:205], v[182:185], v[24:27]
	v_mfma_f32_16x16x32_bf16 v[20:23], v[132:135], v[182:185], v[20:23]
	v_mfma_f32_16x16x32_bf16 v[16:19], v[166:169], v[182:185], v[16:19]
	v_mfma_f32_16x16x32_bf16 v[48:51], v[198:201], v[186:189], v[48:51]
	v_mfma_f32_16x16x32_bf16 v[40:43], v[202:205], v[186:189], v[40:43]
	v_mfma_f32_16x16x32_bf16 v[36:39], v[132:135], v[186:189], v[36:39]
	v_mfma_f32_16x16x32_bf16 v[28:31], v[166:169], v[186:189], v[28:31]
	v_mfma_f32_16x16x32_bf16 v[60:63], v[198:201], v[194:197], v[60:63]
	v_mfma_f32_16x16x32_bf16 v[56:59], v[202:205], v[194:197], v[56:59]
	v_mfma_f32_16x16x32_bf16 v[52:55], v[132:135], v[194:197], v[52:55]
	v_mfma_f32_16x16x32_bf16 v[44:47], v[166:169], v[194:197], v[44:47]
	s_setprio 0
	s_mov_b32 s12, s11
	s_waitcnt vmcnt(0) lgkmcnt(0)
	s_barrier
	s_cmp_lt_u32 s12, 16
	s_cbranch_scc1 .LBB0_740
	s_cmp_eq_u32 s13, 1
	s_cbranch_scc1 .Lnx740_keep
	s_mov_b32 s98, 0
.Lnx740_keep:
	s_waitcnt vmcnt(4)
	v_add_u32_e32 v80, s8, v122
	s_addk_i32 s8, 0xf000
	v_lshlrev_b32_e32 v64, 2, v80
	s_ashr_i32 s8, s8, 10
	global_load_dword v84, v64, s[24:25]
	global_load_dword v85, v64, s[24:25] offset:64
	global_load_dword v86, v64, s[24:25] offset:128
	global_load_dword v87, v64, s[24:25] offset:192
	s_add_i32 s10, s8, 11
	v_or_b32_e32 v96, s9, v234
	s_and_b64 s[8:9], s[22:23], exec
	s_cselect_b32 s8, 10, s10
	s_mul_hi_u32 s9, s8, 0x4200
	s_mulk_i32 s8, 0x4200
	s_add_u32 s8, s1, s8
	s_addc_u32 s9, s2, s9
	v_lshlrev_b32_e32 v64, 2, v154
	v_mov_b32_e32 v65, v97
	v_lshl_add_u64 v[66:67], v[96:97], 2, s[8:9]
	s_waitcnt vmcnt(7)
	v_lshl_add_u64 v[76:77], v[66:67], 0, v[64:65]
	global_load_dwordx4 v[64:67], v[76:77], off
	global_load_dwordx4 v[68:71], v[76:77], off offset:64
	global_load_dwordx4 v[72:75], v[76:77], off offset:128
	s_nop 0
	global_load_dwordx4 v[76:79], v[76:77], off offset:192
	v_mul_u32_u24_e32 v80, 0x1080, v80
	v_or_b32_e32 v82, v96, v154
	v_lshlrev_b32_e32 v96, 1, v80
	v_lshl_add_u64 v[80:81], s[20:21], 0, v[96:97]
	v_lshlrev_b32_e32 v96, 1, v82
	v_lshl_add_u64 v[82:83], v[80:81], 0, v[96:97]
	s_add_i32 s7, s7, s96
	s_cmpk_gt_u32 s7, 0xff
	s_waitcnt vmcnt(7)
	v_fmamk_f32 v84, v84, 0x3a800000, v123
	v_mul_f32_e32 v88, 0x4b800000, v84
	v_cmp_gt_f32_e32 vcc, s6, v84
	s_waitcnt vmcnt(6)
	v_fmamk_f32 v85, v85, 0x3a800000, v123
	v_mul_f32_e32 v89, 0x4b800000, v85
	v_cndmask_b32_e32 v84, v84, v88, vcc
	v_cmp_gt_f32_e64 s[10:11], s6, v85
	v_rsq_f32_e32 v84, v84
	s_waitcnt vmcnt(5)
	v_fmamk_f32 v86, v86, 0x3a800000, v123
	v_cndmask_b32_e64 v85, v85, v89, s[10:11]
	v_mul_f32_e32 v90, 0x4b800000, v86
	v_cmp_gt_f32_e64 s[12:13], s6, v86
	v_rsq_f32_e32 v85, v85
	s_waitcnt vmcnt(4)
	v_fmamk_f32 v87, v87, 0x3a800000, v123
	v_cndmask_b32_e64 v86, v86, v90, s[12:13]
	v_mul_f32_e32 v91, 0x4b800000, v87
	v_cmp_gt_f32_e64 s[14:15], s6, v87
	v_rsq_f32_e32 v88, v86
	v_mul_f32_e32 v86, 0x45800000, v84
	v_cndmask_b32_e64 v87, v87, v91, s[14:15]
	v_cndmask_b32_e32 v84, v84, v86, vcc
	v_rsq_f32_e32 v87, v87
	s_waitcnt vmcnt(2)
	v_pk_fma_f32 v[0:1], v[0:1], v[84:85], v[68:69] op_sel_hi:[1,0,1]
	v_pk_fma_f32 v[2:3], v[2:3], v[84:85], v[70:71] op_sel_hi:[1,0,1]
	s_waitcnt vmcnt(1)
	v_pk_fma_f32 v[12:13], v[12:13], v[84:85], v[72:73] op_sel_hi:[1,0,1]
	v_pk_fma_f32 v[14:15], v[14:15], v[84:85], v[74:75] op_sel_hi:[1,0,1]
	v_cvt_pk_bf16_f32 v0, v0, v1
	v_cvt_pk_bf16_f32 v1, v2, v3
	v_mul_f32_e32 v89, 0x45800000, v85
	s_waitcnt vmcnt(0)
	v_pk_fma_f32 v[4:5], v[4:5], v[84:85], v[76:77] op_sel_hi:[1,0,1]
	v_pk_fma_f32 v[6:7], v[6:7], v[84:85], v[78:79] op_sel_hi:[1,0,1]
	global_store_dwordx2 v[82:83], v[0:1], off offset:32
	v_cvt_pk_bf16_f32 v0, v12, v13
	v_cvt_pk_bf16_f32 v1, v14, v15
	v_cndmask_b32_e64 v86, v85, v89, s[10:11]
	global_store_dwordx2 v[82:83], v[0:1], off offset:64
	v_cvt_pk_bf16_f32 v0, v4, v5
	v_cvt_pk_bf16_f32 v1, v6, v7
	v_pk_fma_f32 v[32:33], v[32:33], v[86:87], v[64:65] op_sel_hi:[1,0,1]
	v_pk_fma_f32 v[34:35], v[34:35], v[86:87], v[66:67] op_sel_hi:[1,0,1]
	global_store_dwordx2 v[82:83], v[0:1], off offset:96
	v_lshl_add_u64 v[0:1], v[80:81], 0, s[36:37]
	v_cvt_pk_bf16_f32 v2, v32, v33
	v_cvt_pk_bf16_f32 v3, v34, v35
	v_lshl_add_u64 v[4:5], v[0:1], 0, v[96:97]
	v_pk_fma_f32 v[24:25], v[24:25], v[86:87], v[68:69] op_sel_hi:[1,0,1]
	v_pk_fma_f32 v[26:27], v[26:27], v[86:87], v[70:71] op_sel_hi:[1,0,1]
	global_store_dwordx2 v[4:5], v[2:3], off
	v_or_b32_e32 v4, 32, v96
	v_mov_b32_e32 v5, v97
	v_pk_fma_f32 v[8:9], v[8:9], v[84:85], v[64:65] op_sel_hi:[1,0,1]
	v_pk_fma_f32 v[10:11], v[10:11], v[84:85], v[66:67] op_sel_hi:[1,0,1]
	v_cvt_pk_bf16_f32 v2, v24, v25
	v_cvt_pk_bf16_f32 v3, v26, v27
	v_lshl_add_u64 v[6:7], v[0:1], 0, v[4:5]
	v_pk_fma_f32 v[20:21], v[20:21], v[86:87], v[72:73] op_sel_hi:[1,0,1]
	v_pk_fma_f32 v[22:23], v[22:23], v[86:87], v[74:75] op_sel_hi:[1,0,1]
	v_cvt_pk_bf16_f32 v8, v8, v9
	v_cvt_pk_bf16_f32 v9, v10, v11
	global_store_dwordx2 v[6:7], v[2:3], off
	v_or_b32_e32 v6, 64, v96
	v_mov_b32_e32 v7, v97
	global_store_dwordx2 v[82:83], v[8:9], off
	v_cvt_pk_bf16_f32 v2, v20, v21
	v_cvt_pk_bf16_f32 v3, v22, v23
	v_lshl_add_u64 v[8:9], v[0:1], 0, v[6:7]
	v_mul_f32_e32 v90, 0x45800000, v88
	v_pk_fma_f32 v[16:17], v[16:17], v[86:87], v[76:77] op_sel_hi:[1,0,1]
	v_pk_fma_f32 v[18:19], v[18:19], v[86:87], v[78:79] op_sel_hi:[1,0,1]
	global_store_dwordx2 v[8:9], v[2:3], off
	v_or_b32_e32 v8, 0x60, v96
	v_mov_b32_e32 v9, v97
	v_cndmask_b32_e64 v88, v88, v90, s[12:13]
	v_cvt_pk_bf16_f32 v2, v16, v17
	v_cvt_pk_bf16_f32 v3, v18, v19
	v_lshl_add_u64 v[0:1], v[0:1], 0, v[8:9]
	v_pk_fma_f32 v[48:49], v[48:49], v[88:89], v[64:65] op_sel_hi:[1,0,1]
	v_pk_fma_f32 v[50:51], v[50:51], v[88:89], v[66:67] op_sel_hi:[1,0,1]
	global_store_dwordx2 v[0:1], v[2:3], off
	v_lshl_add_u64 v[0:1], v[80:81], 0, s[38:39]
	v_pk_fma_f32 v[40:41], v[40:41], v[88:89], v[68:69] op_sel_hi:[1,0,1]
	v_pk_fma_f32 v[42:43], v[42:43], v[88:89], v[70:71] op_sel_hi:[1,0,1]
	v_cvt_pk_bf16_f32 v2, v48, v49
	v_cvt_pk_bf16_f32 v3, v50, v51
	v_lshl_add_u64 v[10:11], v[0:1], 0, v[96:97]
	v_pk_fma_f32 v[36:37], v[36:37], v[88:89], v[72:73] op_sel_hi:[1,0,1]
	v_pk_fma_f32 v[38:39], v[38:39], v[88:89], v[74:75] op_sel_hi:[1,0,1]
	global_store_dwordx2 v[10:11], v[2:3], off
	v_cvt_pk_bf16_f32 v2, v40, v41
	v_cvt_pk_bf16_f32 v3, v42, v43
	v_lshl_add_u64 v[10:11], v[0:1], 0, v[4:5]
	v_mul_f32_e32 v91, 0x45800000, v87
	v_pk_fma_f32 v[28:29], v[28:29], v[88:89], v[76:77] op_sel_hi:[1,0,1]
	v_pk_fma_f32 v[30:31], v[30:31], v[88:89], v[78:79] op_sel_hi:[1,0,1]
	global_store_dwordx2 v[10:11], v[2:3], off
	v_cvt_pk_bf16_f32 v2, v36, v37
	v_cvt_pk_bf16_f32 v3, v38, v39
	v_lshl_add_u64 v[10:11], v[0:1], 0, v[6:7]
	v_cndmask_b32_e64 v90, v87, v91, s[14:15]
	global_store_dwordx2 v[10:11], v[2:3], off
	v_cvt_pk_bf16_f32 v2, v28, v29
	v_cvt_pk_bf16_f32 v3, v30, v31
	v_lshl_add_u64 v[0:1], v[0:1], 0, v[8:9]
	v_pk_fma_f32 v[60:61], v[60:61], v[90:91], v[64:65] op_sel_hi:[1,0,1]
	v_pk_fma_f32 v[62:63], v[62:63], v[90:91], v[66:67] op_sel_hi:[1,0,1]
	global_store_dwordx2 v[0:1], v[2:3], off
	v_lshl_add_u64 v[0:1], v[80:81], 0, s[40:41]
	v_pk_fma_f32 v[56:57], v[56:57], v[90:91], v[68:69] op_sel_hi:[1,0,1]
	v_pk_fma_f32 v[58:59], v[58:59], v[90:91], v[70:71] op_sel_hi:[1,0,1]
	v_cvt_pk_bf16_f32 v2, v60, v61
	v_cvt_pk_bf16_f32 v3, v62, v63
	v_lshl_add_u64 v[10:11], v[0:1], 0, v[96:97]
	v_pk_fma_f32 v[52:53], v[52:53], v[90:91], v[72:73] op_sel_hi:[1,0,1]
	v_pk_fma_f32 v[54:55], v[54:55], v[90:91], v[74:75] op_sel_hi:[1,0,1]
	global_store_dwordx2 v[10:11], v[2:3], off
	v_cvt_pk_bf16_f32 v2, v56, v57
	v_cvt_pk_bf16_f32 v3, v58, v59
	v_lshl_add_u64 v[4:5], v[0:1], 0, v[4:5]
	v_pk_fma_f32 v[44:45], v[44:45], v[90:91], v[76:77] op_sel_hi:[1,0,1]
	v_pk_fma_f32 v[46:47], v[46:47], v[90:91], v[78:79] op_sel_hi:[1,0,1]
	global_store_dwordx2 v[4:5], v[2:3], off
	v_cvt_pk_bf16_f32 v2, v52, v53
	v_cvt_pk_bf16_f32 v3, v54, v55
	v_lshl_add_u64 v[4:5], v[0:1], 0, v[6:7]
	global_store_dwordx2 v[4:5], v[2:3], off
	v_cvt_pk_bf16_f32 v2, v44, v45
	v_cvt_pk_bf16_f32 v3, v46, v47
	v_lshl_add_u64 v[0:1], v[0:1], 0, v[8:9]
	global_store_dwordx2 v[0:1], v[2:3], off
	s_cbranch_scc0 .LBB0_739

.LBB0_1101:
	s_add_i32 s33, s40, 2
	s_setprio 1
	ds_read_b128 v[126:129], v119 offset:32768
	ds_read_b128 v[134:137], v119 offset:34816
	ds_read_b128 v[130:133], v118
	ds_read_b128 v[138:141], v118 offset:2048
	ds_read_b128 v[160:163], v118 offset:4096
	ds_read_b128 v[164:167], v118 offset:6144
	s_waitcnt lgkmcnt(3)
	v_mfma_f32_16x16x32_bf16 v[64:67], v[126:129], v[130:133], v[64:67]
	ds_read_b128 v[168:171], v119 offset:36864
	v_mfma_f32_16x16x32_bf16 v[40:43], v[134:137], v[130:133], v[40:43]
	ds_read_b128 v[172:175], v119 offset:38912
	s_waitcnt lgkmcnt(1)
	v_mfma_f32_16x16x32_bf16 v[28:31], v[168:171], v[130:133], v[28:31]
	s_waitcnt lgkmcnt(0)
	v_mfma_f32_16x16x32_bf16 v[12:15], v[172:175], v[130:133], v[12:15]
	s_add_u32 m0, s42, 0x4000
	s_nop 0
	global_load_lds_dwordx4 v68, s[98:99]
	ds_read_b128 v[176:179], v120
	v_mfma_f32_16x16x32_bf16 v[60:63], v[126:129], v[138:141], v[60:63]
	v_mfma_f32_16x16x32_bf16 v[44:47], v[134:137], v[138:141], v[44:47]
	s_add_u32 m0, s42, 0x5000
	s_nop 0
	global_load_lds_dwordx4 v69, s[98:99]
	ds_read_b128 v[184:187], v120 offset:2048
	v_mfma_f32_16x16x32_bf16 v[24:27], v[168:171], v[138:141], v[24:27]
	v_mfma_f32_16x16x32_bf16 v[8:11], v[172:175], v[138:141], v[8:11]
	s_add_u32 m0, s42, 0x6000
	s_nop 0
	global_load_lds_dwordx4 v70, s[98:99]
	ds_read_b128 v[188:191], v120 offset:4096
	v_mfma_f32_16x16x32_bf16 v[52:55], v[126:129], v[160:163], v[52:55]
	v_mfma_f32_16x16x32_bf16 v[36:39], v[134:137], v[160:163], v[36:39]
	s_add_u32 m0, s42, 0x7000
	s_nop 0
	global_load_lds_dwordx4 v71, s[98:99]
	ds_read_b128 v[196:199], v120 offset:6144
	v_mfma_f32_16x16x32_bf16 v[20:23], v[168:171], v[160:163], v[20:23]
	v_mfma_f32_16x16x32_bf16 v[4:7], v[172:175], v[160:163], v[4:7]
	s_add_u32 m0, s42, 0xc000
	s_nop 0
	global_load_lds_dwordx4 v68, s[100:101]
	ds_read_b128 v[200:203], v121 offset:32768
	v_mfma_f32_16x16x32_bf16 v[48:51], v[126:129], v[164:167], v[48:51]
	v_mfma_f32_16x16x32_bf16 v[32:35], v[134:137], v[164:167], v[32:35]
	s_add_u32 m0, s42, 0xd000
	s_nop 0
	global_load_lds_dwordx4 v69, s[100:101]
	ds_read_b128 v[134:137], v121 offset:34816
	v_mfma_f32_16x16x32_bf16 v[16:19], v[168:171], v[164:167], v[16:19]
	v_mfma_f32_16x16x32_bf16 v[0:3], v[172:175], v[164:167], v[0:3]
	s_add_u32 m0, s42, 0xe000
	s_nop 0
	global_load_lds_dwordx4 v70, s[100:101]
	ds_read_b128 v[168:171], v121 offset:36864
	s_waitcnt lgkmcnt(2)
	v_mfma_f32_16x16x32_bf16 v[64:67], v[200:203], v[176:179], v[64:67]
	s_waitcnt lgkmcnt(1)
	v_mfma_f32_16x16x32_bf16 v[40:43], v[134:137], v[176:179], v[40:43]
	s_add_u32 m0, s42, 0xf000
	s_nop 0
	global_load_lds_dwordx4 v71, s[100:101]
	s_add_u32 s98, s98, 0x80
	s_addc_u32 s99, s99, 0
	s_add_u32 s100, s100, 0x80
	s_addc_u32 s101, s101, 0
	ds_read_b128 v[204:207], v121 offset:38912
	s_waitcnt lgkmcnt(1)
	v_mfma_f32_16x16x32_bf16 v[28:31], v[168:171], v[176:179], v[28:31]
	s_waitcnt lgkmcnt(0)
	v_mfma_f32_16x16x32_bf16 v[12:15], v[204:207], v[176:179], v[12:15]
	v_mfma_f32_16x16x32_bf16 v[60:63], v[200:203], v[184:187], v[60:63]
	v_mfma_f32_16x16x32_bf16 v[44:47], v[134:137], v[184:187], v[44:47]
	v_mfma_f32_16x16x32_bf16 v[24:27], v[168:171], v[184:187], v[24:27]
	v_mfma_f32_16x16x32_bf16 v[8:11], v[204:207], v[184:187], v[8:11]
	v_mfma_f32_16x16x32_bf16 v[52:55], v[200:203], v[188:191], v[52:55]
	v_mfma_f32_16x16x32_bf16 v[36:39], v[134:137], v[188:191], v[36:39]
	v_mfma_f32_16x16x32_bf16 v[20:23], v[168:171], v[188:191], v[20:23]
	v_mfma_f32_16x16x32_bf16 v[4:7], v[204:207], v[188:191], v[4:7]
	v_mfma_f32_16x16x32_bf16 v[48:51], v[200:203], v[196:199], v[48:51]
	v_mfma_f32_16x16x32_bf16 v[32:35], v[134:137], v[196:199], v[32:35]
	v_mfma_f32_16x16x32_bf16 v[16:19], v[168:171], v[196:199], v[16:19]
	v_mfma_f32_16x16x32_bf16 v[0:3], v[204:207], v[196:199], v[0:3]
	s_setprio 0
	s_waitcnt vmcnt(0) lgkmcnt(0)
	s_barrier
	s_setprio 1
	ds_read_b128 v[84:87], v119 offset:49152
	ds_read_b128 v[88:91], v119 offset:51200
	ds_read_b128 v[56:59], v118 offset:16384
	ds_read_b128 v[72:75], v118 offset:18432
	ds_read_b128 v[76:79], v118 offset:20480
	ds_read_b128 v[92:95], v118 offset:22528
	s_waitcnt lgkmcnt(3)
	v_mfma_f32_16x16x32_bf16 v[64:67], v[84:87], v[56:59], v[64:67]
	ds_read_b128 v[134:137], v119 offset:53248
	v_mfma_f32_16x16x32_bf16 v[40:43], v[88:91], v[56:59], v[40:43]
	ds_read_b128 v[168:171], v119 offset:55296
	s_waitcnt lgkmcnt(1)
	v_mfma_f32_16x16x32_bf16 v[28:31], v[134:137], v[56:59], v[28:31]
	s_waitcnt lgkmcnt(0)
	v_mfma_f32_16x16x32_bf16 v[12:15], v[168:171], v[56:59], v[12:15]
	s_add_u32 m0, s42, 0x0
	s_nop 0
	global_load_lds_dwordx4 v68, s[98:99]
	ds_read_b128 v[176:179], v120 offset:16384
	v_mfma_f32_16x16x32_bf16 v[60:63], v[84:87], v[72:75], v[60:63]
	v_mfma_f32_16x16x32_bf16 v[44:47], v[88:91], v[72:75], v[44:47]
	s_add_u32 m0, s42, 0x1000
	s_nop 0
	global_load_lds_dwordx4 v69, s[98:99]
	ds_read_b128 v[184:187], v120 offset:18432
	v_mfma_f32_16x16x32_bf16 v[24:27], v[134:137], v[72:75], v[24:27]
	v_mfma_f32_16x16x32_bf16 v[8:11], v[168:171], v[72:75], v[8:11]
	s_add_u32 m0, s42, 0x2000
	s_nop 0
	global_load_lds_dwordx4 v70, s[98:99]
	ds_read_b128 v[188:191], v120 offset:20480
	v_mfma_f32_16x16x32_bf16 v[52:55], v[84:87], v[76:79], v[52:55]
	v_mfma_f32_16x16x32_bf16 v[36:39], v[88:91], v[76:79], v[36:39]
	s_add_u32 m0, s42, 0x3000
	s_nop 0
	global_load_lds_dwordx4 v71, s[98:99]
	ds_read_b128 v[196:199], v120 offset:22528
	v_mfma_f32_16x16x32_bf16 v[20:23], v[134:137], v[76:79], v[20:23]
	v_mfma_f32_16x16x32_bf16 v[4:7], v[168:171], v[76:79], v[4:7]
	s_add_u32 m0, s42, 0x8000
	s_nop 0
	global_load_lds_dwordx4 v68, s[100:101]
	ds_read_b128 v[200:203], v121 offset:49152
	v_mfma_f32_16x16x32_bf16 v[48:51], v[84:87], v[92:95], v[48:51]
	v_mfma_f32_16x16x32_bf16 v[32:35], v[88:91], v[92:95], v[32:35]
	s_add_u32 m0, s42, 0x9000
	s_nop 0
	global_load_lds_dwordx4 v69, s[100:101]
	ds_read_b128 v[204:207], v121 offset:51200
	v_mfma_f32_16x16x32_bf16 v[16:19], v[134:137], v[92:95], v[16:19]
	v_mfma_f32_16x16x32_bf16 v[0:3], v[168:171], v[92:95], v[0:3]
	s_add_u32 m0, s42, 0xa000
	s_nop 0
	global_load_lds_dwordx4 v70, s[100:101]
	ds_read_b128 v[134:137], v121 offset:53248
	s_waitcnt lgkmcnt(2)
	v_mfma_f32_16x16x32_bf16 v[64:67], v[200:203], v[176:179], v[64:67]
	s_waitcnt lgkmcnt(1)
	v_mfma_f32_16x16x32_bf16 v[40:43], v[204:207], v[176:179], v[40:43]
	s_add_u32 m0, s42, 0xb000
	s_nop 0
	global_load_lds_dwordx4 v71, s[100:101]
	s_add_u32 s98, s98, 0x80
	s_addc_u32 s99, s99, 0
	s_add_u32 s100, s100, 0x80
	s_addc_u32 s101, s101, 0
	ds_read_b128 v[168:171], v121 offset:55296
	s_waitcnt lgkmcnt(1)
	v_mfma_f32_16x16x32_bf16 v[28:31], v[134:137], v[176:179], v[28:31]
	s_waitcnt lgkmcnt(0)
	v_mfma_f32_16x16x32_bf16 v[12:15], v[168:171], v[176:179], v[12:15]
	v_mfma_f32_16x16x32_bf16 v[60:63], v[200:203], v[184:187], v[60:63]
	v_mfma_f32_16x16x32_bf16 v[44:47], v[204:207], v[184:187], v[44:47]
	v_mfma_f32_16x16x32_bf16 v[24:27], v[134:137], v[184:187], v[24:27]
	v_mfma_f32_16x16x32_bf16 v[8:11], v[168:171], v[184:187], v[8:11]
	v_mfma_f32_16x16x32_bf16 v[52:55], v[200:203], v[188:191], v[52:55]
	v_mfma_f32_16x16x32_bf16 v[36:39], v[204:207], v[188:191], v[36:39]
	v_mfma_f32_16x16x32_bf16 v[20:23], v[134:137], v[188:191], v[20:23]
	v_mfma_f32_16x16x32_bf16 v[4:7], v[168:171], v[188:191], v[4:7]
	v_mfma_f32_16x16x32_bf16 v[48:51], v[200:203], v[196:199], v[48:51]
	v_mfma_f32_16x16x32_bf16 v[32:35], v[204:207], v[196:199], v[32:35]
	v_mfma_f32_16x16x32_bf16 v[16:19], v[134:137], v[196:199], v[16:19]
	v_mfma_f32_16x16x32_bf16 v[0:3], v[168:171], v[196:199], v[0:3]
	s_setprio 0
	s_mov_b32 s40, s33
	s_waitcnt vmcnt(0) lgkmcnt(0)
	s_barrier
	s_cmp_lt_u32 s40, 16
	s_cbranch_scc1 .LBB0_1101
	s_mov_b32 s98, 0
	s_waitcnt vmcnt(1)
	v_add_u32_e32 v88, s1, v122
	s_addk_i32 s1, 0xf000
	s_ashr_i32 s1, s1, 10
	s_add_i32 s1, s1, 1
	s_and_b64 s[40:41], s[20:21], exec
	s_cselect_b32 s1, 0, s1
	s_mul_i32 s2, s1, 0x3000
	s_add_i32 s26, s1, 10
	s_add_i32 s33, s2, 0x1e000
	s_mul_hi_u32 s26, s26, 0x3000
	s_add_u32 s33, s4, s33
	s_addc_u32 s26, s5, s26
	s_add_u32 s42, s33, 0x2000
	s_addc_u32 s43, s26, 0
	s_add_i32 s1, s1, 15
	s_add_i32 s2, s2, 0x2d000
	s_mul_hi_u32 s1, s1, 0x3000
	s_add_u32 s2, s4, s2
	s_addc_u32 s1, s5, s1
	s_add_u32 s40, s2, 0x1000
	v_or_b32_e32 v96, s0, v123
	v_lshlrev_b64 v[72:73], 2, v[96:97]
	s_addc_u32 s41, s1, 0
	v_lshl_add_u64 v[56:57], s[42:43], 0, v[72:73]
	v_lshl_add_u64 v[70:71], s[12:13], 0, v[72:73]
	v_lshlrev_b32_e32 v58, 12, v88
	v_mov_b32_e32 v59, v97
	v_lshl_add_u64 v[74:75], s[40:41], 0, v[72:73]
	v_lshl_add_u64 v[68:69], v[70:71], 0, v[58:59]
	global_load_dwordx4 v[90:93], v[56:57], off
	s_nop 0
	global_load_dwordx4 v[56:59], v[68:69], off
	global_load_dwordx4 v[78:81], v[74:75], off
	v_lshl_add_u64 v[72:73], s[14:15], 0, v[72:73]
	global_load_dwordx4 v[82:85], v[72:73], off
	v_mov_b32_e32 v75, v97
	v_lshlrev_b32_e32 v74, 1, v96
	v_lshlrev_b32_e32 v89, 10, v88
	v_mov_b32_e32 v87, v97
	v_lshlrev_b32_e32 v86, 11, v88
	s_waitcnt vmcnt(4)
	v_lshl_add_u64 v[94:95], s[22:23], 0, v[74:75]
	v_or_b32_e32 v104, 0x4000, v89
	v_mov_b32_e32 v77, v97
	v_lshl_add_u64 v[74:75], v[94:95], 0, v[86:87]
	v_lshlrev_b32_e32 v76, 2, v104
	v_lshl_add_u64 v[98:99], v[70:71], 0, v[76:77]
	v_mov_b32_e32 v107, v97
	v_or_b32_e32 v106, 16, v96
	v_lshl_add_u64 v[86:87], s[22:23], 0, v[86:87]
	s_waitcnt vmcnt(2)
	v_pk_fma_f32 v[64:65], v[64:65], v[90:91], v[56:57]
	v_pk_fma_f32 v[66:67], v[66:67], v[92:93], v[58:59]
	s_waitcnt vmcnt(1)
	v_pk_add_f32 v[56:57], v[78:79], 1.0 op_sel_hi:[1,0]
	v_pk_add_f32 v[58:59], v[80:81], 1.0 op_sel_hi:[1,0]
	s_waitcnt vmcnt(0)
	v_pk_mul_f32 v[100:101], v[82:83], v[56:57]
	v_pk_mul_f32 v[102:103], v[84:85], v[58:59]
	v_pk_mul_f32 v[56:57], v[100:101], v[64:65]
	v_pk_mul_f32 v[58:59], v[102:103], v[66:67]
	v_cvt_pk_bf16_f32 v56, v56, v57
	v_cvt_pk_bf16_f32 v57, v58, v59
	global_store_dwordx4 v[68:69], v[64:67], off
	global_store_dwordx2 v[74:75], v[56:57], off
	global_load_dwordx4 v[56:59], v[98:99], off
	v_mov_b32_e32 v79, v97
	v_or_b32_e32 v82, 0x8000, v89
	v_lshlrev_b32_e32 v78, 1, v104
	v_mov_b32_e32 v81, v97
	v_lshlrev_b32_e32 v80, 2, v82
	v_lshl_add_u64 v[74:75], v[94:95], 0, v[78:79]
	v_lshl_add_u64 v[104:105], v[70:71], 0, v[80:81]
	v_mov_b32_e32 v83, v97
	v_or_b32_e32 v89, 0xc000, v89
	v_lshlrev_b32_e32 v82, 1, v82
	v_mov_b32_e32 v85, v97
	v_lshlrev_b32_e32 v84, 2, v89
	v_pk_mul_f32 v[64:65], v[64:65], v[64:65]
	v_pk_mul_f32 v[66:67], v[66:67], v[66:67]
	v_add_f32_e32 v64, v64, v65
	v_add_f32_e32 v64, v66, v64
	v_add_f32_e32 v64, v67, v64
	s_waitcnt vmcnt(0)
	v_pk_fma_f32 v[56:57], v[60:61], v[90:91], v[56:57]
	v_pk_fma_f32 v[58:59], v[62:63], v[92:93], v[58:59]
	v_pk_mul_f32 v[60:61], v[100:101], v[56:57]
	v_pk_mul_f32 v[62:63], v[102:103], v[58:59]
	v_cvt_pk_bf16_f32 v60, v60, v61
	v_cvt_pk_bf16_f32 v61, v62, v63
	global_store_dwordx4 v[98:99], v[56:59], off
	global_store_dwordx2 v[74:75], v[60:61], off
	global_load_dwordx4 v[60:63], v[104:105], off
	v_lshl_add_u64 v[74:75], v[94:95], 0, v[82:83]
	v_lshl_add_u64 v[98:99], v[70:71], 0, v[84:85]
	s_waitcnt vmcnt(0)
	v_pk_fma_f32 v[52:53], v[52:53], v[90:91], v[60:61]
	v_pk_fma_f32 v[54:55], v[54:55], v[92:93], v[62:63]
	v_pk_mul_f32 v[60:61], v[100:101], v[52:53]
	v_pk_mul_f32 v[62:63], v[102:103], v[54:55]
	v_cvt_pk_bf16_f32 v60, v60, v61
	v_cvt_pk_bf16_f32 v61, v62, v63
	global_store_dwordx4 v[104:105], v[52:55], off
	global_store_dwordx2 v[74:75], v[60:61], off
	global_load_dwordx4 v[60:63], v[98:99], off
	v_mov_b32_e32 v75, v97
	v_lshlrev_b32_e32 v74, 1, v89
	v_lshlrev_b64 v[104:105], 2, v[106:107]
	v_lshl_add_u64 v[94:95], v[94:95], 0, v[74:75]
	v_lshl_add_u64 v[108:109], s[42:43], 0, v[104:105]
	s_waitcnt vmcnt(0)
	v_pk_fma_f32 v[48:49], v[48:49], v[90:91], v[60:61]
	v_pk_fma_f32 v[50:51], v[50:51], v[92:93], v[62:63]
	v_pk_mul_f32 v[60:61], v[100:101], v[48:49]
	v_pk_mul_f32 v[62:63], v[102:103], v[50:51]
	v_cvt_pk_bf16_f32 v60, v60, v61
	v_cvt_pk_bf16_f32 v61, v62, v63
	global_store_dwordx4 v[98:99], v[48:51], off
	global_store_dwordx2 v[94:95], v[60:61], off
	global_load_dwordx4 v[90:93], v[108:109], off
	s_nop 0
	global_load_dwordx4 v[60:63], v[68:69], off offset:64
	v_lshl_add_u64 v[94:95], s[40:41], 0, v[104:105]
	global_load_dwordx4 v[98:101], v[94:95], off
	global_load_dwordx4 v[102:105], v[72:73], off offset:64
	v_mov_b32_e32 v95, v97
	v_lshlrev_b32_e32 v94, 1, v106
	v_lshl_add_u64 v[106:107], v[70:71], 0, 64
	v_lshl_add_u64 v[108:109], v[86:87], 0, v[94:95]
	v_lshl_add_u64 v[110:111], v[106:107], 0, v[76:77]
	v_lshl_add_u64 v[94:95], s[22:23], 0, v[94:95]
	s_waitcnt vmcnt(2)
	v_pk_fma_f32 v[60:61], v[40:41], v[90:91], v[60:61]
	v_pk_fma_f32 v[62:63], v[42:43], v[92:93], v[62:63]
	s_waitcnt vmcnt(1)
	v_pk_add_f32 v[40:41], v[98:99], 1.0 op_sel_hi:[1,0]
	v_pk_add_f32 v[42:43], v[100:101], 1.0 op_sel_hi:[1,0]
	s_waitcnt vmcnt(0)
	v_pk_mul_f32 v[98:99], v[102:103], v[40:41]
	v_pk_mul_f32 v[100:101], v[104:105], v[42:43]
	v_pk_mul_f32 v[40:41], v[98:99], v[60:61]
	v_pk_mul_f32 v[42:43], v[100:101], v[62:63]
	v_cvt_pk_bf16_f32 v40, v40, v41
	v_cvt_pk_bf16_f32 v41, v42, v43
	global_store_dwordx4 v[68:69], v[60:63], off offset:64
	global_store_dwordx2 v[108:109], v[40:41], off
	global_load_dwordx4 v[40:43], v[110:111], off
	v_lshl_add_u64 v[102:103], v[94:95], 0, v[78:79]
	v_lshl_add_u64 v[104:105], v[106:107], 0, v[80:81]
	v_lshl_add_u64 v[106:107], v[106:107], 0, v[84:85]
	v_mov_b32_e32 v109, v97
	v_or_b32_e32 v108, 32, v96
	v_or_b32_e32 v96, 48, v96
	v_pk_mul_f32 v[60:61], v[60:61], v[60:61]
	v_pk_mul_f32 v[62:63], v[62:63], v[62:63]
	v_add_f32_e32 v60, v60, v61
	v_add_f32_e32 v60, v62, v60
	v_add_f32_e32 v60, v63, v60
	v_add_f32_e32 v60, v64, v60
	s_waitcnt vmcnt(0)
	v_pk_fma_f32 v[40:41], v[44:45], v[90:91], v[40:41]
	v_pk_fma_f32 v[42:43], v[46:47], v[92:93], v[42:43]
	v_pk_mul_f32 v[44:45], v[98:99], v[40:41]
	v_pk_mul_f32 v[46:47], v[100:101], v[42:43]
	v_cvt_pk_bf16_f32 v44, v44, v45
	v_cvt_pk_bf16_f32 v45, v46, v47
	global_store_dwordx4 v[110:111], v[40:43], off
	global_store_dwordx2 v[102:103], v[44:45], off
	global_load_dwordx4 v[44:47], v[104:105], off
	v_lshl_add_u64 v[102:103], v[94:95], 0, v[82:83]
	v_lshl_add_u64 v[94:95], v[94:95], 0, v[74:75]
	s_waitcnt vmcnt(0)
	v_pk_fma_f32 v[36:37], v[36:37], v[90:91], v[44:45]
	v_pk_fma_f32 v[38:39], v[38:39], v[92:93], v[46:47]
	v_pk_mul_f32 v[44:45], v[98:99], v[36:37]
	v_pk_mul_f32 v[46:47], v[100:101], v[38:39]
	v_cvt_pk_bf16_f32 v44, v44, v45
	v_cvt_pk_bf16_f32 v45, v46, v47
	global_store_dwordx4 v[104:105], v[36:39], off
	global_store_dwordx2 v[102:103], v[44:45], off
	global_load_dwordx4 v[44:47], v[106:107], off
	v_lshlrev_b64 v[102:103], 2, v[108:109]
	v_lshl_add_u64 v[104:105], s[42:43], 0, v[102:103]
	s_waitcnt vmcnt(0)
	v_pk_fma_f32 v[32:33], v[32:33], v[90:91], v[44:45]
	v_pk_fma_f32 v[34:35], v[34:35], v[92:93], v[46:47]
	v_pk_mul_f32 v[44:45], v[98:99], v[32:33]
	v_pk_mul_f32 v[46:47], v[100:101], v[34:35]
	v_cvt_pk_bf16_f32 v44, v44, v45
	v_cvt_pk_bf16_f32 v45, v46, v47
	global_store_dwordx4 v[106:107], v[32:35], off
	global_store_dwordx2 v[94:95], v[44:45], off
	global_load_dwordx4 v[44:47], v[104:105], off
	s_nop 0
	global_load_dwordx4 v[90:93], v[68:69], off offset:128
	v_lshl_add_u64 v[94:95], s[40:41], 0, v[102:103]
	global_load_dwordx4 v[98:101], v[94:95], off
	global_load_dwordx4 v[102:105], v[72:73], off offset:128
	v_mov_b32_e32 v95, v97
	v_lshlrev_b32_e32 v94, 1, v108
	v_lshl_add_u64 v[106:107], v[70:71], 0, s[36:37]
	v_lshl_add_u64 v[108:109], v[86:87], 0, v[94:95]
	v_lshl_add_u64 v[110:111], v[106:107], 0, v[76:77]
	v_lshl_add_u64 v[94:95], s[22:23], 0, v[94:95]
	s_waitcnt vmcnt(2)
	v_pk_fma_f32 v[28:29], v[28:29], v[44:45], v[90:91]
	v_pk_fma_f32 v[30:31], v[30:31], v[46:47], v[92:93]
	s_waitcnt vmcnt(1)
	v_pk_add_f32 v[90:91], v[98:99], 1.0 op_sel_hi:[1,0]
	v_pk_add_f32 v[92:93], v[100:101], 1.0 op_sel_hi:[1,0]
	s_waitcnt vmcnt(0)
	v_pk_mul_f32 v[98:99], v[102:103], v[90:91]
	v_pk_mul_f32 v[100:101], v[104:105], v[92:93]
	v_pk_mul_f32 v[90:91], v[98:99], v[28:29]
	v_pk_mul_f32 v[92:93], v[100:101], v[30:31]
	v_cvt_pk_bf16_f32 v90, v90, v91
	v_cvt_pk_bf16_f32 v91, v92, v93
	global_store_dwordx4 v[68:69], v[28:31], off offset:128
	global_store_dwordx2 v[108:109], v[90:91], off
	global_load_dwordx4 v[90:93], v[110:111], off
	v_lshl_add_u64 v[102:103], v[94:95], 0, v[78:79]
	v_lshl_add_u64 v[104:105], v[106:107], 0, v[80:81]
	v_lshl_add_u64 v[106:107], v[106:107], 0, v[84:85]
	v_pk_mul_f32 v[28:29], v[28:29], v[28:29]
	v_pk_mul_f32 v[30:31], v[30:31], v[30:31]
	v_add_f32_e32 v28, v28, v29
	v_add_f32_e32 v28, v30, v28
	v_add_f32_e32 v28, v31, v28
	v_add_f32_e32 v28, v60, v28
	s_waitcnt vmcnt(0)
	v_pk_fma_f32 v[24:25], v[24:25], v[44:45], v[90:91]
	v_pk_fma_f32 v[26:27], v[26:27], v[46:47], v[92:93]
	v_pk_mul_f32 v[90:91], v[98:99], v[24:25]
	v_pk_mul_f32 v[92:93], v[100:101], v[26:27]
	v_cvt_pk_bf16_f32 v90, v90, v91
	v_cvt_pk_bf16_f32 v91, v92, v93
	global_store_dwordx4 v[110:111], v[24:27], off
	global_store_dwordx2 v[102:103], v[90:91], off
	global_load_dwordx4 v[90:93], v[104:105], off
	v_lshl_add_u64 v[102:103], v[94:95], 0, v[82:83]
	v_lshl_add_u64 v[94:95], v[94:95], 0, v[74:75]
	s_waitcnt vmcnt(0)
	v_pk_fma_f32 v[20:21], v[20:21], v[44:45], v[90:91]
	v_pk_fma_f32 v[22:23], v[22:23], v[46:47], v[92:93]
	v_pk_mul_f32 v[90:91], v[98:99], v[20:21]
	v_pk_mul_f32 v[92:93], v[100:101], v[22:23]
	v_cvt_pk_bf16_f32 v90, v90, v91
	v_cvt_pk_bf16_f32 v91, v92, v93
	global_store_dwordx4 v[104:105], v[20:23], off
	global_store_dwordx2 v[102:103], v[90:91], off
	global_load_dwordx4 v[90:93], v[106:107], off
	v_lshlrev_b64 v[102:103], 2, v[96:97]
	v_lshl_add_u64 v[104:105], s[42:43], 0, v[102:103]
	v_lshlrev_b32_e32 v96, 1, v96
	s_waitcnt vmcnt(0)
	v_pk_fma_f32 v[16:17], v[16:17], v[44:45], v[90:91]
	v_pk_fma_f32 v[18:19], v[18:19], v[46:47], v[92:93]
	v_pk_mul_f32 v[44:45], v[98:99], v[16:17]
	v_pk_mul_f32 v[46:47], v[100:101], v[18:19]
	v_cvt_pk_bf16_f32 v44, v44, v45
	v_cvt_pk_bf16_f32 v45, v46, v47
	global_store_dwordx4 v[106:107], v[16:19], off
	global_store_dwordx2 v[94:95], v[44:45], off
	global_load_dwordx4 v[44:47], v[104:105], off
	s_nop 0
	global_load_dwordx4 v[90:93], v[68:69], off offset:192
	v_lshl_add_u64 v[94:95], s[40:41], 0, v[102:103]
	global_load_dwordx4 v[98:101], v[94:95], off
	global_load_dwordx4 v[102:105], v[72:73], off offset:192
	v_lshl_add_u64 v[72:73], v[70:71], 0, s[38:39]
	v_lshl_add_u64 v[70:71], v[86:87], 0, v[96:97]
	v_lshl_add_u64 v[76:77], v[72:73], 0, v[76:77]
	v_lshl_add_u64 v[80:81], v[72:73], 0, v[80:81]
	v_lshl_add_u64 v[72:73], v[72:73], 0, v[84:85]
	s_waitcnt vmcnt(2)
	v_pk_fma_f32 v[12:13], v[12:13], v[44:45], v[90:91]
	s_waitcnt vmcnt(1)
	v_pk_add_f32 v[86:87], v[98:99], 1.0 op_sel_hi:[1,0]
	v_pk_add_f32 v[90:91], v[100:101], 1.0 op_sel_hi:[1,0]
	v_pk_fma_f32 v[14:15], v[14:15], v[46:47], v[92:93]
	s_waitcnt vmcnt(0)
	v_pk_mul_f32 v[86:87], v[102:103], v[86:87]
	v_pk_mul_f32 v[90:91], v[104:105], v[90:91]
	global_store_dwordx4 v[68:69], v[12:15], off offset:192
	v_pk_mul_f32 v[68:69], v[86:87], v[12:13]
	v_pk_mul_f32 v[92:93], v[90:91], v[14:15]
	v_cvt_pk_bf16_f32 v68, v68, v69
	v_cvt_pk_bf16_f32 v69, v92, v93
	global_store_dwordx2 v[70:71], v[68:69], off
	global_load_dwordx4 v[68:71], v[76:77], off
	v_lshl_add_u64 v[92:93], s[22:23], 0, v[96:97]
	v_lshl_add_u64 v[78:79], v[92:93], 0, v[78:79]
	v_pk_mul_f32 v[12:13], v[12:13], v[12:13]
	v_pk_mul_f32 v[14:15], v[14:15], v[14:15]
	v_add_f32_e32 v12, v12, v13
	v_add_f32_e32 v12, v14, v12
	v_add_f32_e32 v12, v15, v12
	v_add_f32_e32 v14, v28, v12
	ds_bpermute_b32 v15, v124, v14
	v_lshlrev_b32_e32 v96, 2, v88
	v_lshl_add_u64 v[12:13], v[92:93], 0, v[74:75]
	s_waitcnt lgkmcnt(0)
	v_add_f32_e32 v14, v14, v15
	ds_bpermute_b32 v15, v125, v14
	s_waitcnt vmcnt(0)
	v_pk_fma_f32 v[8:9], v[8:9], v[44:45], v[68:69]
	v_pk_fma_f32 v[10:11], v[10:11], v[46:47], v[70:71]
	v_pk_mul_f32 v[68:69], v[86:87], v[8:9]
	v_pk_mul_f32 v[70:71], v[90:91], v[10:11]
	v_cvt_pk_bf16_f32 v68, v68, v69
	v_cvt_pk_bf16_f32 v69, v70, v71
	global_store_dwordx4 v[76:77], v[8:11], off
	global_store_dwordx2 v[78:79], v[68:69], off
	global_load_dwordx4 v[68:71], v[80:81], off
	v_lshl_add_u64 v[76:77], v[92:93], 0, v[82:83]
	s_waitcnt vmcnt(0)
	v_pk_fma_f32 v[4:5], v[4:5], v[44:45], v[68:69]
	v_pk_fma_f32 v[6:7], v[6:7], v[46:47], v[70:71]
	v_pk_mul_f32 v[68:69], v[86:87], v[4:5]
	v_pk_mul_f32 v[70:71], v[90:91], v[6:7]
	v_cvt_pk_bf16_f32 v68, v68, v69
	v_cvt_pk_bf16_f32 v69, v70, v71
	global_store_dwordx4 v[80:81], v[4:7], off
	global_store_dwordx2 v[76:77], v[68:69], off
	global_load_dwordx4 v[68:71], v[72:73], off
	s_waitcnt vmcnt(0)
	v_pk_fma_f32 v[0:1], v[0:1], v[44:45], v[68:69]
	v_pk_fma_f32 v[2:3], v[2:3], v[46:47], v[70:71]
	v_pk_mul_f32 v[28:29], v[86:87], v[0:1]
	v_pk_mul_f32 v[30:31], v[90:91], v[2:3]
	v_cvt_pk_bf16_f32 v28, v28, v29
	v_cvt_pk_bf16_f32 v29, v30, v31
	global_store_dwordx4 v[72:73], v[0:3], off
	global_store_dwordx2 v[12:13], v[28:29], off
	v_lshl_add_u64 v[12:13], s[24:25], 0, v[96:97]
	s_and_saveexec_b64 s[40:41], s[10:11]
	s_cbranch_execz .LBB0_1104
	s_waitcnt lgkmcnt(0)
	v_add_f32_e32 v14, v14, v15
	global_atomic_add_f32 v[12:13], v14, off

.LBB0_1165:
	s_and_b32 s0, s45, 7
	s_or_b32 s0, s0, s3
	s_lshl_b32 s46, s0, 7
	v_or_b32_e32 v0, s46, v149
	v_lshl_or_b32 v130, v0, 11, v129
	v_lshl_add_u64 v[30:31], s[22:23], 0, v[130:131]
	v_add_co_u32_e32 v4, vcc, 0x10000, v30
	s_lshl_b32 s1, s45, 4
	s_nop 0
	v_addc_co_u32_e32 v5, vcc, 0, v31, vcc
	s_and_b32 s0, s1, 0x7fffff80
	v_add_co_u32_e32 v12, vcc, 0x20000, v30
	v_or_b32_e32 v0, s0, v149
	s_nop 0
	v_addc_co_u32_e32 v13, vcc, 0, v31, vcc
	v_lshl_or_b32 v24, v0, 11, v129
	v_add_co_u32_e32 v16, vcc, 0x30000, v30
	v_mov_b32_e32 v25, v131
	s_nop 0
	v_addc_co_u32_e32 v17, vcc, 0, v31, vcc
	v_lshl_add_u64 v[52:53], s[20:21], 0, v[24:25]
	v_add_co_u32_e32 v18, vcc, s8, v52
	s_nop 0
	v_addc_co_u32_e32 v19, vcc, 0, v53, vcc
	v_add_co_u32_e32 v28, vcc, s9, v52
	s_nop 0
	v_addc_co_u32_e32 v29, vcc, 0, v53, vcc
	v_add_co_u32_e32 v58, vcc, s38, v52
	s_nop 0
	v_addc_co_u32_e32 v59, vcc, 0, v53, vcc
	s_nop 0
	s_nop 0
	s_nop 0
	s_movk_i32 s1, 0x100
	s_mov_b32 s6, s37
	v_mov_b32_e32 v8, 0
	v_mov_b32_e32 v9, v131
	v_mov_b32_e32 v10, v131
	v_mov_b32_e32 v11, v131
	v_mov_b32_e32 v26, 0
	v_mov_b32_e32 v27, v131
	v_mov_b32_e32 v28, v131
	v_mov_b32_e32 v29, v131
	v_mov_b32_e32 v16, 0
	v_mov_b32_e32 v17, v131
	v_mov_b32_e32 v18, v131
	v_mov_b32_e32 v19, v131
	v_mov_b32_e32 v60, 0
	v_mov_b32_e32 v61, v131
	v_lshl_add_u64 v[58:59], v[52:53], 0, s[18:19]
	v_lshl_add_u64 v[104:105], v[52:53], 0, s[30:31]
	v_lshl_add_u64 v[106:107], v[52:53], 0, s[34:35]
	v_lshl_add_u64 v[108:109], v[30:31], 0, s[18:19]
	v_lshl_add_u64 v[110:111], v[30:31], 0, s[30:31]
	v_lshl_add_u64 v[112:113], v[30:31], 0, s[34:35]
	s_barrier
	v_mov_b32_e32 v88, 0
	v_mov_b32_e32 v89, v131
	v_mov_b32_e32 v90, v131
	v_mov_b32_e32 v91, v131
	v_mov_b32_e32 v76, 0
	v_mov_b32_e32 v77, v131
	v_mov_b32_e32 v78, v131
	v_mov_b32_e32 v79, v131
	v_mov_b32_e32 v80, 0
	v_mov_b32_e32 v81, v131
	v_mov_b32_e32 v82, v131
	v_mov_b32_e32 v83, v131
	v_mov_b32_e32 v84, 0
	v_mov_b32_e32 v85, v131
	v_mov_b32_e32 v86, v131
	v_mov_b32_e32 v87, v131
	v_mov_b32_e32 v74, v131
	v_mov_b32_e32 v75, v131
	v_mov_b32_e32 v62, v131
	v_mov_b32_e32 v63, v131
	v_mov_b32_e32 v36, 0
	v_mov_b32_e32 v37, v131
	v_mov_b32_e32 v38, v131
	v_mov_b32_e32 v39, v131
	v_mov_b32_e32 v54, 0
	v_mov_b32_e32 v55, v131
	v_mov_b32_e32 v56, v131
	v_mov_b32_e32 v57, v131
	v_mov_b32_e32 v32, 0
	v_mov_b32_e32 v33, v131
	v_mov_b32_e32 v34, v131
	v_mov_b32_e32 v35, v131
	v_mov_b32_e32 v64, 0
	v_mov_b32_e32 v65, v131
	v_mov_b32_e32 v66, v131
	v_mov_b32_e32 v67, v131
	v_mov_b32_e32 v40, 0
	v_mov_b32_e32 v41, v131
	v_mov_b32_e32 v42, v131
	v_mov_b32_e32 v43, v131
	v_mov_b32_e32 v48, 0
	v_mov_b32_e32 v49, v131
	v_mov_b32_e32 v50, v131
	v_mov_b32_e32 v51, v131
	v_mov_b32_e32 v68, 0
	v_mov_b32_e32 v69, v131
	v_mov_b32_e32 v70, v131
	v_mov_b32_e32 v71, v131
	v_mov_b32_e32 v72, 0
	v_mov_b32_e32 v73, v131
	v_readlane_b32 s10, v253, 0
	v_readlane_b32 s11, v253, 1
	s_load_dwordx2 s[10:11], s[10:11], 0x160
	v_lshrrev_b32_e32 v7, 6, v146
	s_nop 0
	v_readfirstlane_b32 s1, v7
	v_lshrrev_b32_e32 v5, 3, v146
	v_and_b32_e32 v6, 7, v146
	v_xor_b32_e32 v6, v5, v6
	v_and_b32_e32 v6, 7, v6
	v_lshlrev_b32_e32 v6, 4, v6
	v_lshl_or_b32 v4, v5, 11, v6
	v_add_u32_e32 v5, 0x10000, v4
	v_add_u32_e32 v6, 0x20000, v4
	v_add_u32_e32 v7, 0x30000, v4
	s_and_b32 s7, s45, 7
	s_and_b32 s36, s69, 7
	s_lshl_b32 s36, s36, 3
	s_or_b32 s7, s7, s36
	s_lshl_b32 s7, s7, 18
	s_add_u32 s7, s7, 0xdc40000
	s_lshr_b32 s36, s45, 3
	s_lshl_b32 s36, s36, 18
	s_add_u32 s36, s36, 0x8740000
	s_lshl_b32 s1, s1, 10
	s_waitcnt lgkmcnt(0)
	s_add_u32 s7, s10, s7
	s_addc_u32 m0, s11, 0
	s_add_u32 s36, s10, s36
	s_addc_u32 s11, s11, 0
	s_add_u32 s10, s7, 0x80
	s_cmp_eq_u32 s10, s98
	s_cbranch_scc0 .Lnp1166_load
	s_add_u32 s10, s36, 0x80
	s_cmp_eq_u32 s10, s100
	s_cbranch_scc1 .Lnp1166_have
.Lnp1166_load:
	s_mov_b32 s98, s7
	s_mov_b32 s99, m0
	s_mov_b32 s100, s36
	s_mov_b32 s101, s11
	s_add_u32 m0, s1, 0x0
	s_nop 0
	global_load_lds_dwordx4 v4, s[98:99]
	s_add_u32 m0, s1, 0x1000
	s_nop 0
	global_load_lds_dwordx4 v5, s[98:99]
	s_add_u32 m0, s1, 0x2000
	s_nop 0
	global_load_lds_dwordx4 v6, s[98:99]
	s_add_u32 m0, s1, 0x3000
	s_nop 0
	global_load_lds_dwordx4 v7, s[98:99]
	s_add_u32 m0, s1, 0x8000
	s_nop 0
	global_load_lds_dwordx4 v4, s[100:101]
	s_add_u32 m0, s1, 0x9000
	s_nop 0
	global_load_lds_dwordx4 v5, s[100:101]
	s_add_u32 m0, s1, 0xa000
	s_nop 0
	global_load_lds_dwordx4 v6, s[100:101]
	s_add_u32 m0, s1, 0xb000
	s_nop 0
	global_load_lds_dwordx4 v7, s[100:101]
	s_add_u32 s98, s98, 0x80
	s_addc_u32 s99, s99, 0
	s_add_u32 s100, s100, 0x80
	s_addc_u32 s101, s101, 0
	s_waitcnt vmcnt(0)

.LBB0_1166:
	s_add_i32 s2, s6, 2
	s_setprio 1
	ds_read_b128 v[114:117], v171 offset:32768
	ds_read_b128 v[122:125], v171 offset:34816
	ds_read_b128 v[118:121], v155
	ds_read_b128 v[140:143], v155 offset:2048
	ds_read_b128 v[160:163], v155 offset:4096
	ds_read_b128 v[164:167], v155 offset:6144
	s_waitcnt lgkmcnt(3)
	v_mfma_f32_16x16x32_bf16 v[8:11], v[114:117], v[118:121], v[8:11]
	ds_read_b128 v[188:191], v171 offset:36864
	v_mfma_f32_16x16x32_bf16 v[26:29], v[122:125], v[118:121], v[26:29]
	ds_read_b128 v[192:195], v171 offset:38912
	s_waitcnt lgkmcnt(1)
	v_mfma_f32_16x16x32_bf16 v[16:19], v[188:191], v[118:121], v[16:19]
	s_waitcnt lgkmcnt(0)
	v_mfma_f32_16x16x32_bf16 v[60:63], v[192:195], v[118:121], v[60:63]
	s_add_u32 m0, s1, 0x4000
	s_nop 0
	global_load_lds_dwordx4 v4, s[98:99]
	ds_read_b128 v[196:199], v172
	v_mfma_f32_16x16x32_bf16 v[36:39], v[114:117], v[140:143], v[36:39]
	v_mfma_f32_16x16x32_bf16 v[54:57], v[122:125], v[140:143], v[54:57]
	s_add_u32 m0, s1, 0x5000
	s_nop 0
	global_load_lds_dwordx4 v5, s[98:99]
	ds_read_b128 v[204:207], v172 offset:2048
	v_mfma_f32_16x16x32_bf16 v[32:35], v[188:191], v[140:143], v[32:35]
	v_mfma_f32_16x16x32_bf16 v[64:67], v[192:195], v[140:143], v[64:67]
	s_add_u32 m0, s1, 0x6000
	s_nop 0
	global_load_lds_dwordx4 v6, s[98:99]
	ds_read_b128 v[208:211], v172 offset:4096
	v_mfma_f32_16x16x32_bf16 v[40:43], v[114:117], v[160:163], v[40:43]
	v_mfma_f32_16x16x32_bf16 v[88:91], v[122:125], v[160:163], v[88:91]
	s_add_u32 m0, s1, 0x7000
	s_nop 0
	global_load_lds_dwordx4 v7, s[98:99]
	ds_read_b128 v[216:219], v172 offset:6144
	v_mfma_f32_16x16x32_bf16 v[48:51], v[188:191], v[160:163], v[48:51]
	v_mfma_f32_16x16x32_bf16 v[76:79], v[192:195], v[160:163], v[76:79]
	s_add_u32 m0, s1, 0xc000
	s_nop 0
	global_load_lds_dwordx4 v4, s[100:101]
	ds_read_b128 v[222:225], v173 offset:32768
	v_mfma_f32_16x16x32_bf16 v[80:83], v[114:117], v[164:167], v[80:83]
	v_mfma_f32_16x16x32_bf16 v[84:87], v[122:125], v[164:167], v[84:87]
	s_add_u32 m0, s1, 0xd000
	s_nop 0
	global_load_lds_dwordx4 v5, s[100:101]
	ds_read_b128 v[122:125], v173 offset:34816
	v_mfma_f32_16x16x32_bf16 v[68:71], v[188:191], v[164:167], v[68:71]
	v_mfma_f32_16x16x32_bf16 v[72:75], v[192:195], v[164:167], v[72:75]
	s_add_u32 m0, s1, 0xe000
	s_nop 0
	global_load_lds_dwordx4 v6, s[100:101]
	ds_read_b128 v[188:191], v173 offset:36864
	s_waitcnt lgkmcnt(2)
	v_mfma_f32_16x16x32_bf16 v[8:11], v[222:225], v[196:199], v[8:11]
	s_waitcnt lgkmcnt(1)
	v_mfma_f32_16x16x32_bf16 v[26:29], v[122:125], v[196:199], v[26:29]
	s_add_u32 m0, s1, 0xf000
	s_nop 0
	global_load_lds_dwordx4 v7, s[100:101]
	s_add_u32 s98, s98, 0x80
	s_addc_u32 s99, s99, 0
	s_add_u32 s100, s100, 0x80
	s_addc_u32 s101, s101, 0
	ds_read_b128 v[226:229], v173 offset:38912
	s_waitcnt lgkmcnt(1)
	v_mfma_f32_16x16x32_bf16 v[16:19], v[188:191], v[196:199], v[16:19]
	s_waitcnt lgkmcnt(0)
	v_mfma_f32_16x16x32_bf16 v[60:63], v[226:229], v[196:199], v[60:63]
	v_mfma_f32_16x16x32_bf16 v[36:39], v[222:225], v[204:207], v[36:39]
	v_mfma_f32_16x16x32_bf16 v[54:57], v[122:125], v[204:207], v[54:57]
	v_mfma_f32_16x16x32_bf16 v[32:35], v[188:191], v[204:207], v[32:35]
	v_mfma_f32_16x16x32_bf16 v[64:67], v[226:229], v[204:207], v[64:67]
	v_mfma_f32_16x16x32_bf16 v[40:43], v[222:225], v[208:211], v[40:43]
	v_mfma_f32_16x16x32_bf16 v[88:91], v[122:125], v[208:211], v[88:91]
	v_mfma_f32_16x16x32_bf16 v[48:51], v[188:191], v[208:211], v[48:51]
	v_mfma_f32_16x16x32_bf16 v[76:79], v[226:229], v[208:211], v[76:79]
	v_mfma_f32_16x16x32_bf16 v[80:83], v[222:225], v[216:219], v[80:83]
	v_mfma_f32_16x16x32_bf16 v[84:87], v[122:125], v[216:219], v[84:87]
	v_mfma_f32_16x16x32_bf16 v[68:71], v[188:191], v[216:219], v[68:71]
	v_mfma_f32_16x16x32_bf16 v[72:75], v[226:229], v[216:219], v[72:75]
	s_setprio 0
	s_waitcnt vmcnt(0) lgkmcnt(0)
	s_barrier
	s_cmp_lg_u32 s6, 14
	s_cbranch_scc1 .Lnh1166_skip
	s_mov_b32 s7, 0
	s_add_i32 s36, s45, s96
	s_cmp_lt_u32 s36, 0xa0
	s_cbranch_scc0 .Lnh1166_skip
	s_lshr_b32 s10, s45, 3
	s_sub_u32 s10, s10, 10
	s_cmp_lt_u32 s10, 2
	s_cbranch_scc1 .Lnh1166_skip
	s_and_b32 s11, s36, 7
	s_and_b32 m0, s45, 7
	s_sub_i32 s11, s11, m0
	s_lshl_b32 s11, s11, 18
	s_sub_i32 s11, s11, 0x800
	s_ashr_i32 m0, s11, 31
	s_add_u32 s98, s98, s11
	s_addc_u32 s99, s99, m0
	s_lshr_b32 s10, s36, 3
	s_lshr_b32 m0, s45, 3
	s_sub_i32 s10, s10, m0
	s_lshl_b32 s10, s10, 18
	s_sub_i32 s10, s10, 0x800
	s_ashr_i32 m0, s10, 31
	s_add_u32 s100, s100, s10
	s_addc_u32 s101, s101, m0
	s_mov_b32 s7, 1
.Lnh1166_skip:
	s_setprio 1
	ds_read_b128 v[92:95], v171 offset:49152
	ds_read_b128 v[96:99], v171 offset:51200
	ds_read_b128 v[0:3], v155 offset:16384
	ds_read_b128 v[12:15], v155 offset:18432
	ds_read_b128 v[20:23], v155 offset:20480
	ds_read_b128 v[100:103], v155 offset:22528
	s_waitcnt lgkmcnt(3)
	v_mfma_f32_16x16x32_bf16 v[8:11], v[92:95], v[0:3], v[8:11]
	ds_read_b128 v[122:125], v171 offset:53248
	v_mfma_f32_16x16x32_bf16 v[26:29], v[96:99], v[0:3], v[26:29]
	ds_read_b128 v[188:191], v171 offset:55296
	s_waitcnt lgkmcnt(1)
	v_mfma_f32_16x16x32_bf16 v[16:19], v[122:125], v[0:3], v[16:19]
	s_waitcnt lgkmcnt(0)
	v_mfma_f32_16x16x32_bf16 v[60:63], v[188:191], v[0:3], v[60:63]
	s_add_u32 m0, s1, 0x0
	s_nop 0
	global_load_lds_dwordx4 v4, s[98:99]
	ds_read_b128 v[196:199], v172 offset:16384
	v_mfma_f32_16x16x32_bf16 v[36:39], v[92:95], v[12:15], v[36:39]
	v_mfma_f32_16x16x32_bf16 v[54:57], v[96:99], v[12:15], v[54:57]
	s_add_u32 m0, s1, 0x1000
	s_nop 0
	global_load_lds_dwordx4 v5, s[98:99]
	ds_read_b128 v[204:207], v172 offset:18432
	v_mfma_f32_16x16x32_bf16 v[32:35], v[122:125], v[12:15], v[32:35]
	v_mfma_f32_16x16x32_bf16 v[64:67], v[188:191], v[12:15], v[64:67]
	s_add_u32 m0, s1, 0x2000
	s_nop 0
	global_load_lds_dwordx4 v6, s[98:99]
	ds_read_b128 v[208:211], v172 offset:20480
	v_mfma_f32_16x16x32_bf16 v[40:43], v[92:95], v[20:23], v[40:43]
	v_mfma_f32_16x16x32_bf16 v[88:91], v[96:99], v[20:23], v[88:91]
	s_add_u32 m0, s1, 0x3000
	s_nop 0
	global_load_lds_dwordx4 v7, s[98:99]
	ds_read_b128 v[216:219], v172 offset:22528
	v_mfma_f32_16x16x32_bf16 v[48:51], v[122:125], v[20:23], v[48:51]
	v_mfma_f32_16x16x32_bf16 v[76:79], v[188:191], v[20:23], v[76:79]
	s_add_u32 m0, s1, 0x8000
	s_nop 0
	global_load_lds_dwordx4 v4, s[100:101]
	ds_read_b128 v[222:225], v173 offset:49152
	v_mfma_f32_16x16x32_bf16 v[80:83], v[92:95], v[100:103], v[80:83]
	v_mfma_f32_16x16x32_bf16 v[84:87], v[96:99], v[100:103], v[84:87]
	s_add_u32 m0, s1, 0x9000
	s_nop 0
	global_load_lds_dwordx4 v5, s[100:101]
	ds_read_b128 v[226:229], v173 offset:51200
	v_mfma_f32_16x16x32_bf16 v[68:71], v[122:125], v[100:103], v[68:71]
	v_mfma_f32_16x16x32_bf16 v[72:75], v[188:191], v[100:103], v[72:75]
	s_add_u32 m0, s1, 0xa000
	s_nop 0
	global_load_lds_dwordx4 v6, s[100:101]
	ds_read_b128 v[122:125], v173 offset:53248
	s_waitcnt lgkmcnt(2)
	v_mfma_f32_16x16x32_bf16 v[8:11], v[222:225], v[196:199], v[8:11]
	s_waitcnt lgkmcnt(1)
	v_mfma_f32_16x16x32_bf16 v[26:29], v[226:229], v[196:199], v[26:29]
	s_add_u32 m0, s1, 0xb000
	s_nop 0
	global_load_lds_dwordx4 v7, s[100:101]
	s_add_u32 s98, s98, 0x80
	s_addc_u32 s99, s99, 0
	s_add_u32 s100, s100, 0x80
	s_addc_u32 s101, s101, 0
	ds_read_b128 v[188:191], v173 offset:55296
	s_waitcnt lgkmcnt(1)
	v_mfma_f32_16x16x32_bf16 v[16:19], v[122:125], v[196:199], v[16:19]
	s_waitcnt lgkmcnt(0)
	v_mfma_f32_16x16x32_bf16 v[60:63], v[188:191], v[196:199], v[60:63]
	v_mfma_f32_16x16x32_bf16 v[36:39], v[222:225], v[204:207], v[36:39]
	v_mfma_f32_16x16x32_bf16 v[54:57], v[226:229], v[204:207], v[54:57]
	v_mfma_f32_16x16x32_bf16 v[32:35], v[122:125], v[204:207], v[32:35]
	v_mfma_f32_16x16x32_bf16 v[64:67], v[188:191], v[204:207], v[64:67]
	v_mfma_f32_16x16x32_bf16 v[40:43], v[222:225], v[208:211], v[40:43]
	v_mfma_f32_16x16x32_bf16 v[88:91], v[226:229], v[208:211], v[88:91]
	v_mfma_f32_16x16x32_bf16 v[48:51], v[122:125], v[208:211], v[48:51]
	v_mfma_f32_16x16x32_bf16 v[76:79], v[188:191], v[208:211], v[76:79]
	v_mfma_f32_16x16x32_bf16 v[80:83], v[222:225], v[216:219], v[80:83]
	v_mfma_f32_16x16x32_bf16 v[84:87], v[226:229], v[216:219], v[84:87]
	v_mfma_f32_16x16x32_bf16 v[68:71], v[122:125], v[216:219], v[68:71]
	v_mfma_f32_16x16x32_bf16 v[72:75], v[188:191], v[216:219], v[72:75]
	s_setprio 0
	s_mov_b32 s6, s2
	s_waitcnt vmcnt(0) lgkmcnt(0)
	s_barrier
	s_cmp_lt_u32 s6, 16
	s_cbranch_scc1 .LBB0_1166
	s_cmp_eq_u32 s7, 1
	s_cbranch_scc1 .Lnx1166_keep
	s_mov_b32 s98, 0
.Lnx1166_keep:
	s_waitcnt vmcnt(5)
	v_add_u32_e32 v15, s46, v170
	v_or_b32_e32 v188, v15, v148
	v_or_b32_e32 v130, s0, v234
	s_add_i32 s0, s46, 0xfffff000
	v_lshlrev_b32_e32 v0, 2, v188
	s_ashr_i32 s0, s0, 10
	global_load_dword v14, v0, s[28:29]
	global_load_dword v30, v0, s[28:29] offset:64
	global_load_dword v31, v0, s[28:29] offset:128
	global_load_dword v44, v0, s[28:29] offset:192
	s_add_i32 s2, s0, 16
	s_and_b64 s[0:1], s[24:25], exec
	s_cselect_b32 s0, 15, s2
	s_mul_hi_u32 s1, s0, 0x4200
	s_mulk_i32 s0, 0x4200
	s_add_u32 s0, s4, s0
	s_addc_u32 s1, s5, s1
	v_mov_b32_e32 v139, v131
	v_lshl_add_u64 v[0:1], v[130:131], 2, s[0:1]
	v_lshl_add_u64 v[4:5], v[0:1], 0, v[138:139]
	global_load_dwordx4 v[22:25], v[4:5], off
	global_load_dwordx4 v[0:3], v[4:5], off offset:64
	global_load_dwordx4 v[92:95], v[4:5], off offset:128
	s_nop 0
	global_load_dwordx4 v[4:7], v[4:5], off offset:192
	v_mov_b32_e32 v12, v26
	v_mov_b32_e32 v13, v9
	v_mov_b32_e32 v9, v27
	s_waitcnt vmcnt(11)
	v_mov_b32_e32 v20, v54
	v_mov_b32_e32 v21, v37
	v_mov_b32_e32 v37, v55
	s_cmpk_lt_u32 s45, 0x50
	s_waitcnt vmcnt(7)
	v_fmamk_f32 v14, v14, 0x3a800000, v183
	s_waitcnt vmcnt(6)
	v_fmamk_f32 v26, v30, 0x3a800000, v183
	v_cmp_gt_f32_e64 s[10:11], s39, v26
	s_waitcnt vmcnt(4)
	v_fmamk_f32 v30, v44, 0x3a800000, v183
	v_mul_f32_e32 v44, 0x4b800000, v26
	v_fmamk_f32 v27, v31, 0x3a800000, v183
	v_mul_f32_e32 v46, 0x4b800000, v30
	v_cndmask_b32_e64 v26, v26, v44, s[10:11]
	v_cmp_gt_f32_e64 s[14:15], s39, v30
	v_mul_f32_e32 v31, 0x4b800000, v14
	v_mul_f32_e32 v45, 0x4b800000, v27
	v_cmp_gt_f32_e32 vcc, s39, v14
	v_cmp_gt_f32_e64 s[12:13], s39, v27
	v_cndmask_b32_e64 v30, v30, v46, s[14:15]
	v_rsq_f32_e32 v26, v26
	v_cndmask_b32_e32 v14, v14, v31, vcc
	v_cndmask_b32_e64 v27, v27, v45, s[12:13]
	v_rsq_f32_e32 v30, v30
	v_rsq_f32_e32 v14, v14
	v_rsq_f32_e32 v27, v27
	s_waitcnt vmcnt(2)
	v_mov_b32_e32 v97, v3
	v_mul_f32_e32 v3, 0x45800000, v26
	v_mov_b32_e32 v96, v25
	v_mul_f32_e32 v25, 0x45800000, v30
	v_cndmask_b32_e64 v102, v26, v3, s[10:11]
	v_mul_f32_e32 v31, 0x45800000, v14
	s_waitcnt vmcnt(0)
	v_mov_b32_e32 v99, v7
	v_mul_f32_e32 v7, 0x45800000, v27
	v_cndmask_b32_e64 v106, v30, v25, s[14:15]
	v_fma_f32 v30, v56, v102, v2
	v_mov_b32_e32 v56, v39
	v_mov_b32_e32 v53, v1
	v_mov_b32_e32 v1, v23
	v_cndmask_b32_e32 v100, v14, v31, vcc
	v_cndmask_b32_e64 v104, v27, v7, s[12:13]
	v_pk_fma_f32 v[152:153], v[56:57], v[102:103], v[96:97] op_sel_hi:[1,0,1]
	v_mov_b32_e32 v56, v88
	v_mov_b32_e32 v57, v41
	v_mov_b32_e32 v98, v95
	v_mov_b32_e32 v52, v22
	v_fma_f32 v14, v28, v100, v2
	v_mov_b32_e32 v28, v11
	v_fma_f32 v26, v38, v102, v24
	v_fma_f32 v38, v66, v102, v6
	v_mov_b32_e32 v66, v35
	v_mov_b32_e32 v41, v89
	v_pk_fma_f32 v[160:161], v[56:57], v[104:105], v[0:1] op_sel_hi:[1,0,1]
	v_mov_b32_e32 v56, v80
	v_mov_b32_e32 v57, v85
	v_mov_b32_e32 v85, v81
	v_fma_f32 v10, v10, v100, v24
	v_fma_f32 v42, v42, v104, v24
	v_fma_f32 v58, v82, v106, v24
	v_pk_fma_f32 v[8:9], v[8:9], v[100:101], v[52:53] op_sel_hi:[1,0,1]
	v_pk_fma_f32 v[140:141], v[12:13], v[100:101], v[0:1] op_sel_hi:[1,0,1]
	v_pk_fma_f32 v[24:25], v[36:37], v[102:103], v[52:53] op_sel_hi:[1,0,1]
	v_pk_fma_f32 v[20:21], v[20:21], v[102:103], v[0:1] op_sel_hi:[1,0,1]
	v_pk_fma_f32 v[142:143], v[28:29], v[100:101], v[96:97] op_sel_hi:[1,0,1]
	v_pk_fma_f32 v[28:29], v[66:67], v[102:103], v[98:99] op_sel_hi:[1,0,1]
	v_pk_fma_f32 v[40:41], v[40:41], v[104:105], v[52:53] op_sel_hi:[1,0,1]
	v_pk_fma_f32 v[56:57], v[56:57], v[106:107], v[52:53] op_sel_hi:[1,0,1]
	v_pk_fma_f32 v[52:53], v[84:85], v[106:107], v[0:1] op_sel_hi:[1,0,1]
	v_mov_b32_e32 v0, v60
	v_mov_b32_e32 v1, v17
	v_mov_b32_e32 v66, v4
	v_mov_b32_e32 v67, v93
	v_pk_fma_f32 v[156:157], v[0:1], v[100:101], v[66:67] op_sel_hi:[1,0,1]
	v_mov_b32_e32 v0, v64
	v_mov_b32_e32 v1, v33
	v_pk_fma_f32 v[162:163], v[0:1], v[102:103], v[66:67] op_sel_hi:[1,0,1]
	v_mov_b32_e32 v0, v76
	v_mov_b32_e32 v1, v49
	v_fma_f32 v22, v62, v100, v6
	v_mov_b32_e32 v62, v19
	v_fma_f32 v46, v90, v104, v2
	v_mov_b32_e32 v90, v43
	v_fma_f32 v54, v78, v104, v6
	v_mov_b32_e32 v78, v51
	v_fmac_f32_e32 v2, v86, v106
	v_mov_b32_e32 v86, v83
	v_mov_b32_e32 v17, v61
	v_mov_b32_e32 v93, v5
	v_mov_b32_e32 v33, v65
	v_pk_fma_f32 v[166:167], v[0:1], v[104:105], v[66:67] op_sel_hi:[1,0,1]
	v_mov_b32_e32 v49, v77
	v_mov_b32_e32 v0, v68
	v_mov_b32_e32 v1, v73
	v_mov_b32_e32 v73, v69
	v_fmac_f32_e32 v6, v74, v106
	v_mov_b32_e32 v74, v71
	s_cselect_b64 s[12:13], -1, 0
	s_and_b32 s0, s45, 0x7ffffff0
	v_fma_f32 v18, v18, v100, v94
	v_fma_f32 v34, v34, v102, v94
	v_fma_f32 v50, v50, v104, v94
	v_pk_fma_f32 v[12:13], v[62:63], v[100:101], v[98:99] op_sel_hi:[1,0,1]
	v_pk_fma_f32 v[36:37], v[90:91], v[104:105], v[96:97] op_sel_hi:[1,0,1]
	v_pk_fma_f32 v[44:45], v[78:79], v[104:105], v[98:99] op_sel_hi:[1,0,1]
	v_pk_fma_f32 v[164:165], v[86:87], v[106:107], v[96:97] op_sel_hi:[1,0,1]
	v_fma_f32 v62, v70, v106, v94
	v_pk_fma_f32 v[16:17], v[16:17], v[100:101], v[92:93] op_sel_hi:[1,0,1]
	v_pk_fma_f32 v[32:33], v[32:33], v[102:103], v[92:93] op_sel_hi:[1,0,1]
	v_pk_fma_f32 v[48:49], v[48:49], v[104:105], v[92:93] op_sel_hi:[1,0,1]
	v_pk_fma_f32 v[60:61], v[0:1], v[106:107], v[92:93] op_sel_hi:[1,0,1]
	v_pk_fma_f32 v[0:1], v[72:73], v[106:107], v[66:67] op_sel_hi:[1,0,1]
	v_pk_fma_f32 v[168:169], v[74:75], v[106:107], v[98:99] op_sel_hi:[1,0,1]
	s_cmpk_lg_i32 s0, 0x50
	s_mov_b64 s[10:11], -1
	s_cbranch_scc0 .LBB0_1181
	v_lshlrev_b32_e32 v3, 1, v15
	s_and_b64 s[0:1], s[26:27], s[12:13]
	v_and_b32_e32 v4, 0x780, v3
	v_mov_b32_e32 v5, v131
	v_cndmask_b32_e64 v3, 0, 1, s[0:1]
	v_lshl_add_u64 v[112:113], v[134:135], 0, v[4:5]
	v_cmp_ne_u32_e64 s[10:11], 1, v3
	s_andn2_b64 vcc, exec, s[0:1]
	v_lshlrev_b32_e32 v3, 7, v188
	s_cbranch_vccnz .LBB0_1170
	v_and_b32_e32 v4, 0x780, v3
	v_mov_b32_e32 v5, v131
	global_load_dwordx4 v[64:67], v[112:113], off
	global_load_dwordx4 v[68:71], v[112:113], off offset:16
	v_lshl_add_u64 v[4:5], v[134:135], 0, v[4:5]
	global_load_dwordx4 v[72:75], v[4:5], off
	global_load_dwordx4 v[76:79], v[4:5], off offset:16
	v_mov_b32_e32 v4, v140
	v_mov_b32_e32 v5, v9
	v_mov_b32_e32 v80, v8
	v_mov_b32_e32 v81, v141
	v_mov_b32_e32 v82, v156
	v_mov_b32_e32 v83, v17
	v_mov_b32_e32 v84, v16
	v_mov_b32_e32 v85, v157
	s_waitcnt vmcnt(3)
	v_mov_b32_e32 v90, v65
	v_mov_b32_e32 v91, v67
	v_mov_b32_e32 v86, v65
	v_mov_b32_e32 v65, v66
	v_pk_mul_f32 v[4:5], v[4:5], v[90:91]
	v_mov_b32_e32 v87, v66
	v_mov_b32_e32 v88, v64
	v_mov_b32_e32 v89, v67
	s_waitcnt vmcnt(2)
	v_mul_f32_e32 v66, v10, v68
	v_mul_f32_e32 v92, v14, v69
	v_mul_f32_e32 v94, v14, v68
	v_mul_f32_e32 v96, v10, v69
	v_pk_mul_f32 v[68:69], v[142:143], v[70:71]
	v_pk_mul_f32 v[70:71], v[142:143], v[70:71] op_sel:[1,0] op_sel_hi:[0,1]
	s_waitcnt vmcnt(1)
	v_mov_b32_e32 v90, v73
	v_mov_b32_e32 v91, v74
	v_mov_b32_e32 v98, v72
	v_mov_b32_e32 v99, v75
	v_mov_b32_e32 v100, v73
	v_mov_b32_e32 v101, v75
	v_mov_b32_e32 v73, v74
	s_waitcnt vmcnt(0)
	v_mul_f32_e32 v74, v18, v76
	v_mul_f32_e32 v102, v22, v77
	v_mul_f32_e32 v104, v22, v76
	v_mul_f32_e32 v106, v18, v77
	v_pk_fma_f32 v[64:65], v[80:81], v[64:65], v[4:5] neg_lo:[0,0,1] neg_hi:[0,0,1]
	v_pk_mul_f32 v[4:5], v[12:13], v[78:79]
	v_pk_mul_f32 v[76:77], v[12:13], v[78:79] op_sel:[1,0] op_sel_hi:[0,1]
	v_pk_mul_f32 v[88:89], v[140:141], v[88:89]
	v_mov_b32_e32 v67, v68
	v_mov_b32_e32 v93, v69
	v_mov_b32_e32 v95, v70
	v_mov_b32_e32 v97, v71
	v_pk_mul_f32 v[78:79], v[156:157], v[98:99]
	v_pk_mul_f32 v[80:81], v[82:83], v[100:101]
	v_mov_b32_e32 v75, v4
	v_mov_b32_e32 v103, v5
	v_mov_b32_e32 v105, v76
	v_mov_b32_e32 v107, v77
	v_pk_add_f32 v[66:67], v[66:67], v[92:93] neg_lo:[0,1] neg_hi:[0,1]
	v_pk_fma_f32 v[68:69], v[8:9], v[86:87], v[88:89]
	v_pk_add_f32 v[70:71], v[94:95], v[96:97]
	v_pk_fma_f32 v[72:73], v[84:85], v[72:73], v[80:81] neg_lo:[0,0,1] neg_hi:[0,0,1]
	v_pk_add_f32 v[74:75], v[74:75], v[102:103] neg_lo:[0,1] neg_hi:[0,1]
	v_pk_fma_f32 v[76:77], v[16:17], v[90:91], v[78:79]
	v_pk_add_f32 v[78:79], v[104:105], v[106:107]
	s_branch .LBB0_1171

.LBB0_1345:
	s_add_i32 s25, s28, 2
	s_setprio 1
	ds_read_b128 v[124:127], v119 offset:32768
	ds_read_b128 v[132:135], v119 offset:34816
	ds_read_b128 v[128:131], v118
	ds_read_b128 v[136:139], v118 offset:2048
	ds_read_b128 v[140:143], v118 offset:4096
	ds_read_b128 v[152:155], v118 offset:6144
	s_waitcnt lgkmcnt(3)
	v_mfma_f32_16x16x32_bf16 v[8:11], v[124:127], v[128:131], v[8:11]
	ds_read_b128 v[156:159], v119 offset:36864
	v_mfma_f32_16x16x32_bf16 v[4:7], v[132:135], v[128:131], v[4:7]
	ds_read_b128 v[160:163], v119 offset:38912
	s_waitcnt lgkmcnt(1)
	v_mfma_f32_16x16x32_bf16 v[12:15], v[156:159], v[128:131], v[12:15]
	s_waitcnt lgkmcnt(0)
	v_mfma_f32_16x16x32_bf16 v[0:3], v[160:163], v[128:131], v[0:3]
	s_add_u32 m0, s30, 0x4000
	s_nop 0
	global_load_lds_dwordx4 v68, s[98:99]
	ds_read_b128 v[164:167], v120
	v_mfma_f32_16x16x32_bf16 v[44:47], v[124:127], v[136:139], v[44:47]
	v_mfma_f32_16x16x32_bf16 v[36:39], v[132:135], v[136:139], v[36:39]
	s_add_u32 m0, s30, 0x5000
	s_nop 0
	global_load_lds_dwordx4 v69, s[98:99]
	ds_read_b128 v[172:175], v120 offset:2048
	v_mfma_f32_16x16x32_bf16 v[20:23], v[156:159], v[136:139], v[20:23]
	v_mfma_f32_16x16x32_bf16 v[16:19], v[160:163], v[136:139], v[16:19]
	s_add_u32 m0, s30, 0x6000
	s_nop 0
	global_load_lds_dwordx4 v70, s[98:99]
	ds_read_b128 v[176:179], v120 offset:4096
	v_mfma_f32_16x16x32_bf16 v[52:55], v[124:127], v[140:143], v[52:55]
	v_mfma_f32_16x16x32_bf16 v[48:51], v[132:135], v[140:143], v[48:51]
	s_add_u32 m0, s30, 0x7000
	s_nop 0
	global_load_lds_dwordx4 v71, s[98:99]
	ds_read_b128 v[184:187], v120 offset:6144
	v_mfma_f32_16x16x32_bf16 v[32:35], v[156:159], v[140:143], v[32:35]
	v_mfma_f32_16x16x32_bf16 v[24:27], v[160:163], v[140:143], v[24:27]
	s_add_u32 m0, s30, 0xc000
	s_nop 0
	global_load_lds_dwordx4 v68, s[100:101]
	ds_read_b128 v[188:191], v121 offset:32768
	v_mfma_f32_16x16x32_bf16 v[60:63], v[124:127], v[152:155], v[60:63]
	v_mfma_f32_16x16x32_bf16 v[56:59], v[132:135], v[152:155], v[56:59]
	s_add_u32 m0, s30, 0xd000
	s_nop 0
	global_load_lds_dwordx4 v69, s[100:101]
	ds_read_b128 v[132:135], v121 offset:34816
	v_mfma_f32_16x16x32_bf16 v[40:43], v[156:159], v[152:155], v[40:43]
	v_mfma_f32_16x16x32_bf16 v[28:31], v[160:163], v[152:155], v[28:31]
	s_add_u32 m0, s30, 0xe000
	s_nop 0
	global_load_lds_dwordx4 v70, s[100:101]
	ds_read_b128 v[156:159], v121 offset:36864
	s_waitcnt lgkmcnt(2)
	v_mfma_f32_16x16x32_bf16 v[8:11], v[188:191], v[164:167], v[8:11]
	s_waitcnt lgkmcnt(1)
	v_mfma_f32_16x16x32_bf16 v[4:7], v[132:135], v[164:167], v[4:7]
	s_add_u32 m0, s30, 0xf000
	s_nop 0
	global_load_lds_dwordx4 v71, s[100:101]
	s_add_u32 s98, s98, 0x80
	s_addc_u32 s99, s99, 0
	s_add_u32 s100, s100, 0x80
	s_addc_u32 s101, s101, 0
	ds_read_b128 v[192:195], v121 offset:38912
	s_waitcnt lgkmcnt(1)
	v_mfma_f32_16x16x32_bf16 v[12:15], v[156:159], v[164:167], v[12:15]
	s_waitcnt lgkmcnt(0)
	v_mfma_f32_16x16x32_bf16 v[0:3], v[192:195], v[164:167], v[0:3]
	v_mfma_f32_16x16x32_bf16 v[44:47], v[188:191], v[172:175], v[44:47]
	v_mfma_f32_16x16x32_bf16 v[36:39], v[132:135], v[172:175], v[36:39]
	v_mfma_f32_16x16x32_bf16 v[20:23], v[156:159], v[172:175], v[20:23]
	v_mfma_f32_16x16x32_bf16 v[16:19], v[192:195], v[172:175], v[16:19]
	v_mfma_f32_16x16x32_bf16 v[52:55], v[188:191], v[176:179], v[52:55]
	v_mfma_f32_16x16x32_bf16 v[48:51], v[132:135], v[176:179], v[48:51]
	v_mfma_f32_16x16x32_bf16 v[32:35], v[156:159], v[176:179], v[32:35]
	v_mfma_f32_16x16x32_bf16 v[24:27], v[192:195], v[176:179], v[24:27]
	v_mfma_f32_16x16x32_bf16 v[60:63], v[188:191], v[184:187], v[60:63]
	v_mfma_f32_16x16x32_bf16 v[56:59], v[132:135], v[184:187], v[56:59]
	v_mfma_f32_16x16x32_bf16 v[40:43], v[156:159], v[184:187], v[40:43]
	v_mfma_f32_16x16x32_bf16 v[28:31], v[192:195], v[184:187], v[28:31]
	s_setprio 0
	s_waitcnt vmcnt(0) lgkmcnt(0)
	s_barrier
	s_setprio 1
	ds_read_b128 v[84:87], v119 offset:49152
	ds_read_b128 v[88:91], v119 offset:51200
	ds_read_b128 v[64:67], v118 offset:16384
	ds_read_b128 v[72:75], v118 offset:18432
	ds_read_b128 v[76:79], v118 offset:20480
	ds_read_b128 v[92:95], v118 offset:22528
	s_waitcnt lgkmcnt(3)
	v_mfma_f32_16x16x32_bf16 v[8:11], v[84:87], v[64:67], v[8:11]
	ds_read_b128 v[132:135], v119 offset:53248
	v_mfma_f32_16x16x32_bf16 v[4:7], v[88:91], v[64:67], v[4:7]
	ds_read_b128 v[156:159], v119 offset:55296
	s_waitcnt lgkmcnt(1)
	v_mfma_f32_16x16x32_bf16 v[12:15], v[132:135], v[64:67], v[12:15]
	s_waitcnt lgkmcnt(0)
	v_mfma_f32_16x16x32_bf16 v[0:3], v[156:159], v[64:67], v[0:3]
	s_add_u32 m0, s30, 0x0
	s_nop 0
	global_load_lds_dwordx4 v68, s[98:99]
	ds_read_b128 v[164:167], v120 offset:16384
	v_mfma_f32_16x16x32_bf16 v[44:47], v[84:87], v[72:75], v[44:47]
	v_mfma_f32_16x16x32_bf16 v[36:39], v[88:91], v[72:75], v[36:39]
	s_add_u32 m0, s30, 0x1000
	s_nop 0
	global_load_lds_dwordx4 v69, s[98:99]
	ds_read_b128 v[172:175], v120 offset:18432
	v_mfma_f32_16x16x32_bf16 v[20:23], v[132:135], v[72:75], v[20:23]
	v_mfma_f32_16x16x32_bf16 v[16:19], v[156:159], v[72:75], v[16:19]
	s_add_u32 m0, s30, 0x2000
	s_nop 0
	global_load_lds_dwordx4 v70, s[98:99]
	ds_read_b128 v[176:179], v120 offset:20480
	v_mfma_f32_16x16x32_bf16 v[52:55], v[84:87], v[76:79], v[52:55]
	v_mfma_f32_16x16x32_bf16 v[48:51], v[88:91], v[76:79], v[48:51]
	s_add_u32 m0, s30, 0x3000
	s_nop 0
	global_load_lds_dwordx4 v71, s[98:99]
	ds_read_b128 v[184:187], v120 offset:22528
	v_mfma_f32_16x16x32_bf16 v[32:35], v[132:135], v[76:79], v[32:35]
	v_mfma_f32_16x16x32_bf16 v[24:27], v[156:159], v[76:79], v[24:27]
	s_add_u32 m0, s30, 0x8000
	s_nop 0
	global_load_lds_dwordx4 v68, s[100:101]
	ds_read_b128 v[188:191], v121 offset:49152
	v_mfma_f32_16x16x32_bf16 v[60:63], v[84:87], v[92:95], v[60:63]
	v_mfma_f32_16x16x32_bf16 v[56:59], v[88:91], v[92:95], v[56:59]
	s_add_u32 m0, s30, 0x9000
	s_nop 0
	global_load_lds_dwordx4 v69, s[100:101]
	ds_read_b128 v[192:195], v121 offset:51200
	v_mfma_f32_16x16x32_bf16 v[40:43], v[132:135], v[92:95], v[40:43]
	v_mfma_f32_16x16x32_bf16 v[28:31], v[156:159], v[92:95], v[28:31]
	s_add_u32 m0, s30, 0xa000
	s_nop 0
	global_load_lds_dwordx4 v70, s[100:101]
	ds_read_b128 v[132:135], v121 offset:53248
	s_waitcnt lgkmcnt(2)
	v_mfma_f32_16x16x32_bf16 v[8:11], v[188:191], v[164:167], v[8:11]
	s_waitcnt lgkmcnt(1)
	v_mfma_f32_16x16x32_bf16 v[4:7], v[192:195], v[164:167], v[4:7]
	s_add_u32 m0, s30, 0xb000
	s_nop 0
	global_load_lds_dwordx4 v71, s[100:101]
	s_add_u32 s98, s98, 0x80
	s_addc_u32 s99, s99, 0
	s_add_u32 s100, s100, 0x80
	s_addc_u32 s101, s101, 0
	ds_read_b128 v[156:159], v121 offset:55296
	s_waitcnt lgkmcnt(1)
	v_mfma_f32_16x16x32_bf16 v[12:15], v[132:135], v[164:167], v[12:15]
	s_waitcnt lgkmcnt(0)
	v_mfma_f32_16x16x32_bf16 v[0:3], v[156:159], v[164:167], v[0:3]
	v_mfma_f32_16x16x32_bf16 v[44:47], v[188:191], v[172:175], v[44:47]
	v_mfma_f32_16x16x32_bf16 v[36:39], v[192:195], v[172:175], v[36:39]
	v_mfma_f32_16x16x32_bf16 v[20:23], v[132:135], v[172:175], v[20:23]
	v_mfma_f32_16x16x32_bf16 v[16:19], v[156:159], v[172:175], v[16:19]
	v_mfma_f32_16x16x32_bf16 v[52:55], v[188:191], v[176:179], v[52:55]
	v_mfma_f32_16x16x32_bf16 v[48:51], v[192:195], v[176:179], v[48:51]
	v_mfma_f32_16x16x32_bf16 v[32:35], v[132:135], v[176:179], v[32:35]
	v_mfma_f32_16x16x32_bf16 v[24:27], v[156:159], v[176:179], v[24:27]
	v_mfma_f32_16x16x32_bf16 v[60:63], v[188:191], v[184:187], v[60:63]
	v_mfma_f32_16x16x32_bf16 v[56:59], v[192:195], v[184:187], v[56:59]
	v_mfma_f32_16x16x32_bf16 v[40:43], v[132:135], v[184:187], v[40:43]
	v_mfma_f32_16x16x32_bf16 v[28:31], v[156:159], v[184:187], v[28:31]
	s_setprio 0
	s_mov_b32 s28, s25
	s_waitcnt vmcnt(0) lgkmcnt(0)
	s_barrier
	s_cmp_lt_u32 s28, 16
	s_cbranch_scc1 .LBB0_1345
	s_mov_b32 s98, 0
	s_add_i32 s18, s26, 0xfffff000
	s_ashr_i32 s18, s18, 10
	s_add_i32 s18, s18, 16
	s_and_b64 s[24:25], s[2:3], exec
	s_cselect_b32 s18, 15, s18
	s_mul_hi_u32 s24, s18, 0x3000
	s_mulk_i32 s18, 0x3000
	s_add_u32 s18, s6, s18
	v_or_b32_e32 v96, s27, v123
	s_addc_u32 s25, s7, s24
	s_waitcnt vmcnt(7)
	v_lshlrev_b64 v[64:65], 2, v[96:97]
	s_add_u32 s24, s18, 0xf442000
	s_waitcnt vmcnt(0)
	v_lshl_add_u64 v[94:95], s[6:7], 0, v[64:65]
	v_add_lshl_u32 v78, s26, v122, 12
	s_addc_u32 s25, s25, 0
	v_mov_b32_e32 v79, v97
	v_or_b32_e32 v114, 0x10000, v78
	v_mov_b32_e32 v115, v97
	v_or_b32_e32 v160, 0x20000, v78
	v_mov_b32_e32 v161, v97
	v_or_b32_e32 v164, 0x30000, v78
	v_mov_b32_e32 v165, v97
	v_or_b32_e32 v86, 16, v96
	v_mov_b32_e32 v87, v97
	v_lshl_add_u64 v[102:103], v[94:95], 0, 64
	v_or_b32_e32 v110, 32, v96
	v_mov_b32_e32 v111, v97
	v_lshl_add_u64 v[136:137], v[94:95], 0, s[20:21]
	v_or_b32_e32 v96, 48, v96
	v_lshl_add_u64 v[74:75], s[24:25], 0, v[64:65]
	v_lshl_add_u64 v[64:65], v[94:95], 0, v[78:79]
	v_lshl_add_u64 v[146:147], v[94:95], 0, v[114:115]
	v_lshl_add_u64 v[168:169], v[94:95], 0, v[160:161]
	v_lshl_add_u64 v[170:171], v[94:95], 0, v[164:165]
	v_lshl_add_u64 v[90:91], v[86:87], 2, s[24:25]
	v_lshl_add_u64 v[174:175], v[102:103], 0, v[160:161]
	v_lshl_add_u64 v[110:111], v[110:111], 2, s[24:25]
	v_lshl_add_u64 v[178:179], v[136:137], 0, v[114:115]
	v_lshl_add_u64 v[180:181], v[136:137], 0, v[160:161]
	v_lshl_add_u64 v[182:183], v[136:137], 0, v[164:165]
	v_lshl_add_u64 v[140:141], v[96:97], 2, s[24:25]
	v_lshl_add_u64 v[94:95], v[94:95], 0, s[22:23]
	global_load_dwordx4 v[66:69], v[74:75], off
	global_load_dwordx4 v[70:73], v[64:65], off
	v_lshl_add_u64 v[172:173], v[102:103], 0, v[114:115]
	global_load_dwordx4 v[74:77], v[146:147], off
	global_load_dwordx4 v[78:81], v[168:169], off
	global_load_dwordx4 v[82:85], v[170:171], off
	global_load_dwordx4 v[86:89], v[64:65], off offset:64
	s_nop 0
	global_load_dwordx4 v[90:93], v[90:91], off
	s_nop 0
	global_load_dwordx4 v[98:101], v[172:173], off
	v_lshl_add_u64 v[176:177], v[102:103], 0, v[164:165]
	global_load_dwordx4 v[102:105], v[174:175], off
	global_load_dwordx4 v[106:109], v[176:177], off
	s_nop 0
	global_load_dwordx4 v[110:113], v[110:111], off
	s_nop 0
	global_load_dwordx4 v[124:127], v[64:65], off offset:128
	global_load_dwordx4 v[128:131], v[178:179], off
	global_load_dwordx4 v[132:135], v[180:181], off
	global_load_dwordx4 v[136:139], v[182:183], off
	s_nop 0
	global_load_dwordx4 v[140:143], v[140:141], off
	s_nop 0
	global_load_dwordx4 v[152:155], v[64:65], off offset:192
	v_lshl_add_u64 v[114:115], v[94:95], 0, v[114:115]
	global_load_dwordx4 v[156:159], v[114:115], off
	v_lshl_add_u64 v[184:185], v[94:95], 0, v[160:161]
	global_load_dwordx4 v[160:163], v[184:185], off
	v_lshl_add_u64 v[94:95], v[94:95], 0, v[164:165]
	global_load_dwordx4 v[164:167], v[94:95], off
	s_add_i32 s97, s97, s96
	s_cmp_gt_u32 s97, 63
	s_waitcnt vmcnt(18)
	v_pk_fma_f32 v[8:9], v[8:9], v[66:67], v[70:71]
	v_pk_fma_f32 v[10:11], v[10:11], v[68:69], v[72:73]
	s_waitcnt vmcnt(17)
	v_pk_fma_f32 v[44:45], v[44:45], v[66:67], v[74:75]
	v_pk_fma_f32 v[46:47], v[46:47], v[68:69], v[76:77]
	s_waitcnt vmcnt(13)
	v_pk_fma_f32 v[4:5], v[4:5], v[90:91], v[86:87]
	v_pk_fma_f32 v[6:7], v[6:7], v[92:93], v[88:89]
	v_pk_fma_f32 v[52:53], v[52:53], v[66:67], v[78:79]
	v_pk_fma_f32 v[54:55], v[54:55], v[68:69], v[80:81]
	v_pk_fma_f32 v[60:61], v[60:61], v[66:67], v[82:83]
	v_pk_fma_f32 v[62:63], v[62:63], v[68:69], v[84:85]
	s_waitcnt vmcnt(12)
	v_pk_fma_f32 v[36:37], v[36:37], v[90:91], v[98:99]
	v_pk_fma_f32 v[38:39], v[38:39], v[92:93], v[100:101]
	s_waitcnt vmcnt(3)
	v_pk_fma_f32 v[0:1], v[0:1], v[140:141], v[152:153]
	v_pk_fma_f32 v[2:3], v[2:3], v[142:143], v[154:155]
	v_pk_fma_f32 v[48:49], v[48:49], v[90:91], v[102:103]
	v_pk_fma_f32 v[50:51], v[50:51], v[92:93], v[104:105]
	v_pk_fma_f32 v[56:57], v[56:57], v[90:91], v[106:107]
	v_pk_fma_f32 v[58:59], v[58:59], v[92:93], v[108:109]
	v_pk_fma_f32 v[12:13], v[12:13], v[110:111], v[124:125]
	v_pk_fma_f32 v[14:15], v[14:15], v[112:113], v[126:127]
	global_store_dwordx4 v[64:65], v[8:11], off
	global_store_dwordx4 v[146:147], v[44:47], off
	global_store_dwordx4 v[168:169], v[52:55], off
	global_store_dwordx4 v[170:171], v[60:63], off
	global_store_dwordx4 v[64:65], v[4:7], off offset:64
	global_store_dwordx4 v[172:173], v[36:39], off
	global_store_dwordx4 v[174:175], v[48:51], off
	global_store_dwordx4 v[176:177], v[56:59], off
	global_store_dwordx4 v[64:65], v[12:15], off offset:128
	v_pk_fma_f32 v[4:5], v[20:21], v[110:111], v[128:129]
	v_pk_fma_f32 v[6:7], v[22:23], v[112:113], v[130:131]
	global_store_dwordx4 v[64:65], v[0:3], off offset:192
	global_store_dwordx4 v[178:179], v[4:7], off
	s_waitcnt vmcnt(13)
	v_pk_fma_f32 v[0:1], v[16:17], v[140:141], v[156:157]
	v_pk_fma_f32 v[2:3], v[18:19], v[142:143], v[158:159]
	v_pk_fma_f32 v[4:5], v[32:33], v[110:111], v[132:133]
	v_pk_fma_f32 v[6:7], v[34:35], v[112:113], v[134:135]
	global_store_dwordx4 v[114:115], v[0:3], off
	global_store_dwordx4 v[180:181], v[4:7], off
	s_waitcnt vmcnt(14)
	v_pk_fma_f32 v[0:1], v[24:25], v[140:141], v[160:161]
	v_pk_fma_f32 v[2:3], v[26:27], v[142:143], v[162:163]
	v_pk_fma_f32 v[4:5], v[40:41], v[110:111], v[136:137]
	v_pk_fma_f32 v[6:7], v[42:43], v[112:113], v[138:139]
	global_store_dwordx4 v[184:185], v[0:3], off
	global_store_dwordx4 v[182:183], v[4:7], off
	s_waitcnt vmcnt(15)
	v_pk_fma_f32 v[0:1], v[28:29], v[140:141], v[164:165]
	v_pk_fma_f32 v[2:3], v[30:31], v[142:143], v[166:167]
	global_store_dwordx4 v[94:95], v[0:3], off
	s_cbranch_scc0 .LBB0_1344
